# v071: v064 + seven 8-phase GEMM K-loops regrouped to two MFMA blocks per barrier pair (pre2 memKV/kinv, b1 + filler, UQ, KvUp, a1) with the matching prologue wait
# speedup vs baseline: 1.0020x; 1.0020x over previous
.LBB0_329:
	s_add_u32 s14, s24, 0x56cc000
	s_addc_u32 s15, s25, 0
	s_add_u32 s16, s24, 0x5ecc000
	s_addc_u32 s17, s25, 0
	s_add_u32 s18, s26, 0x1a923c00
	s_addc_u32 s19, s27, 0
	s_add_u32 s20, s26, 0x1ad23c00
	s_addc_u32 s21, s27, 0
	s_lshl_b32 s7, s23, 12
	s_lshl_b32 s1, s22, 13
	s_and_b32 s7, s7, 0x3000
	s_add_u32 s22, s40, 0x80
	s_addc_u32 s23, s41, 0
	s_waitcnt vmcnt(2)
	s_barrier
	s_add_i32 m0, s53, 0x18000
	v_lshl_add_u64 v[2:3], s[22:23], 0, v[130:131]
	global_load_lds_dwordx4 v[2:3], off
	s_add_i32 m0, s53, 0x1a000
	v_lshl_add_u64 v[2:3], s[22:23], 0, v[132:133]
	s_add_u32 s22, s38, 0x80
	s_addc_u32 s23, s39, 0
	s_add_i32 s58, s53, 0x8000
	global_load_lds_dwordx4 v[2:3], off
	s_mov_b32 m0, s58
	v_lshl_add_u64 v[2:3], s[22:23], 0, v[130:131]
	s_add_i32 s59, s53, 0xa000
	global_load_lds_dwordx4 v[2:3], off
	v_lshl_add_u64 v[2:3], s[22:23], 0, v[132:133]
	s_add_u32 s22, s40, 0x40080
	s_mov_b32 m0, s59
	s_addc_u32 s23, s41, 0
	global_load_lds_dwordx4 v[2:3], off
	s_add_i32 m0, s53, 0x1c000
	v_lshl_add_u64 v[2:3], s[22:23], 0, v[130:131]
	global_load_lds_dwordx4 v[2:3], off
	v_lshl_add_u64 v[2:3], s[22:23], 0, v[132:133]
	s_add_i32 m0, s53, 0x1e000
	s_add_i32 s62, 0, 0x10000
	global_load_lds_dwordx4 v[2:3], off
	v_and_b32_e32 v2, 15, v1
	v_and_b32_e32 v3, 48, v1
	v_lshlrev_b32_e32 v1, 2, v1
	v_lshlrev_b32_e32 v2, 6, v2
	v_and_b32_e32 v1, 32, v1
	v_or_b32_e32 v4, v2, v3
	v_bitop3_b32 v2, v2, v1, v3 bitop3:0x36
	s_waitcnt vmcnt(6)
	v_bitop3_b32 v3, v4, s1, v1 bitop3:0xde
	v_or_b32_e32 v1, s7, v2
	s_add_i32 s63, 0, 0x14000
	v_mbcnt_lo_u32_b32 v2, -1, 0
	v_add_u32_e32 v144, s62, v1
	v_add_u32_e32 v145, 0, v3
	v_add_u32_e32 v146, s63, v1
	v_mov_b32_e32 v147, 0x358637bd
	s_mov_b32 s64, 0x800000
	v_mbcnt_hi_u32_b32 v148, -1, v2
	s_barrier
	s_branch .LBB0_332

.LBB0_339:
	ds_read_b128 v[136:139], v144
	ds_read_b128 v[140:143], v144 offset:1024
	ds_read_b128 v[150:153], v144 offset:2048
	ds_read_b128 v[154:157], v144 offset:3072
	ds_read_b128 v[158:161], v145
	ds_read_b128 v[162:165], v145 offset:1024
	ds_read_b128 v[166:169], v145 offset:2048
	ds_read_b128 v[170:173], v145 offset:3072
	ds_read_b128 v[174:177], v145 offset:4096
	ds_read_b128 v[178:181], v145 offset:5120
	ds_read_b128 v[182:185], v145 offset:6144
	ds_read_b128 v[186:189], v145 offset:7168
	ds_read_b128 v[190:193], v146
	ds_read_b128 v[194:197], v146 offset:1024
	ds_read_b128 v[198:201], v146 offset:2048
	ds_read_b128 v[202:205], v146 offset:3072
	s_add_u32 s40, s38, 0x100
	s_addc_u32 s41, s39, 0
	s_cmp_eq_u32 s67, 12
	s_cselect_b32 s46, s7, s40
	s_cselect_b32 s47, s1, s41
	s_cselect_b32 s42, s31, s65
	s_cselect_b32 s43, s29, s66
	s_add_u32 s44, s46, 0x80
	s_addc_u32 s45, s47, 0
	s_add_u32 s38, s38, 0x40080
	s_addc_u32 s39, s39, 0
	s_add_i32 m0, s53, 0xc000
	s_nop 0
	global_load_lds_dwordx4 v130, s[38:39]
	s_add_i32 m0, s53, 0xe000
	s_nop 0
	global_load_lds_dwordx4 v132, s[38:39]
	s_waitcnt vmcnt(8)
	s_waitcnt lgkmcnt(0)
	s_barrier
	s_setprio 1
	v_mfma_f32_16x16x32_bf16 v[126:129], v[136:139], v[158:161], v[126:129]
	v_mfma_f32_16x16x32_bf16 v[122:125], v[150:153], v[158:161], v[122:125]
	v_mfma_f32_16x16x32_bf16 v[110:113], v[136:139], v[166:169], v[110:113]
	v_mfma_f32_16x16x32_bf16 v[106:109], v[150:153], v[166:169], v[106:109]
	v_mfma_f32_16x16x32_bf16 v[94:97], v[136:139], v[174:177], v[94:97]
	v_mfma_f32_16x16x32_bf16 v[90:93], v[150:153], v[174:177], v[90:93]
	v_mfma_f32_16x16x32_bf16 v[78:81], v[136:139], v[182:185], v[78:81]
	v_mfma_f32_16x16x32_bf16 v[74:77], v[150:153], v[182:185], v[74:77]
	v_mfma_f32_16x16x32_bf16 v[126:129], v[140:143], v[162:165], v[126:129]
	v_mfma_f32_16x16x32_bf16 v[122:125], v[154:157], v[162:165], v[122:125]
	v_mfma_f32_16x16x32_bf16 v[110:113], v[140:143], v[170:173], v[110:113]
	v_mfma_f32_16x16x32_bf16 v[106:109], v[154:157], v[170:173], v[106:109]
	v_mfma_f32_16x16x32_bf16 v[94:97], v[140:143], v[178:181], v[94:97]
	v_mfma_f32_16x16x32_bf16 v[90:93], v[154:157], v[178:181], v[90:93]
	v_mfma_f32_16x16x32_bf16 v[78:81], v[140:143], v[186:189], v[78:81]
	v_mfma_f32_16x16x32_bf16 v[74:77], v[154:157], v[186:189], v[74:77]
	s_setprio 0
	s_setprio 1
	v_mfma_f32_16x16x32_bf16 v[118:121], v[190:193], v[158:161], v[118:121]
	v_mfma_f32_16x16x32_bf16 v[114:117], v[198:201], v[158:161], v[114:117]
	v_mfma_f32_16x16x32_bf16 v[102:105], v[190:193], v[166:169], v[102:105]
	v_mfma_f32_16x16x32_bf16 v[98:101], v[198:201], v[166:169], v[98:101]
	v_mfma_f32_16x16x32_bf16 v[86:89], v[190:193], v[174:177], v[86:89]
	v_mfma_f32_16x16x32_bf16 v[82:85], v[198:201], v[174:177], v[82:85]
	v_mfma_f32_16x16x32_bf16 v[70:73], v[190:193], v[182:185], v[70:73]
	v_mfma_f32_16x16x32_bf16 v[66:69], v[198:201], v[182:185], v[66:69]
	v_mfma_f32_16x16x32_bf16 v[118:121], v[194:197], v[162:165], v[118:121]
	v_mfma_f32_16x16x32_bf16 v[114:117], v[202:205], v[162:165], v[114:117]
	v_mfma_f32_16x16x32_bf16 v[102:105], v[194:197], v[170:173], v[102:105]
	v_mfma_f32_16x16x32_bf16 v[98:101], v[202:205], v[170:173], v[98:101]
	v_mfma_f32_16x16x32_bf16 v[86:89], v[194:197], v[178:181], v[86:89]
	v_mfma_f32_16x16x32_bf16 v[82:85], v[202:205], v[178:181], v[82:85]
	v_mfma_f32_16x16x32_bf16 v[70:73], v[194:197], v[186:189], v[70:73]
	v_mfma_f32_16x16x32_bf16 v[66:69], v[202:205], v[186:189], v[66:69]
	s_setprio 0
	s_barrier
	ds_read_b128 v[158:161], v145 offset:16384
	ds_read_b128 v[162:165], v145 offset:17408
	ds_read_b128 v[166:169], v145 offset:18432
	ds_read_b128 v[170:173], v145 offset:19456
	ds_read_b128 v[174:177], v145 offset:20480
	ds_read_b128 v[178:181], v145 offset:21504
	ds_read_b128 v[182:185], v145 offset:22528
	ds_read_b128 v[186:189], v145 offset:23552
	s_mov_b64 s[38:39], s[42:43]
	s_add_i32 s68, s62, s52
	s_mov_b32 m0, s68
	s_nop 0
	global_load_lds_dwordx4 v130, s[38:39]
	s_add_i32 m0, s68, 0x2000
	s_nop 0
	global_load_lds_dwordx4 v132, s[38:39]
	s_mov_b64 s[38:39], s[46:47]
	s_mov_b32 m0, s53
	s_nop 0
	global_load_lds_dwordx4 v130, s[38:39]
	s_mov_b32 m0, s54
	s_nop 0
	global_load_lds_dwordx4 v132, s[38:39]
	s_add_u32 s38, s42, 0x40000
	s_addc_u32 s39, s43, 0
	s_add_i32 s68, s63, s52
	s_mov_b32 m0, s68
	s_nop 0
	global_load_lds_dwordx4 v130, s[38:39]
	s_add_i32 m0, s68, 0x2000
	s_nop 0
	global_load_lds_dwordx4 v132, s[38:39]
	s_add_i32 s68, 0, 0x18000
	s_waitcnt vmcnt(8)
	s_waitcnt lgkmcnt(0)
	s_barrier
	s_setprio 1
	v_mfma_f32_16x16x32_bf16 v[62:65], v[136:139], v[158:161], v[62:65]
	v_mfma_f32_16x16x32_bf16 v[58:61], v[150:153], v[158:161], v[58:61]
	v_mfma_f32_16x16x32_bf16 v[46:49], v[136:139], v[166:169], v[46:49]
	v_mfma_f32_16x16x32_bf16 v[42:45], v[150:153], v[166:169], v[42:45]
	v_mfma_f32_16x16x32_bf16 v[30:33], v[136:139], v[174:177], v[30:33]
	v_mfma_f32_16x16x32_bf16 v[26:29], v[150:153], v[174:177], v[26:29]
	v_mfma_f32_16x16x32_bf16 v[14:17], v[136:139], v[182:185], v[14:17]
	v_mfma_f32_16x16x32_bf16 v[10:13], v[150:153], v[182:185], v[10:13]
	v_mfma_f32_16x16x32_bf16 v[62:65], v[140:143], v[162:165], v[62:65]
	v_mfma_f32_16x16x32_bf16 v[58:61], v[154:157], v[162:165], v[58:61]
	v_mfma_f32_16x16x32_bf16 v[46:49], v[140:143], v[170:173], v[46:49]
	v_mfma_f32_16x16x32_bf16 v[42:45], v[154:157], v[170:173], v[42:45]
	v_mfma_f32_16x16x32_bf16 v[30:33], v[140:143], v[178:181], v[30:33]
	v_mfma_f32_16x16x32_bf16 v[26:29], v[154:157], v[178:181], v[26:29]
	v_mfma_f32_16x16x32_bf16 v[14:17], v[140:143], v[186:189], v[14:17]
	v_mfma_f32_16x16x32_bf16 v[10:13], v[154:157], v[186:189], v[10:13]
	s_setprio 0
	s_setprio 1
	v_mfma_f32_16x16x32_bf16 v[54:57], v[190:193], v[158:161], v[54:57]
	v_mfma_f32_16x16x32_bf16 v[50:53], v[198:201], v[158:161], v[50:53]
	v_mfma_f32_16x16x32_bf16 v[38:41], v[190:193], v[166:169], v[38:41]
	v_mfma_f32_16x16x32_bf16 v[34:37], v[198:201], v[166:169], v[34:37]
	v_mfma_f32_16x16x32_bf16 v[22:25], v[190:193], v[174:177], v[22:25]
	v_mfma_f32_16x16x32_bf16 v[18:21], v[198:201], v[174:177], v[18:21]
	v_mfma_f32_16x16x32_bf16 v[6:9], v[190:193], v[182:185], v[6:9]
	v_mfma_f32_16x16x32_bf16 v[2:5], v[198:201], v[182:185], v[2:5]
	v_mfma_f32_16x16x32_bf16 v[54:57], v[194:197], v[162:165], v[54:57]
	v_mfma_f32_16x16x32_bf16 v[50:53], v[202:205], v[162:165], v[50:53]
	v_mfma_f32_16x16x32_bf16 v[38:41], v[194:197], v[170:173], v[38:41]
	v_mfma_f32_16x16x32_bf16 v[34:37], v[202:205], v[170:173], v[34:37]
	v_mfma_f32_16x16x32_bf16 v[22:25], v[194:197], v[178:181], v[22:25]
	v_mfma_f32_16x16x32_bf16 v[18:21], v[202:205], v[178:181], v[18:21]
	v_mfma_f32_16x16x32_bf16 v[6:9], v[194:197], v[186:189], v[6:9]
	v_mfma_f32_16x16x32_bf16 v[2:5], v[202:205], v[186:189], v[2:5]
	s_setprio 0
	s_barrier
	ds_read_b128 v[136:139], v216 offset:32768
	ds_read_b128 v[140:143], v216 offset:33792
	ds_read_b128 v[150:153], v216 offset:34816
	ds_read_b128 v[154:157], v216 offset:35840
	ds_read_b128 v[158:161], v145 offset:32768
	ds_read_b128 v[162:165], v145 offset:33792
	ds_read_b128 v[166:169], v145 offset:34816
	ds_read_b128 v[170:173], v145 offset:35840
	ds_read_b128 v[174:177], v145 offset:36864
	ds_read_b128 v[178:181], v145 offset:37888
	ds_read_b128 v[182:185], v145 offset:38912
	ds_read_b128 v[186:189], v145 offset:39936
	ds_read_b128 v[190:193], v216 offset:49152
	ds_read_b128 v[194:197], v216 offset:50176
	ds_read_b128 v[198:201], v216 offset:51200
	ds_read_b128 v[202:205], v216 offset:52224
	s_add_u32 s38, s46, 0x40000
	s_addc_u32 s39, s47, 0
	s_mov_b32 m0, s55
	s_nop 0
	global_load_lds_dwordx4 v130, s[38:39]
	s_mov_b32 m0, s56
	s_nop 0
	global_load_lds_dwordx4 v132, s[38:39]
	s_waitcnt vmcnt(8)
	s_waitcnt lgkmcnt(0)
	s_barrier
	s_setprio 1
	v_mfma_f32_16x16x32_bf16 v[126:129], v[136:139], v[158:161], v[126:129]
	v_mfma_f32_16x16x32_bf16 v[122:125], v[150:153], v[158:161], v[122:125]
	v_mfma_f32_16x16x32_bf16 v[110:113], v[136:139], v[166:169], v[110:113]
	v_mfma_f32_16x16x32_bf16 v[106:109], v[150:153], v[166:169], v[106:109]
	v_mfma_f32_16x16x32_bf16 v[94:97], v[136:139], v[174:177], v[94:97]
	v_mfma_f32_16x16x32_bf16 v[90:93], v[150:153], v[174:177], v[90:93]
	v_mfma_f32_16x16x32_bf16 v[78:81], v[136:139], v[182:185], v[78:81]
	v_mfma_f32_16x16x32_bf16 v[74:77], v[150:153], v[182:185], v[74:77]
	v_mfma_f32_16x16x32_bf16 v[126:129], v[140:143], v[162:165], v[126:129]
	v_mfma_f32_16x16x32_bf16 v[122:125], v[154:157], v[162:165], v[122:125]
	v_mfma_f32_16x16x32_bf16 v[110:113], v[140:143], v[170:173], v[110:113]
	v_mfma_f32_16x16x32_bf16 v[106:109], v[154:157], v[170:173], v[106:109]
	v_mfma_f32_16x16x32_bf16 v[94:97], v[140:143], v[178:181], v[94:97]
	v_mfma_f32_16x16x32_bf16 v[90:93], v[154:157], v[178:181], v[90:93]
	v_mfma_f32_16x16x32_bf16 v[78:81], v[140:143], v[186:189], v[78:81]
	v_mfma_f32_16x16x32_bf16 v[74:77], v[154:157], v[186:189], v[74:77]
	s_setprio 0
	s_setprio 1
	v_mfma_f32_16x16x32_bf16 v[118:121], v[190:193], v[158:161], v[118:121]
	v_mfma_f32_16x16x32_bf16 v[114:117], v[198:201], v[158:161], v[114:117]
	v_mfma_f32_16x16x32_bf16 v[102:105], v[190:193], v[166:169], v[102:105]
	v_mfma_f32_16x16x32_bf16 v[98:101], v[198:201], v[166:169], v[98:101]
	v_mfma_f32_16x16x32_bf16 v[86:89], v[190:193], v[174:177], v[86:89]
	v_mfma_f32_16x16x32_bf16 v[82:85], v[198:201], v[174:177], v[82:85]
	v_mfma_f32_16x16x32_bf16 v[70:73], v[190:193], v[182:185], v[70:73]
	v_mfma_f32_16x16x32_bf16 v[66:69], v[198:201], v[182:185], v[66:69]
	v_mfma_f32_16x16x32_bf16 v[118:121], v[194:197], v[162:165], v[118:121]
	v_mfma_f32_16x16x32_bf16 v[114:117], v[202:205], v[162:165], v[114:117]
	v_mfma_f32_16x16x32_bf16 v[102:105], v[194:197], v[170:173], v[102:105]
	v_mfma_f32_16x16x32_bf16 v[98:101], v[202:205], v[170:173], v[98:101]
	v_mfma_f32_16x16x32_bf16 v[86:89], v[194:197], v[178:181], v[86:89]
	v_mfma_f32_16x16x32_bf16 v[82:85], v[202:205], v[178:181], v[82:85]
	v_mfma_f32_16x16x32_bf16 v[70:73], v[194:197], v[186:189], v[70:73]
	v_mfma_f32_16x16x32_bf16 v[66:69], v[202:205], v[186:189], v[66:69]
	s_setprio 0
	s_barrier
	ds_read_b128 v[158:161], v145 offset:49152
	ds_read_b128 v[162:165], v145 offset:50176
	ds_read_b128 v[166:169], v145 offset:51200
	ds_read_b128 v[170:173], v145 offset:52224
	ds_read_b128 v[174:177], v145 offset:53248
	ds_read_b128 v[178:181], v145 offset:54272
	ds_read_b128 v[182:185], v145 offset:55296
	ds_read_b128 v[186:189], v145 offset:56320
	s_add_i32 s46, 0, 0x1c000
	s_add_u32 s38, s42, 0x80
	s_addc_u32 s39, s43, 0
	s_add_i32 s47, s68, s52
	s_mov_b32 m0, s47
	s_nop 0
	global_load_lds_dwordx4 v130, s[38:39]
	s_add_i32 m0, s47, 0x2000
	s_nop 0
	global_load_lds_dwordx4 v132, s[38:39]
	s_mov_b32 m0, s58
	s_nop 0
	global_load_lds_dwordx4 v130, s[44:45]
	s_mov_b32 m0, s59
	s_nop 0
	global_load_lds_dwordx4 v132, s[44:45]
	s_add_u32 s38, s42, 0x40080
	s_addc_u32 s39, s43, 0
	s_add_i32 s42, s46, s52
	s_mov_b32 m0, s42
	s_nop 0
	global_load_lds_dwordx4 v130, s[38:39]
	s_add_i32 m0, s42, 0x2000
	s_nop 0
	global_load_lds_dwordx4 v132, s[38:39]
	s_add_i32 s67, s67, 2
	s_add_u32 s65, s65, 0x100
	s_addc_u32 s66, s66, 0
	s_cmp_gt_u32 s67, 13
	s_mov_b64 s[38:39], s[40:41]
	s_waitcnt vmcnt(8)
	s_waitcnt lgkmcnt(0)
	s_barrier
	s_setprio 1
	v_mfma_f32_16x16x32_bf16 v[62:65], v[136:139], v[158:161], v[62:65]
	v_mfma_f32_16x16x32_bf16 v[58:61], v[150:153], v[158:161], v[58:61]
	v_mfma_f32_16x16x32_bf16 v[46:49], v[136:139], v[166:169], v[46:49]
	v_mfma_f32_16x16x32_bf16 v[42:45], v[150:153], v[166:169], v[42:45]
	v_mfma_f32_16x16x32_bf16 v[30:33], v[136:139], v[174:177], v[30:33]
	v_mfma_f32_16x16x32_bf16 v[26:29], v[150:153], v[174:177], v[26:29]
	v_mfma_f32_16x16x32_bf16 v[14:17], v[136:139], v[182:185], v[14:17]
	v_mfma_f32_16x16x32_bf16 v[10:13], v[150:153], v[182:185], v[10:13]
	v_mfma_f32_16x16x32_bf16 v[62:65], v[140:143], v[162:165], v[62:65]
	v_mfma_f32_16x16x32_bf16 v[58:61], v[154:157], v[162:165], v[58:61]
	v_mfma_f32_16x16x32_bf16 v[46:49], v[140:143], v[170:173], v[46:49]
	v_mfma_f32_16x16x32_bf16 v[42:45], v[154:157], v[170:173], v[42:45]
	v_mfma_f32_16x16x32_bf16 v[30:33], v[140:143], v[178:181], v[30:33]
	v_mfma_f32_16x16x32_bf16 v[26:29], v[154:157], v[178:181], v[26:29]
	v_mfma_f32_16x16x32_bf16 v[14:17], v[140:143], v[186:189], v[14:17]
	v_mfma_f32_16x16x32_bf16 v[10:13], v[154:157], v[186:189], v[10:13]
	s_setprio 0
	s_setprio 1
	v_mfma_f32_16x16x32_bf16 v[54:57], v[190:193], v[158:161], v[54:57]
	v_mfma_f32_16x16x32_bf16 v[50:53], v[198:201], v[158:161], v[50:53]
	v_mfma_f32_16x16x32_bf16 v[38:41], v[190:193], v[166:169], v[38:41]
	v_mfma_f32_16x16x32_bf16 v[34:37], v[198:201], v[166:169], v[34:37]
	v_mfma_f32_16x16x32_bf16 v[22:25], v[190:193], v[174:177], v[22:25]
	v_mfma_f32_16x16x32_bf16 v[18:21], v[198:201], v[174:177], v[18:21]
	v_mfma_f32_16x16x32_bf16 v[6:9], v[190:193], v[182:185], v[6:9]
	v_mfma_f32_16x16x32_bf16 v[2:5], v[198:201], v[182:185], v[2:5]
	v_mfma_f32_16x16x32_bf16 v[54:57], v[194:197], v[162:165], v[54:57]
	v_mfma_f32_16x16x32_bf16 v[50:53], v[202:205], v[162:165], v[50:53]
	v_mfma_f32_16x16x32_bf16 v[38:41], v[194:197], v[170:173], v[38:41]
	v_mfma_f32_16x16x32_bf16 v[34:37], v[202:205], v[170:173], v[34:37]
	v_mfma_f32_16x16x32_bf16 v[22:25], v[194:197], v[178:181], v[22:25]
	v_mfma_f32_16x16x32_bf16 v[18:21], v[202:205], v[178:181], v[18:21]
	v_mfma_f32_16x16x32_bf16 v[6:9], v[194:197], v[186:189], v[6:9]
	v_mfma_f32_16x16x32_bf16 v[2:5], v[202:205], v[186:189], v[2:5]
	s_setprio 0
	s_barrier
	s_cbranch_scc0 .LBB0_339
	v_mov_b32_e32 v134, v0
	s_ashr_i32 s38, s0, 1
	v_readfirstlane_b32 s1, v134
	s_and_b32 s7, s1, 0xc0
	s_ashr_i32 s1, s1, 2
	s_andn2_b32 s1, s1, 63
	v_and_or_b32 v136, v134, 15, s1
	s_ashr_i32 s39, s38, 31
	s_lshl_b64 s[40:41], s[38:39], 19
	v_lshl_add_u32 v140, s6, 8, v136
	s_or_b32 s40, s40, s7
	v_lshrrev_b32_e32 v134, 1, v134
	v_ashrrev_i32_e32 v141, 31, v140
	s_and_b32 s29, s0, 1
	v_and_b32_e32 v139, 24, v134
	v_lshlrev_b64 v[136:137], 8, v[140:141]
	s_bitcmp1_b32 s0, 0
	v_lshl_add_u64 v[142:143], v[136:137], 0, s[40:41]
	s_mov_b64 s[6:7], -1
	s_cselect_b64 s[0:1], -1, 0
	s_cmp_eq_u32 s29, 0
	v_lshlrev_b32_e32 v134, 2, v139
	v_lshlrev_b32_e32 v138, 1, v139
	v_or_b32_e32 v136, 32, v139
	s_cbranch_scc1 .LBB0_342
	v_lshl_add_u64 v[150:151], v[142:143], 2, s[16:17]
	v_lshl_add_u64 v[154:155], v[150:151], 0, v[134:135]
	v_lshl_add_u64 v[150:151], v[142:143], 1, s[20:21]
	v_mov_b32_e32 v139, v135
	v_lshl_add_u64 v[156:157], v[150:151], 0, v[138:139]
	v_cvt_pk_bf16_f32 v150, v126, v127
	v_cvt_pk_bf16_f32 v151, v128, v129
	v_cvt_pk_bf16_f32 v152, v122, v123
	v_cvt_pk_bf16_f32 v153, v124, v125
	v_mov_b32_e32 v137, v135
	s_mov_b64 s[6:7], 0
	global_store_dwordx4 v[154:155], v[126:129], off
	global_store_dwordx4 v[154:155], v[122:125], off offset:16
	global_store_dwordx4 v[156:157], v[150:153], off
	global_store_dwordx4 v[154:155], v[118:121], off offset:128

.LBB0_384:
	s_add_u32 s54, s26, 0x34d30000
	s_addc_u32 s55, s27, 0
	s_add_u32 s56, s26, 0x3048fc00
	s_addc_u32 s57, s27, 0
	s_lshl_b32 s14, s14, 12
	s_lshl_b32 s1, s1, 13
	s_and_b32 s16, s14, 0x3000
	s_add_u32 s14, s6, 0x80
	s_addc_u32 s15, s7, 0
	s_waitcnt vmcnt(2)
	s_barrier
	s_add_i32 m0, s50, 0x18000
	v_lshl_add_u64 v[2:3], s[14:15], 0, v[132:133]
	global_load_lds_dwordx4 v[2:3], off
	s_add_i32 m0, s50, 0x1a000
	v_lshl_add_u64 v[2:3], s[14:15], 0, v[136:137]
	s_add_u32 s14, s20, 0x80
	s_addc_u32 s15, s21, 0
	s_add_i32 s58, s50, 0x8000
	global_load_lds_dwordx4 v[2:3], off
	s_mov_b32 m0, s58
	v_lshl_add_u64 v[2:3], s[14:15], 0, v[130:131]
	s_add_i32 s59, s50, 0xa000
	global_load_lds_dwordx4 v[2:3], off
	v_lshl_add_u64 v[2:3], s[14:15], 0, v[134:135]
	s_add_u32 s14, s6, 0x10080
	s_mov_b32 m0, s59
	s_addc_u32 s15, s7, 0
	global_load_lds_dwordx4 v[2:3], off
	s_add_i32 m0, s50, 0x1c000
	v_lshl_add_u64 v[2:3], s[14:15], 0, v[132:133]
	global_load_lds_dwordx4 v[2:3], off
	v_lshl_add_u64 v[2:3], s[14:15], 0, v[136:137]
	s_add_i32 m0, s50, 0x1e000
	s_add_i32 s63, 0, 0x10000
	global_load_lds_dwordx4 v[2:3], off
	v_and_b32_e32 v2, 15, v1
	v_and_b32_e32 v3, 48, v1
	v_lshlrev_b32_e32 v1, 2, v1
	v_lshlrev_b32_e32 v2, 6, v2
	v_and_b32_e32 v1, 32, v1
	v_or_b32_e32 v4, v2, v3
	v_bitop3_b32 v2, v2, v1, v3 bitop3:0x36
	s_waitcnt vmcnt(6)
	v_bitop3_b32 v3, v4, s1, v1 bitop3:0xde
	v_or_b32_e32 v1, s16, v2
	s_add_i32 s64, 0, 0x14000
	v_mbcnt_lo_u32_b32 v2, -1, 0
	s_sext_i32_i8 s68, s12
	s_add_i32 s62, s2, 0x2c0
	s_xor_b64 s[10:11], s[10:11], -1
	v_add_u32_e32 v140, s63, v1
	v_add_u32_e32 v141, 0, v3
	v_add_u32_e32 v142, s64, v1
	v_mbcnt_hi_u32_b32 v143, -1, v2
	v_mov_b32_e32 v144, 0x358637bd
	s_mov_b32 s65, 0x800000
	s_barrier
	s_branch .LBB0_386

.LBB0_394:
	ds_read_b128 v[146:149], v140
	ds_read_b128 v[150:153], v140 offset:1024
	ds_read_b128 v[154:157], v140 offset:2048
	ds_read_b128 v[158:161], v140 offset:3072
	ds_read_b128 v[162:165], v141
	ds_read_b128 v[166:169], v141 offset:1024
	ds_read_b128 v[170:173], v141 offset:2048
	ds_read_b128 v[174:177], v141 offset:3072
	ds_read_b128 v[178:181], v141 offset:4096
	ds_read_b128 v[182:185], v141 offset:5120
	ds_read_b128 v[186:189], v141 offset:6144
	ds_read_b128 v[190:193], v141 offset:7168
	ds_read_b128 v[194:197], v142
	ds_read_b128 v[198:201], v142 offset:1024
	ds_read_b128 v[202:205], v142 offset:2048
	ds_read_b128 v[206:209], v142 offset:3072
	s_add_u32 s34, s20, s24
	s_addc_u32 s35, s21, s25
	s_add_u32 s36, s34, 0x100
	s_addc_u32 s37, s35, 0
	s_and_b64 s[30:31], s[28:29], exec
	s_cselect_b32 s39, s15, s37
	s_cselect_b32 s38, s14, s36
	s_add_u32 s24, s6, s24
	s_addc_u32 s25, s7, s25
	s_add_u32 s30, s24, 0x100
	s_addc_u32 s31, s25, 0
	s_add_u32 s24, s38, 0x80
	s_addc_u32 s25, s39, 0
	s_and_b64 s[28:29], s[28:29], exec
	s_cselect_b32 s41, s1, s31
	s_cselect_b32 s40, s13, s30
	s_add_u32 s42, s34, 0x12080
	s_addc_u32 s43, s35, 0
	s_add_i32 s78, s63, s49
	s_add_i32 m0, s50, 0xc000
	s_add_i32 s79, s50, 0xe000
	s_add_i32 s77, s78, 0x2000
	s_add_u32 s36, s40, 0x10000
	s_addc_u32 s37, s41, 0
	s_add_i32 s75, s64, s49
	s_add_i32 s73, s75, 0x2000
	s_add_i32 s72, 0, 0x18000
	s_add_u32 s34, s38, 0x12000
	s_addc_u32 s35, s39, 0
	s_add_i32 s70, 0, 0x1c000
	s_add_u32 s30, s40, 0x80
	s_addc_u32 s31, s41, 0
	s_add_i32 s71, s72, s49
	s_add_i32 s69, s71, 0x2000
	s_add_u32 s28, s40, 0x10080
	s_addc_u32 s29, s41, 0
	s_add_i32 s76, s70, s49
	s_add_i32 s74, s76, 0x2000
	s_nop 0
	global_load_lds_dwordx4 v130, s[42:43]
	s_mov_b32 m0, s79
	s_nop 0
	global_load_lds_dwordx4 v134, s[42:43]
	s_waitcnt vmcnt(8)
	s_waitcnt lgkmcnt(0)
	s_barrier
	s_setprio 1
	v_mfma_f32_16x16x32_bf16 v[126:129], v[146:149], v[162:165], v[126:129]
	v_mfma_f32_16x16x32_bf16 v[122:125], v[154:157], v[162:165], v[122:125]
	v_mfma_f32_16x16x32_bf16 v[110:113], v[146:149], v[170:173], v[110:113]
	v_mfma_f32_16x16x32_bf16 v[106:109], v[154:157], v[170:173], v[106:109]
	v_mfma_f32_16x16x32_bf16 v[94:97], v[146:149], v[178:181], v[94:97]
	v_mfma_f32_16x16x32_bf16 v[90:93], v[154:157], v[178:181], v[90:93]
	v_mfma_f32_16x16x32_bf16 v[78:81], v[146:149], v[186:189], v[78:81]
	v_mfma_f32_16x16x32_bf16 v[74:77], v[154:157], v[186:189], v[74:77]
	v_mfma_f32_16x16x32_bf16 v[126:129], v[150:153], v[166:169], v[126:129]
	v_mfma_f32_16x16x32_bf16 v[122:125], v[158:161], v[166:169], v[122:125]
	v_mfma_f32_16x16x32_bf16 v[110:113], v[150:153], v[174:177], v[110:113]
	v_mfma_f32_16x16x32_bf16 v[106:109], v[158:161], v[174:177], v[106:109]
	v_mfma_f32_16x16x32_bf16 v[94:97], v[150:153], v[182:185], v[94:97]
	v_mfma_f32_16x16x32_bf16 v[90:93], v[158:161], v[182:185], v[90:93]
	v_mfma_f32_16x16x32_bf16 v[78:81], v[150:153], v[190:193], v[78:81]
	v_mfma_f32_16x16x32_bf16 v[74:77], v[158:161], v[190:193], v[74:77]
	s_setprio 0
	s_setprio 1
	v_mfma_f32_16x16x32_bf16 v[118:121], v[194:197], v[162:165], v[118:121]
	v_mfma_f32_16x16x32_bf16 v[114:117], v[202:205], v[162:165], v[114:117]
	v_mfma_f32_16x16x32_bf16 v[102:105], v[194:197], v[170:173], v[102:105]
	v_mfma_f32_16x16x32_bf16 v[98:101], v[202:205], v[170:173], v[98:101]
	v_mfma_f32_16x16x32_bf16 v[86:89], v[194:197], v[178:181], v[86:89]
	v_mfma_f32_16x16x32_bf16 v[82:85], v[202:205], v[178:181], v[82:85]
	v_mfma_f32_16x16x32_bf16 v[70:73], v[194:197], v[186:189], v[70:73]
	v_mfma_f32_16x16x32_bf16 v[66:69], v[202:205], v[186:189], v[66:69]
	v_mfma_f32_16x16x32_bf16 v[118:121], v[198:201], v[166:169], v[118:121]
	v_mfma_f32_16x16x32_bf16 v[114:117], v[206:209], v[166:169], v[114:117]
	v_mfma_f32_16x16x32_bf16 v[102:105], v[198:201], v[174:177], v[102:105]
	v_mfma_f32_16x16x32_bf16 v[98:101], v[206:209], v[174:177], v[98:101]
	v_mfma_f32_16x16x32_bf16 v[86:89], v[198:201], v[182:185], v[86:89]
	v_mfma_f32_16x16x32_bf16 v[82:85], v[206:209], v[182:185], v[82:85]
	v_mfma_f32_16x16x32_bf16 v[70:73], v[198:201], v[190:193], v[70:73]
	v_mfma_f32_16x16x32_bf16 v[66:69], v[206:209], v[190:193], v[66:69]
	s_setprio 0
	s_barrier
	ds_read_b128 v[162:165], v141 offset:16384
	ds_read_b128 v[166:169], v141 offset:17408
	ds_read_b128 v[170:173], v141 offset:18432
	ds_read_b128 v[174:177], v141 offset:19456
	ds_read_b128 v[178:181], v141 offset:20480
	ds_read_b128 v[182:185], v141 offset:21504
	ds_read_b128 v[186:189], v141 offset:22528
	ds_read_b128 v[190:193], v141 offset:23552
	s_mov_b32 m0, s78
	s_nop 0
	global_load_lds_dwordx4 v132, s[40:41]
	s_mov_b32 m0, s77
	s_nop 0
	global_load_lds_dwordx4 v136, s[40:41]
	s_mov_b32 m0, s50
	s_nop 0
	global_load_lds_dwordx4 v130, s[38:39]
	s_mov_b32 m0, s51
	s_nop 0
	global_load_lds_dwordx4 v134, s[38:39]
	s_mov_b32 m0, s75
	s_nop 0
	global_load_lds_dwordx4 v132, s[36:37]
	s_mov_b32 m0, s73
	s_nop 0
	global_load_lds_dwordx4 v136, s[36:37]
	s_waitcnt vmcnt(8)
	s_waitcnt lgkmcnt(0)
	s_barrier
	s_setprio 1
	v_mfma_f32_16x16x32_bf16 v[62:65], v[146:149], v[162:165], v[62:65]
	v_mfma_f32_16x16x32_bf16 v[58:61], v[154:157], v[162:165], v[58:61]
	v_mfma_f32_16x16x32_bf16 v[46:49], v[146:149], v[170:173], v[46:49]
	v_mfma_f32_16x16x32_bf16 v[42:45], v[154:157], v[170:173], v[42:45]
	v_mfma_f32_16x16x32_bf16 v[30:33], v[146:149], v[178:181], v[30:33]
	v_mfma_f32_16x16x32_bf16 v[26:29], v[154:157], v[178:181], v[26:29]
	v_mfma_f32_16x16x32_bf16 v[14:17], v[146:149], v[186:189], v[14:17]
	v_mfma_f32_16x16x32_bf16 v[10:13], v[154:157], v[186:189], v[10:13]
	v_mfma_f32_16x16x32_bf16 v[62:65], v[150:153], v[166:169], v[62:65]
	v_mfma_f32_16x16x32_bf16 v[58:61], v[158:161], v[166:169], v[58:61]
	v_mfma_f32_16x16x32_bf16 v[46:49], v[150:153], v[174:177], v[46:49]
	v_mfma_f32_16x16x32_bf16 v[42:45], v[158:161], v[174:177], v[42:45]
	v_mfma_f32_16x16x32_bf16 v[30:33], v[150:153], v[182:185], v[30:33]
	v_mfma_f32_16x16x32_bf16 v[26:29], v[158:161], v[182:185], v[26:29]
	v_mfma_f32_16x16x32_bf16 v[14:17], v[150:153], v[190:193], v[14:17]
	v_mfma_f32_16x16x32_bf16 v[10:13], v[158:161], v[190:193], v[10:13]
	s_setprio 0
	s_setprio 1
	v_mfma_f32_16x16x32_bf16 v[54:57], v[194:197], v[162:165], v[54:57]
	v_mfma_f32_16x16x32_bf16 v[50:53], v[202:205], v[162:165], v[50:53]
	v_mfma_f32_16x16x32_bf16 v[38:41], v[194:197], v[170:173], v[38:41]
	v_mfma_f32_16x16x32_bf16 v[34:37], v[202:205], v[170:173], v[34:37]
	v_mfma_f32_16x16x32_bf16 v[22:25], v[194:197], v[178:181], v[22:25]
	v_mfma_f32_16x16x32_bf16 v[18:21], v[202:205], v[178:181], v[18:21]
	v_mfma_f32_16x16x32_bf16 v[6:9], v[194:197], v[186:189], v[6:9]
	v_mfma_f32_16x16x32_bf16 v[2:5], v[202:205], v[186:189], v[2:5]
	v_mfma_f32_16x16x32_bf16 v[54:57], v[198:201], v[166:169], v[54:57]
	v_mfma_f32_16x16x32_bf16 v[50:53], v[206:209], v[166:169], v[50:53]
	v_mfma_f32_16x16x32_bf16 v[38:41], v[198:201], v[174:177], v[38:41]
	v_mfma_f32_16x16x32_bf16 v[34:37], v[206:209], v[174:177], v[34:37]
	v_mfma_f32_16x16x32_bf16 v[22:25], v[198:201], v[182:185], v[22:25]
	v_mfma_f32_16x16x32_bf16 v[18:21], v[206:209], v[182:185], v[18:21]
	v_mfma_f32_16x16x32_bf16 v[6:9], v[198:201], v[190:193], v[6:9]
	v_mfma_f32_16x16x32_bf16 v[2:5], v[206:209], v[190:193], v[2:5]
	s_setprio 0
	s_barrier
	ds_read_b128 v[146:149], v216 offset:32768
	ds_read_b128 v[150:153], v216 offset:33792
	ds_read_b128 v[154:157], v216 offset:34816
	ds_read_b128 v[158:161], v216 offset:35840
	ds_read_b128 v[162:165], v141 offset:32768
	ds_read_b128 v[166:169], v141 offset:33792
	ds_read_b128 v[170:173], v141 offset:34816
	ds_read_b128 v[174:177], v141 offset:35840
	ds_read_b128 v[178:181], v141 offset:36864
	ds_read_b128 v[182:185], v141 offset:37888
	ds_read_b128 v[186:189], v141 offset:38912
	ds_read_b128 v[190:193], v141 offset:39936
	ds_read_b128 v[194:197], v216 offset:49152
	ds_read_b128 v[198:201], v216 offset:50176
	ds_read_b128 v[202:205], v216 offset:51200
	ds_read_b128 v[206:209], v216 offset:52224
	s_mov_b32 m0, s52
	s_nop 0
	global_load_lds_dwordx4 v130, s[34:35]
	s_mov_b32 m0, s53
	s_nop 0
	global_load_lds_dwordx4 v134, s[34:35]
	s_waitcnt vmcnt(8)
	s_waitcnt lgkmcnt(0)
	s_barrier
	s_setprio 1
	v_mfma_f32_16x16x32_bf16 v[126:129], v[146:149], v[162:165], v[126:129]
	v_mfma_f32_16x16x32_bf16 v[122:125], v[154:157], v[162:165], v[122:125]
	v_mfma_f32_16x16x32_bf16 v[110:113], v[146:149], v[170:173], v[110:113]
	v_mfma_f32_16x16x32_bf16 v[106:109], v[154:157], v[170:173], v[106:109]
	v_mfma_f32_16x16x32_bf16 v[94:97], v[146:149], v[178:181], v[94:97]
	v_mfma_f32_16x16x32_bf16 v[90:93], v[154:157], v[178:181], v[90:93]
	v_mfma_f32_16x16x32_bf16 v[78:81], v[146:149], v[186:189], v[78:81]
	v_mfma_f32_16x16x32_bf16 v[74:77], v[154:157], v[186:189], v[74:77]
	v_mfma_f32_16x16x32_bf16 v[126:129], v[150:153], v[166:169], v[126:129]
	v_mfma_f32_16x16x32_bf16 v[122:125], v[158:161], v[166:169], v[122:125]
	v_mfma_f32_16x16x32_bf16 v[110:113], v[150:153], v[174:177], v[110:113]
	v_mfma_f32_16x16x32_bf16 v[106:109], v[158:161], v[174:177], v[106:109]
	v_mfma_f32_16x16x32_bf16 v[94:97], v[150:153], v[182:185], v[94:97]
	v_mfma_f32_16x16x32_bf16 v[90:93], v[158:161], v[182:185], v[90:93]
	v_mfma_f32_16x16x32_bf16 v[78:81], v[150:153], v[190:193], v[78:81]
	v_mfma_f32_16x16x32_bf16 v[74:77], v[158:161], v[190:193], v[74:77]
	s_setprio 0
	s_setprio 1
	v_mfma_f32_16x16x32_bf16 v[118:121], v[194:197], v[162:165], v[118:121]
	v_mfma_f32_16x16x32_bf16 v[114:117], v[202:205], v[162:165], v[114:117]
	v_mfma_f32_16x16x32_bf16 v[102:105], v[194:197], v[170:173], v[102:105]
	v_mfma_f32_16x16x32_bf16 v[98:101], v[202:205], v[170:173], v[98:101]
	v_mfma_f32_16x16x32_bf16 v[86:89], v[194:197], v[178:181], v[86:89]
	v_mfma_f32_16x16x32_bf16 v[82:85], v[202:205], v[178:181], v[82:85]
	v_mfma_f32_16x16x32_bf16 v[70:73], v[194:197], v[186:189], v[70:73]
	v_mfma_f32_16x16x32_bf16 v[66:69], v[202:205], v[186:189], v[66:69]
	v_mfma_f32_16x16x32_bf16 v[118:121], v[198:201], v[166:169], v[118:121]
	v_mfma_f32_16x16x32_bf16 v[114:117], v[206:209], v[166:169], v[114:117]
	v_mfma_f32_16x16x32_bf16 v[102:105], v[198:201], v[174:177], v[102:105]
	v_mfma_f32_16x16x32_bf16 v[98:101], v[206:209], v[174:177], v[98:101]
	v_mfma_f32_16x16x32_bf16 v[86:89], v[198:201], v[182:185], v[86:89]
	v_mfma_f32_16x16x32_bf16 v[82:85], v[206:209], v[182:185], v[82:85]
	v_mfma_f32_16x16x32_bf16 v[70:73], v[198:201], v[190:193], v[70:73]
	v_mfma_f32_16x16x32_bf16 v[66:69], v[206:209], v[190:193], v[66:69]
	s_setprio 0
	s_barrier
	ds_read_b128 v[162:165], v141 offset:49152
	ds_read_b128 v[166:169], v141 offset:50176
	ds_read_b128 v[170:173], v141 offset:51200
	ds_read_b128 v[174:177], v141 offset:52224
	ds_read_b128 v[178:181], v141 offset:53248
	ds_read_b128 v[182:185], v141 offset:54272
	ds_read_b128 v[186:189], v141 offset:55296
	ds_read_b128 v[190:193], v141 offset:56320
	s_mov_b32 m0, s71
	s_nop 0
	global_load_lds_dwordx4 v132, s[30:31]
	s_mov_b32 m0, s69
	s_nop 0
	global_load_lds_dwordx4 v136, s[30:31]
	s_mov_b32 m0, s58
	s_nop 0
	global_load_lds_dwordx4 v130, s[24:25]
	s_mov_b32 m0, s59
	s_nop 0
	global_load_lds_dwordx4 v134, s[24:25]
	s_mov_b32 m0, s76
	s_nop 0
	global_load_lds_dwordx4 v132, s[28:29]
	s_mov_b32 m0, s74
	s_nop 0
	global_load_lds_dwordx4 v136, s[28:29]
	s_andn2_b64 vcc, exec, s[22:23]
	s_mov_b64 s[28:29], -1
	s_mov_b64 s[22:23], 0
	s_mov_b64 s[24:25], 0x100
	s_waitcnt vmcnt(8)
	s_waitcnt lgkmcnt(0)
	s_barrier
	s_setprio 1
	v_mfma_f32_16x16x32_bf16 v[62:65], v[146:149], v[162:165], v[62:65]
	v_mfma_f32_16x16x32_bf16 v[58:61], v[154:157], v[162:165], v[58:61]
	v_mfma_f32_16x16x32_bf16 v[46:49], v[146:149], v[170:173], v[46:49]
	v_mfma_f32_16x16x32_bf16 v[42:45], v[154:157], v[170:173], v[42:45]
	v_mfma_f32_16x16x32_bf16 v[30:33], v[146:149], v[178:181], v[30:33]
	v_mfma_f32_16x16x32_bf16 v[26:29], v[154:157], v[178:181], v[26:29]
	v_mfma_f32_16x16x32_bf16 v[14:17], v[146:149], v[186:189], v[14:17]
	v_mfma_f32_16x16x32_bf16 v[10:13], v[154:157], v[186:189], v[10:13]
	v_mfma_f32_16x16x32_bf16 v[62:65], v[150:153], v[166:169], v[62:65]
	v_mfma_f32_16x16x32_bf16 v[58:61], v[158:161], v[166:169], v[58:61]
	v_mfma_f32_16x16x32_bf16 v[46:49], v[150:153], v[174:177], v[46:49]
	v_mfma_f32_16x16x32_bf16 v[42:45], v[158:161], v[174:177], v[42:45]
	v_mfma_f32_16x16x32_bf16 v[30:33], v[150:153], v[182:185], v[30:33]
	v_mfma_f32_16x16x32_bf16 v[26:29], v[158:161], v[182:185], v[26:29]
	v_mfma_f32_16x16x32_bf16 v[14:17], v[150:153], v[190:193], v[14:17]
	v_mfma_f32_16x16x32_bf16 v[10:13], v[158:161], v[190:193], v[10:13]
	s_setprio 0
	s_setprio 1
	v_mfma_f32_16x16x32_bf16 v[54:57], v[194:197], v[162:165], v[54:57]
	v_mfma_f32_16x16x32_bf16 v[50:53], v[202:205], v[162:165], v[50:53]
	v_mfma_f32_16x16x32_bf16 v[38:41], v[194:197], v[170:173], v[38:41]
	v_mfma_f32_16x16x32_bf16 v[34:37], v[202:205], v[170:173], v[34:37]
	v_mfma_f32_16x16x32_bf16 v[22:25], v[194:197], v[178:181], v[22:25]
	v_mfma_f32_16x16x32_bf16 v[18:21], v[202:205], v[178:181], v[18:21]
	v_mfma_f32_16x16x32_bf16 v[6:9], v[194:197], v[186:189], v[6:9]
	v_mfma_f32_16x16x32_bf16 v[2:5], v[202:205], v[186:189], v[2:5]
	v_mfma_f32_16x16x32_bf16 v[54:57], v[198:201], v[166:169], v[54:57]
	v_mfma_f32_16x16x32_bf16 v[50:53], v[206:209], v[166:169], v[50:53]
	v_mfma_f32_16x16x32_bf16 v[38:41], v[198:201], v[174:177], v[38:41]
	v_mfma_f32_16x16x32_bf16 v[34:37], v[206:209], v[174:177], v[34:37]
	v_mfma_f32_16x16x32_bf16 v[22:25], v[198:201], v[182:185], v[22:25]
	v_mfma_f32_16x16x32_bf16 v[18:21], v[206:209], v[182:185], v[18:21]
	v_mfma_f32_16x16x32_bf16 v[6:9], v[198:201], v[190:193], v[6:9]
	v_mfma_f32_16x16x32_bf16 v[2:5], v[206:209], v[190:193], v[2:5]
	s_setprio 0
	s_barrier
	s_cbranch_vccz .LBB0_394
	v_mov_b32_e32 v154, v0
	s_ashr_i32 s1, s0, 31
	v_readfirstlane_b32 s6, v154
	s_bfe_u32 s13, s6, 0x20006
	s_ashr_i32 s6, s6, 2
	s_andn2_b32 s6, s6, 63
	s_ashr_i32 s7, s6, 31
	s_lshl_b64 s[20:21], s[0:1], 10
	s_add_u32 s22, s54, s20
	s_addc_u32 s23, s55, s21
	s_lshl_b64 s[20:21], s[6:7], 2
	v_and_b32_e32 v145, 15, v154
	s_add_u32 s20, s22, s20
	s_addc_u32 s21, s23, s21
	v_lshlrev_b32_e32 v138, 2, v145
	global_load_dword v153, v138, s[20:21] offset:64
	global_load_dword v152, v138, s[20:21] offset:128
	global_load_dword v151, v138, s[20:21] offset:192
	global_load_dword v150, v138, s[20:21] offset:512
	global_load_dword v149, v138, s[20:21] offset:576
	global_load_dword v148, v138, s[20:21] offset:640
	global_load_dword v147, v138, s[20:21] offset:704
	v_mul_f32_e32 v127, v127, v127
	v_mul_f32_e32 v123, v123, v123
	v_mul_f32_e32 v119, v119, v119
	v_mul_f32_e32 v115, v115, v115
	v_fmac_f32_e32 v127, v126, v126
	v_mul_f32_e32 v126, v129, v129
	v_fmac_f32_e32 v123, v122, v122
	v_mul_f32_e32 v122, v125, v125
	v_fmac_f32_e32 v119, v118, v118
	v_mul_f32_e32 v118, v121, v121
	v_fmac_f32_e32 v115, v114, v114
	v_mul_f32_e32 v114, v117, v117
	v_fmac_f32_e32 v126, v128, v128
	v_fmac_f32_e32 v122, v124, v124
	v_fmac_f32_e32 v118, v120, v120
	v_fmac_f32_e32 v114, v116, v116
	v_add_f32_e32 v126, v127, v126
	v_add_f32_e32 v122, v123, v122
	v_add_f32_e32 v118, v119, v118
	v_add_f32_e32 v114, v115, v114
	v_add_f32_e32 v122, v126, v122
	v_add_f32_e32 v114, v118, v114
	v_add_f32_e32 v115, v122, v114
	ds_swizzle_b32 v116, v115 offset:swizzle(SWAP,16)
	v_and_b32_e32 v156, 64, v143
	v_xor_b32_e32 v155, 32, v143
	v_add_u32_e32 v156, 64, v156
	v_cmp_lt_i32_e32 vcc, v155, v156
	s_lshl_b32 s22, s68, 2
	s_or_b32 s22, s13, s22
	v_cndmask_b32_e32 v114, v143, v155, vcc
	s_lshl_b64 s[0:1], s[0:1], 8
	v_lshlrev_b32_e32 v114, 2, v114
	s_waitcnt lgkmcnt(0)
	v_add_f32_e32 v115, v115, v116
	s_add_u32 s0, s0, s6
	ds_bpermute_b32 v116, v114, v115
	s_addc_u32 s1, s1, s7
	s_ashr_i32 s23, s22, 31
	v_or_b32_e32 v146, s0, v145
	v_mov_b32_e32 v145, s1
	s_lshl_b64 s[0:1], s[22:23], 2
	v_and_b32_e32 v117, 48, v154
	s_add_u32 s0, s56, s0
	v_cmp_eq_u32_e64 s[6:7], 0, v117
	s_addc_u32 s1, s57, s1
	s_and_saveexec_b64 s[22:23], s[6:7]
	s_cbranch_execz .LBB0_397
	v_lshl_add_u64 v[118:119], s[20:21], 0, v[138:139]
	global_load_dword v118, v[118:119], off
	s_waitcnt lgkmcnt(0)
	v_add_f32_e32 v115, v115, v116
	v_mad_u64_u32 v[116:117], s[20:21], v146, 48, s[0:1]
	s_waitcnt vmcnt(0)
	v_add_f32_e32 v115, v115, v118
	v_fmamk_f32 v115, v115, 0x3c2aaaab, v144
	v_mul_f32_e32 v118, 0x4b800000, v115
	v_cmp_gt_f32_e32 vcc, s65, v115
	s_nop 1
	v_cndmask_b32_e32 v115, v115, v118, vcc
	v_rsq_f32_e32 v115, v115
	v_mov_b32_e32 v118, v117
	v_mad_u64_u32 v[118:119], s[20:21], v145, 48, v[118:119]
	v_mul_f32_e32 v117, 0x45800000, v115
	v_cndmask_b32_e32 v115, v115, v117, vcc
	v_mov_b32_e32 v117, v118
	global_store_dword v[116:117], v115, off

.LBB0_495:
	s_mul_i32 s68, s34, 0x8200
	s_lshl_b64 s[24:25], s[68:69], 2
	s_add_u32 s1, s22, s24
	s_addc_u32 s9, s23, s25
	s_add_u32 s24, s1, 0x5000
	s_addc_u32 s25, s9, 0
	s_add_u32 s26, s22, 0x12f3ec00
	s_addc_u32 s27, s23, 0
	s_add_u32 s1, s22, s54
	s_addc_u32 s9, s23, s35
	s_add_u32 s28, s1, 0x97400
	s_addc_u32 s29, s9, 0
	s_add_u32 s30, s22, 0x94ddc00
	s_addc_u32 s31, s23, 0
	s_lshl_b32 s68, s34, 6
	s_lshl_b64 s[36:37], s[68:69], 2
	s_add_u32 s36, s20, s36
	s_addc_u32 s37, s21, s37
	s_add_u32 s38, s22, 0x2f184c00
	s_addc_u32 s39, s23, 0
	s_lshl_b32 s9, s41, 12
	s_lshl_b32 s1, s15, 13
	s_and_b32 s9, s9, 0x3000
	s_add_u32 s20, s18, 0x80
	v_mov_b32_e32 v137, v2
	s_addc_u32 s21, s19, 0
	s_waitcnt vmcnt(2)
	s_barrier
	s_add_i32 m0, s74, 0x18000
	v_lshl_add_u64 v[4:5], s[20:21], 0, v[136:137]
	v_mov_b32_e32 v139, v2
	global_load_lds_dwordx4 v[4:5], off
	s_add_i32 m0, s74, 0x1a000
	v_lshl_add_u64 v[4:5], s[20:21], 0, v[138:139]
	s_add_u32 s20, s16, 0x80
	s_addc_u32 s21, s17, 0
	s_add_i32 s80, s74, 0x8000
	global_load_lds_dwordx4 v[4:5], off
	s_mov_b32 m0, s80
	v_lshl_add_u64 v[4:5], s[20:21], 0, v[136:137]
	s_add_i32 s81, s74, 0xa000
	global_load_lds_dwordx4 v[4:5], off
	v_lshl_add_u64 v[4:5], s[20:21], 0, v[138:139]
	s_add_u32 s20, s18, 0x40080
	s_mov_b32 m0, s81
	s_addc_u32 s21, s19, 0
	global_load_lds_dwordx4 v[4:5], off
	s_add_i32 m0, s74, 0x1c000
	v_lshl_add_u64 v[4:5], s[20:21], 0, v[136:137]
	global_load_lds_dwordx4 v[4:5], off
	v_lshl_add_u64 v[4:5], s[20:21], 0, v[138:139]
	s_add_i32 m0, s74, 0x1e000
	v_and_b32_e32 v3, 15, v1
	global_load_lds_dwordx4 v[4:5], off
	v_and_b32_e32 v4, 48, v1
	v_lshlrev_b32_e32 v1, 2, v1
	v_lshlrev_b32_e32 v3, 6, v3
	v_and_b32_e32 v1, 32, v1
	s_lshl_b32 s82, s40, 3
	v_or_b32_e32 v5, v3, v4
	v_bitop3_b32 v3, v3, v1, v4 bitop3:0x36
	s_abs_i32 s83, s82
	v_bitop3_b32 v4, v5, s1, v1 bitop3:0xde
	v_or_b32_e32 v1, s9, v3
	v_cvt_f32_u32_e32 v3, s83
	s_sub_i32 s1, 0, s83
	s_waitcnt vmcnt(6)
	s_mov_b32 s15, s69
	v_rcp_iflag_f32_e32 v3, v3
	s_lshr_b32 s84, s14, 3
	s_and_b32 s85, s14, 7
	s_add_i32 s86, s84, 1
	v_mul_f32_e32 v3, 0x4f7ffffe, v3
	v_cvt_u32_f32_e32 v3, v3
	s_bfe_i32 s87, s40, 0x1001c
	s_mov_b32 s88, 0
	v_mov_b64_e32 v[140:141], s[14:15]
	v_readfirstlane_b32 s9, v3
	s_mul_i32 s1, s1, s9
	s_mul_hi_u32 s1, s9, s1
	s_add_i32 s89, s9, s1
	v_add_u32_e32 v3, 0, v4
	s_barrier
	s_branch .LBB0_498

.LBB0_505:
	ds_read_b128 v[132:135], v218
	ds_read_b128 v[142:145], v218 offset:1024
	ds_read_b128 v[146:149], v218 offset:2048
	ds_read_b128 v[150:153], v218 offset:3072
	ds_read_b128 v[154:157], v3
	ds_read_b128 v[158:161], v3 offset:1024
	ds_read_b128 v[162:165], v3 offset:2048
	ds_read_b128 v[166:169], v3 offset:3072
	ds_read_b128 v[170:173], v3 offset:4096
	ds_read_b128 v[174:177], v3 offset:5120
	ds_read_b128 v[178:181], v3 offset:6144
	ds_read_b128 v[182:185], v3 offset:7168
	ds_read_b128 v[186:189], v218 offset:16384
	ds_read_b128 v[190:193], v218 offset:17408
	ds_read_b128 v[210:213], v218 offset:18432
	ds_read_b128 v[214:217], v218 offset:19456
	s_add_u32 s18, s16, 0x100
	s_addc_u32 s19, s17, 0
	s_cmp_eq_u32 s62, 12
	s_cselect_b32 s50, s9, s18
	s_cselect_b32 s51, s1, s19
	s_cselect_b32 s20, s43, s52
	s_cselect_b32 s21, s41, s53
	s_add_u32 s48, s50, 0x80
	s_addc_u32 s49, s51, 0
	s_add_i32 s64, 0, 0x10000
	s_add_u32 s16, s16, 0x40080
	s_addc_u32 s17, s17, 0
	s_add_i32 m0, s74, 0xc000
	s_nop 0
	global_load_lds_dwordx4 v136, s[16:17]
	s_add_i32 m0, s74, 0xe000
	s_nop 0
	global_load_lds_dwordx4 v138, s[16:17]
	s_waitcnt vmcnt(8)
	s_waitcnt lgkmcnt(0)
	s_barrier
	s_setprio 1
	v_mfma_f32_16x16x32_bf16 v[128:131], v[132:135], v[154:157], v[128:131]
	v_mfma_f32_16x16x32_bf16 v[124:127], v[146:149], v[154:157], v[124:127]
	v_mfma_f32_16x16x32_bf16 v[112:115], v[132:135], v[162:165], v[112:115]
	v_mfma_f32_16x16x32_bf16 v[108:111], v[146:149], v[162:165], v[108:111]
	v_mfma_f32_16x16x32_bf16 v[96:99], v[132:135], v[170:173], v[96:99]
	v_mfma_f32_16x16x32_bf16 v[92:95], v[146:149], v[170:173], v[92:95]
	v_mfma_f32_16x16x32_bf16 v[80:83], v[132:135], v[178:181], v[80:83]
	v_mfma_f32_16x16x32_bf16 v[76:79], v[146:149], v[178:181], v[76:79]
	v_mfma_f32_16x16x32_bf16 v[128:131], v[142:145], v[158:161], v[128:131]
	v_mfma_f32_16x16x32_bf16 v[124:127], v[150:153], v[158:161], v[124:127]
	v_mfma_f32_16x16x32_bf16 v[112:115], v[142:145], v[166:169], v[112:115]
	v_mfma_f32_16x16x32_bf16 v[108:111], v[150:153], v[166:169], v[108:111]
	v_mfma_f32_16x16x32_bf16 v[96:99], v[142:145], v[174:177], v[96:99]
	v_mfma_f32_16x16x32_bf16 v[92:95], v[150:153], v[174:177], v[92:95]
	v_mfma_f32_16x16x32_bf16 v[80:83], v[142:145], v[182:185], v[80:83]
	v_mfma_f32_16x16x32_bf16 v[76:79], v[150:153], v[182:185], v[76:79]
	s_setprio 0
	s_setprio 1
	v_mfma_f32_16x16x32_bf16 v[120:123], v[186:189], v[154:157], v[120:123]
	v_mfma_f32_16x16x32_bf16 v[116:119], v[210:213], v[154:157], v[116:119]
	v_mfma_f32_16x16x32_bf16 v[104:107], v[186:189], v[162:165], v[104:107]
	v_mfma_f32_16x16x32_bf16 v[100:103], v[210:213], v[162:165], v[100:103]
	v_mfma_f32_16x16x32_bf16 v[88:91], v[186:189], v[170:173], v[88:91]
	v_mfma_f32_16x16x32_bf16 v[84:87], v[210:213], v[170:173], v[84:87]
	v_mfma_f32_16x16x32_bf16 v[72:75], v[186:189], v[178:181], v[72:75]
	v_mfma_f32_16x16x32_bf16 v[68:71], v[210:213], v[178:181], v[68:71]
	v_mfma_f32_16x16x32_bf16 v[120:123], v[190:193], v[158:161], v[120:123]
	v_mfma_f32_16x16x32_bf16 v[116:119], v[214:217], v[158:161], v[116:119]
	v_mfma_f32_16x16x32_bf16 v[104:107], v[190:193], v[166:169], v[104:107]
	v_mfma_f32_16x16x32_bf16 v[100:103], v[214:217], v[166:169], v[100:103]
	v_mfma_f32_16x16x32_bf16 v[88:91], v[190:193], v[174:177], v[88:91]
	v_mfma_f32_16x16x32_bf16 v[84:87], v[214:217], v[174:177], v[84:87]
	v_mfma_f32_16x16x32_bf16 v[72:75], v[190:193], v[182:185], v[72:75]
	v_mfma_f32_16x16x32_bf16 v[68:71], v[214:217], v[182:185], v[68:71]
	s_setprio 0
	s_barrier
	ds_read_b128 v[154:157], v3 offset:16384
	ds_read_b128 v[158:161], v3 offset:17408
	ds_read_b128 v[162:165], v3 offset:18432
	ds_read_b128 v[166:169], v3 offset:19456
	ds_read_b128 v[170:173], v3 offset:20480
	ds_read_b128 v[174:177], v3 offset:21504
	ds_read_b128 v[178:181], v3 offset:22528
	ds_read_b128 v[182:185], v3 offset:23552
	s_add_i32 s65, 0, 0x14000
	s_mov_b64 s[16:17], s[20:21]
	s_add_i32 s64, s64, s73
	s_mov_b32 m0, s64
	s_nop 0
	global_load_lds_dwordx4 v136, s[16:17]
	s_add_i32 m0, s64, 0x2000
	s_nop 0
	global_load_lds_dwordx4 v138, s[16:17]
	s_mov_b64 s[16:17], s[50:51]
	s_mov_b32 m0, s74
	s_nop 0
	global_load_lds_dwordx4 v136, s[16:17]
	s_mov_b32 m0, s75
	s_nop 0
	global_load_lds_dwordx4 v138, s[16:17]
	s_add_u32 s16, s20, 0x40000
	s_addc_u32 s17, s21, 0
	s_add_i32 s64, s65, s73
	s_mov_b32 m0, s64
	s_nop 0
	global_load_lds_dwordx4 v136, s[16:17]
	s_add_i32 m0, s64, 0x2000
	s_nop 0
	global_load_lds_dwordx4 v138, s[16:17]
	s_add_i32 s64, 0, 0x18000
	s_waitcnt vmcnt(8)
	s_waitcnt lgkmcnt(0)
	s_barrier
	s_setprio 1
	v_mfma_f32_16x16x32_bf16 v[64:67], v[132:135], v[154:157], v[64:67]
	v_mfma_f32_16x16x32_bf16 v[60:63], v[146:149], v[154:157], v[60:63]
	v_mfma_f32_16x16x32_bf16 v[48:51], v[132:135], v[162:165], v[48:51]
	v_mfma_f32_16x16x32_bf16 v[44:47], v[146:149], v[162:165], v[44:47]
	v_mfma_f32_16x16x32_bf16 v[32:35], v[132:135], v[170:173], v[32:35]
	v_mfma_f32_16x16x32_bf16 v[28:31], v[146:149], v[170:173], v[28:31]
	v_mfma_f32_16x16x32_bf16 v[16:19], v[132:135], v[178:181], v[16:19]
	v_mfma_f32_16x16x32_bf16 v[12:15], v[146:149], v[178:181], v[12:15]
	v_mfma_f32_16x16x32_bf16 v[64:67], v[142:145], v[158:161], v[64:67]
	v_mfma_f32_16x16x32_bf16 v[60:63], v[150:153], v[158:161], v[60:63]
	v_mfma_f32_16x16x32_bf16 v[48:51], v[142:145], v[166:169], v[48:51]
	v_mfma_f32_16x16x32_bf16 v[44:47], v[150:153], v[166:169], v[44:47]
	v_mfma_f32_16x16x32_bf16 v[32:35], v[142:145], v[174:177], v[32:35]
	v_mfma_f32_16x16x32_bf16 v[28:31], v[150:153], v[174:177], v[28:31]
	v_mfma_f32_16x16x32_bf16 v[16:19], v[142:145], v[182:185], v[16:19]
	v_mfma_f32_16x16x32_bf16 v[12:15], v[150:153], v[182:185], v[12:15]
	s_setprio 0
	s_setprio 1
	v_mfma_f32_16x16x32_bf16 v[56:59], v[186:189], v[154:157], v[56:59]
	v_mfma_f32_16x16x32_bf16 v[52:55], v[210:213], v[154:157], v[52:55]
	v_mfma_f32_16x16x32_bf16 v[40:43], v[186:189], v[162:165], v[40:43]
	v_mfma_f32_16x16x32_bf16 v[36:39], v[210:213], v[162:165], v[36:39]
	v_mfma_f32_16x16x32_bf16 v[24:27], v[186:189], v[170:173], v[24:27]
	v_mfma_f32_16x16x32_bf16 v[20:23], v[210:213], v[170:173], v[20:23]
	v_mfma_f32_16x16x32_bf16 v[8:11], v[186:189], v[178:181], v[8:11]
	v_mfma_f32_16x16x32_bf16 v[4:7], v[210:213], v[178:181], v[4:7]
	v_mfma_f32_16x16x32_bf16 v[56:59], v[190:193], v[158:161], v[56:59]
	v_mfma_f32_16x16x32_bf16 v[52:55], v[214:217], v[158:161], v[52:55]
	v_mfma_f32_16x16x32_bf16 v[40:43], v[190:193], v[166:169], v[40:43]
	v_mfma_f32_16x16x32_bf16 v[36:39], v[214:217], v[166:169], v[36:39]
	v_mfma_f32_16x16x32_bf16 v[24:27], v[190:193], v[174:177], v[24:27]
	v_mfma_f32_16x16x32_bf16 v[20:23], v[214:217], v[174:177], v[20:23]
	v_mfma_f32_16x16x32_bf16 v[8:11], v[190:193], v[182:185], v[8:11]
	v_mfma_f32_16x16x32_bf16 v[4:7], v[214:217], v[182:185], v[4:7]
	s_setprio 0
	s_barrier
	ds_read_b128 v[132:135], v218 offset:32768
	ds_read_b128 v[142:145], v218 offset:33792
	ds_read_b128 v[146:149], v218 offset:34816
	ds_read_b128 v[150:153], v218 offset:35840
	ds_read_b128 v[154:157], v3 offset:32768
	ds_read_b128 v[158:161], v3 offset:33792
	ds_read_b128 v[162:165], v3 offset:34816
	ds_read_b128 v[166:169], v3 offset:35840
	ds_read_b128 v[170:173], v3 offset:36864
	ds_read_b128 v[174:177], v3 offset:37888
	ds_read_b128 v[178:181], v3 offset:38912
	ds_read_b128 v[182:185], v3 offset:39936
	ds_read_b128 v[186:189], v218 offset:49152
	ds_read_b128 v[190:193], v218 offset:50176
	ds_read_b128 v[210:213], v218 offset:51200
	ds_read_b128 v[214:217], v218 offset:52224
	s_add_u32 s16, s50, 0x40000
	s_addc_u32 s17, s51, 0
	s_mov_b32 m0, s78
	s_nop 0
	global_load_lds_dwordx4 v136, s[16:17]
	s_mov_b32 m0, s79
	s_nop 0
	global_load_lds_dwordx4 v138, s[16:17]
	s_waitcnt vmcnt(8)
	s_waitcnt lgkmcnt(0)
	s_barrier
	s_setprio 1
	v_mfma_f32_16x16x32_bf16 v[128:131], v[132:135], v[154:157], v[128:131]
	v_mfma_f32_16x16x32_bf16 v[124:127], v[146:149], v[154:157], v[124:127]
	v_mfma_f32_16x16x32_bf16 v[112:115], v[132:135], v[162:165], v[112:115]
	v_mfma_f32_16x16x32_bf16 v[108:111], v[146:149], v[162:165], v[108:111]
	v_mfma_f32_16x16x32_bf16 v[96:99], v[132:135], v[170:173], v[96:99]
	v_mfma_f32_16x16x32_bf16 v[92:95], v[146:149], v[170:173], v[92:95]
	v_mfma_f32_16x16x32_bf16 v[80:83], v[132:135], v[178:181], v[80:83]
	v_mfma_f32_16x16x32_bf16 v[76:79], v[146:149], v[178:181], v[76:79]
	v_mfma_f32_16x16x32_bf16 v[128:131], v[142:145], v[158:161], v[128:131]
	v_mfma_f32_16x16x32_bf16 v[124:127], v[150:153], v[158:161], v[124:127]
	v_mfma_f32_16x16x32_bf16 v[112:115], v[142:145], v[166:169], v[112:115]
	v_mfma_f32_16x16x32_bf16 v[108:111], v[150:153], v[166:169], v[108:111]
	v_mfma_f32_16x16x32_bf16 v[96:99], v[142:145], v[174:177], v[96:99]
	v_mfma_f32_16x16x32_bf16 v[92:95], v[150:153], v[174:177], v[92:95]
	v_mfma_f32_16x16x32_bf16 v[80:83], v[142:145], v[182:185], v[80:83]
	v_mfma_f32_16x16x32_bf16 v[76:79], v[150:153], v[182:185], v[76:79]
	s_setprio 0
	s_setprio 1
	v_mfma_f32_16x16x32_bf16 v[120:123], v[186:189], v[154:157], v[120:123]
	v_mfma_f32_16x16x32_bf16 v[116:119], v[210:213], v[154:157], v[116:119]
	v_mfma_f32_16x16x32_bf16 v[104:107], v[186:189], v[162:165], v[104:107]
	v_mfma_f32_16x16x32_bf16 v[100:103], v[210:213], v[162:165], v[100:103]
	v_mfma_f32_16x16x32_bf16 v[88:91], v[186:189], v[170:173], v[88:91]
	v_mfma_f32_16x16x32_bf16 v[84:87], v[210:213], v[170:173], v[84:87]
	v_mfma_f32_16x16x32_bf16 v[72:75], v[186:189], v[178:181], v[72:75]
	v_mfma_f32_16x16x32_bf16 v[68:71], v[210:213], v[178:181], v[68:71]
	v_mfma_f32_16x16x32_bf16 v[120:123], v[190:193], v[158:161], v[120:123]
	v_mfma_f32_16x16x32_bf16 v[116:119], v[214:217], v[158:161], v[116:119]
	v_mfma_f32_16x16x32_bf16 v[104:107], v[190:193], v[166:169], v[104:107]
	v_mfma_f32_16x16x32_bf16 v[100:103], v[214:217], v[166:169], v[100:103]
	v_mfma_f32_16x16x32_bf16 v[88:91], v[190:193], v[174:177], v[88:91]
	v_mfma_f32_16x16x32_bf16 v[84:87], v[214:217], v[174:177], v[84:87]
	v_mfma_f32_16x16x32_bf16 v[72:75], v[190:193], v[182:185], v[72:75]
	v_mfma_f32_16x16x32_bf16 v[68:71], v[214:217], v[182:185], v[68:71]
	s_setprio 0
	s_barrier
	ds_read_b128 v[154:157], v3 offset:49152
	ds_read_b128 v[158:161], v3 offset:50176
	ds_read_b128 v[162:165], v3 offset:51200
	ds_read_b128 v[166:169], v3 offset:52224
	ds_read_b128 v[170:173], v3 offset:53248
	ds_read_b128 v[174:177], v3 offset:54272
	ds_read_b128 v[178:181], v3 offset:55296
	ds_read_b128 v[182:185], v3 offset:56320
	s_add_i32 s50, 0, 0x1c000
	s_add_u32 s16, s20, 0x80
	s_addc_u32 s17, s21, 0
	s_add_i32 s51, s64, s73
	s_mov_b32 m0, s51
	s_nop 0
	global_load_lds_dwordx4 v136, s[16:17]
	s_add_i32 m0, s51, 0x2000
	s_nop 0
	global_load_lds_dwordx4 v138, s[16:17]
	s_mov_b32 m0, s80
	s_nop 0
	global_load_lds_dwordx4 v136, s[48:49]
	s_mov_b32 m0, s81
	s_nop 0
	global_load_lds_dwordx4 v138, s[48:49]
	s_add_u32 s16, s20, 0x40080
	s_addc_u32 s17, s21, 0
	s_add_i32 s20, s50, s73
	s_mov_b32 m0, s20
	s_nop 0
	global_load_lds_dwordx4 v136, s[16:17]
	s_add_i32 m0, s20, 0x2000
	s_nop 0
	global_load_lds_dwordx4 v138, s[16:17]
	s_add_i32 s62, s62, 2
	s_add_u32 s52, s52, 0x100
	s_addc_u32 s53, s53, 0
	s_cmp_gt_u32 s62, 13
	s_mov_b64 s[16:17], s[18:19]
	s_waitcnt vmcnt(8)
	s_waitcnt lgkmcnt(0)
	s_barrier
	s_setprio 1
	v_mfma_f32_16x16x32_bf16 v[64:67], v[132:135], v[154:157], v[64:67]
	v_mfma_f32_16x16x32_bf16 v[60:63], v[146:149], v[154:157], v[60:63]
	v_mfma_f32_16x16x32_bf16 v[48:51], v[132:135], v[162:165], v[48:51]
	v_mfma_f32_16x16x32_bf16 v[44:47], v[146:149], v[162:165], v[44:47]
	v_mfma_f32_16x16x32_bf16 v[32:35], v[132:135], v[170:173], v[32:35]
	v_mfma_f32_16x16x32_bf16 v[28:31], v[146:149], v[170:173], v[28:31]
	v_mfma_f32_16x16x32_bf16 v[16:19], v[132:135], v[178:181], v[16:19]
	v_mfma_f32_16x16x32_bf16 v[12:15], v[146:149], v[178:181], v[12:15]
	v_mfma_f32_16x16x32_bf16 v[64:67], v[142:145], v[158:161], v[64:67]
	v_mfma_f32_16x16x32_bf16 v[60:63], v[150:153], v[158:161], v[60:63]
	v_mfma_f32_16x16x32_bf16 v[48:51], v[142:145], v[166:169], v[48:51]
	v_mfma_f32_16x16x32_bf16 v[44:47], v[150:153], v[166:169], v[44:47]
	v_mfma_f32_16x16x32_bf16 v[32:35], v[142:145], v[174:177], v[32:35]
	v_mfma_f32_16x16x32_bf16 v[28:31], v[150:153], v[174:177], v[28:31]
	v_mfma_f32_16x16x32_bf16 v[16:19], v[142:145], v[182:185], v[16:19]
	v_mfma_f32_16x16x32_bf16 v[12:15], v[150:153], v[182:185], v[12:15]
	s_setprio 0
	s_setprio 1
	v_mfma_f32_16x16x32_bf16 v[56:59], v[186:189], v[154:157], v[56:59]
	v_mfma_f32_16x16x32_bf16 v[52:55], v[210:213], v[154:157], v[52:55]
	v_mfma_f32_16x16x32_bf16 v[40:43], v[186:189], v[162:165], v[40:43]
	v_mfma_f32_16x16x32_bf16 v[36:39], v[210:213], v[162:165], v[36:39]
	v_mfma_f32_16x16x32_bf16 v[24:27], v[186:189], v[170:173], v[24:27]
	v_mfma_f32_16x16x32_bf16 v[20:23], v[210:213], v[170:173], v[20:23]
	v_mfma_f32_16x16x32_bf16 v[8:11], v[186:189], v[178:181], v[8:11]
	v_mfma_f32_16x16x32_bf16 v[4:7], v[210:213], v[178:181], v[4:7]
	v_mfma_f32_16x16x32_bf16 v[56:59], v[190:193], v[158:161], v[56:59]
	v_mfma_f32_16x16x32_bf16 v[52:55], v[214:217], v[158:161], v[52:55]
	v_mfma_f32_16x16x32_bf16 v[40:43], v[190:193], v[166:169], v[40:43]
	v_mfma_f32_16x16x32_bf16 v[36:39], v[214:217], v[166:169], v[36:39]
	v_mfma_f32_16x16x32_bf16 v[24:27], v[190:193], v[174:177], v[24:27]
	v_mfma_f32_16x16x32_bf16 v[20:23], v[214:217], v[174:177], v[20:23]
	v_mfma_f32_16x16x32_bf16 v[8:11], v[190:193], v[182:185], v[8:11]
	v_mfma_f32_16x16x32_bf16 v[4:7], v[214:217], v[182:185], v[4:7]
	s_setprio 0
	s_barrier
	s_cbranch_scc0 .LBB0_505
	v_mov_b32_e32 v132, v0
	s_lshl_b32 s16, s0, 2
	v_readfirstlane_b32 s1, v132
	s_bfe_u32 s9, s1, 0x20006
	s_ashr_i32 s1, s1, 2
	s_lshl_b32 s0, s8, 8
	s_andn2_b32 s1, s1, 63
	s_add_i32 s1, s1, s0
	v_and_or_b32 v142, v132, 15, s1
	v_ashrrev_i32_e32 v143, 31, v142
	v_bfe_u32 v134, v132, 4, 2
	v_lshl_add_u64 v[132:133], v[142:143], 2, s[24:25]
	global_load_dword v135, v[132:133], off
	global_load_dword v147, v[132:133], off offset:64
	global_load_dword v173, v[132:133], off offset:128
	global_load_dword v172, v[132:133], off offset:192
	global_load_dword v171, v[132:133], off offset:512
	global_load_dword v170, v[132:133], off offset:576
	global_load_dword v169, v[132:133], off offset:640
	global_load_dword v168, v[132:133], off offset:704
	s_or_b32 s17, s9, s16
	s_cmp_gt_i32 s17, 5
	s_cselect_b64 s[0:1], -1, 0
	s_cmp_gt_u32 s17, 9
	s_cselect_b64 s[8:9], -1, 0
	s_cmp_lg_u32 s17, 10
	s_cselect_b64 s[50:51], -1, 0
	s_cmp_gt_u32 s16, 11
	s_cselect_b64 s[48:49], -1, 0
	s_lshl_b32 s68, s17, 6
	s_add_i32 s16, s68, 0xfffffd00
	v_lshlrev_b32_e32 v157, 3, v134
	v_or_b32_e32 v144, s16, v157
	v_cmp_eq_u32_e64 s[16:17], 0, v134
	s_mov_b64 s[18:19], -1
	s_waitcnt vmcnt(0)
	v_fmamk_f32 v132, v135, 0x3a800000, v231
	v_cmp_gt_f32_e32 vcc, s11, v132
	v_mul_f32_e32 v133, 0x4b800000, v132
	s_nop 0
	v_cndmask_b32_e32 v132, v132, v133, vcc
	v_rsq_f32_e32 v132, v132
	s_nop 0
	v_mul_f32_e32 v133, 0x45800000, v132
	v_cndmask_b32_e32 v146, v132, v133, vcc
	s_and_b64 vcc, exec, s[0:1]
	s_cbranch_vccz .LBB0_519
	s_and_b64 vcc, exec, s[8:9]
	s_cbranch_vccz .LBB0_516
	s_and_b64 vcc, exec, s[50:51]
	s_cbranch_vccz .LBB0_512
	s_andn2_b64 vcc, exec, s[48:49]
	s_cbranch_vccnz .LBB0_511
	v_mov_b64_e32 v[148:149], s[38:39]
	s_movk_i32 s18, 0x480
	v_mad_i64_i32 v[148:149], s[18:19], v142, s18, v[148:149]
	v_mov_b32_e32 v145, v2
	v_pk_mul_f32 v[134:135], v[130:131], v[146:147] op_sel_hi:[1,0]
	v_pk_mul_f32 v[132:133], v[128:129], v[146:147] op_sel_hi:[1,0]
	v_lshl_add_u64 v[150:151], v[144:145], 2, v[148:149]
	global_store_dwordx4 v[150:151], v[132:135], off
	v_ashrrev_i32_e32 v145, 31, v144
	v_lshl_add_u64 v[148:149], v[144:145], 2, v[148:149]
	v_pk_mul_f32 v[134:135], v[126:127], v[146:147] op_sel_hi:[1,0]
	v_pk_mul_f32 v[132:133], v[124:125], v[146:147] op_sel_hi:[1,0]
	global_store_dwordx4 v[150:151], v[132:135], off offset:16
	s_nop 1
	v_pk_mul_f32 v[134:135], v[122:123], v[146:147] op_sel_hi:[1,0]
	v_pk_mul_f32 v[132:133], v[120:121], v[146:147] op_sel_hi:[1,0]
	global_store_dwordx4 v[148:149], v[132:135], off offset:128
	s_nop 1
	v_pk_mul_f32 v[134:135], v[118:119], v[146:147] op_sel_hi:[1,0]
	v_pk_mul_f32 v[132:133], v[116:117], v[146:147] op_sel_hi:[1,0]
	global_store_dwordx4 v[148:149], v[132:135], off offset:144

.LBB0_647:
	s_add_u32 s57, s22, 0x34d30000
	s_addc_u32 s62, s23, 0
	s_add_u32 s63, s22, 0x3048fc00
	s_addc_u32 s64, s23, 0
	s_lshl_b32 s16, s8, 13
	s_lshl_b32 s8, s9, 12
	s_and_b32 s17, s8, 0x3000
	s_add_u32 s8, s0, 0x80
	v_mov_b32_e32 v135, v2
	s_addc_u32 s9, s1, 0
	s_waitcnt vmcnt(2)
	s_barrier
	s_add_i32 m0, s52, 0x18000
	v_lshl_add_u64 v[4:5], s[8:9], 0, v[134:135]
	v_mov_b32_e32 v139, v2
	global_load_lds_dwordx4 v[4:5], off
	s_add_i32 m0, s52, 0x1a000
	v_lshl_add_u64 v[4:5], s[8:9], 0, v[138:139]
	s_add_u32 s8, s14, 0x80
	v_mov_b32_e32 v133, v2
	s_addc_u32 s9, s15, 0
	s_add_i32 s65, s52, 0x8000
	v_mov_b32_e32 v137, v2
	global_load_lds_dwordx4 v[4:5], off
	s_mov_b32 m0, s65
	v_lshl_add_u64 v[4:5], s[8:9], 0, v[132:133]
	s_add_i32 s67, s52, 0xa000
	global_load_lds_dwordx4 v[4:5], off
	v_lshl_add_u64 v[4:5], s[8:9], 0, v[136:137]
	s_add_u32 s8, s0, 0x10080
	s_mov_b32 m0, s67
	s_addc_u32 s9, s1, 0
	global_load_lds_dwordx4 v[4:5], off
	s_add_i32 m0, s52, 0x1c000
	v_lshl_add_u64 v[4:5], s[8:9], 0, v[134:135]
	global_load_lds_dwordx4 v[4:5], off
	v_lshl_add_u64 v[4:5], s[8:9], 0, v[138:139]
	s_add_i32 m0, s52, 0x1e000
	v_and_b32_e32 v3, 15, v1
	global_load_lds_dwordx4 v[4:5], off
	v_and_b32_e32 v4, 48, v1
	v_lshlrev_b32_e32 v3, 6, v3
	v_lshlrev_b32_e32 v1, 2, v1
	v_or_b32_e32 v5, v3, v4
	v_and_b32_e32 v1, 32, v1
	s_waitcnt vmcnt(6)
	v_readlane_b32 s8, v254, 41
	v_bitop3_b32 v3, v3, v1, v4 bitop3:0x36
	v_bitop3_b32 v4, v5, s16, v1 bitop3:0xde
	s_mov_b32 s73, s8
	v_readlane_b32 s8, v254, 40
	v_or_b32_e32 v1, s17, v3
	s_mov_b32 s68, 0
	v_add_u32_e32 v3, 0, v4
	s_mov_b32 s22, s8
	s_barrier
	v_readlane_b32 s9, v254, 42
	s_branch .LBB0_649

.LBB0_654:
	ds_read_b128 v[140:143], v218
	ds_read_b128 v[144:147], v218 offset:1024
	ds_read_b128 v[148:151], v218 offset:2048
	ds_read_b128 v[152:155], v218 offset:3072
	ds_read_b128 v[156:159], v3
	ds_read_b128 v[160:163], v3 offset:1024
	ds_read_b128 v[164:167], v3 offset:2048
	ds_read_b128 v[168:171], v3 offset:3072
	ds_read_b128 v[172:175], v3 offset:4096
	ds_read_b128 v[176:179], v3 offset:5120
	ds_read_b128 v[180:183], v3 offset:6144
	ds_read_b128 v[184:187], v3 offset:7168
	ds_read_b128 v[188:191], v218 offset:16384
	ds_read_b128 v[192:195], v218 offset:17408
	ds_read_b128 v[210:213], v218 offset:18432
	ds_read_b128 v[214:217], v218 offset:19456
	s_add_u32 s36, s14, s26
	s_addc_u32 s37, s15, s27
	s_add_u32 s38, s36, 0x100
	s_addc_u32 s39, s37, 0
	s_and_b64 s[30:31], s[28:29], exec
	s_cselect_b32 s41, s19, s39
	s_cselect_b32 s40, s18, s38
	s_add_u32 s26, s0, s26
	s_addc_u32 s27, s1, s27
	s_add_u32 s30, s26, 0x100
	s_addc_u32 s31, s27, 0
	s_add_u32 s26, s40, 0x80
	s_addc_u32 s27, s41, 0
	s_add_i32 s81, 0, 0x10000
	s_and_b64 s[28:29], s[28:29], exec
	s_cselect_b32 s43, s17, s31
	s_cselect_b32 s42, s23, s30
	s_add_u32 s44, s36, 0x12080
	s_addc_u32 s45, s37, 0
	s_add_i32 s86, s81, s51
	s_add_i32 m0, s52, 0xc000
	s_add_i32 s87, s52, 0xe000
	s_add_i32 s85, 0, 0x14000
	s_add_i32 s84, s86, 0x2000
	s_add_u32 s38, s42, 0x10000
	s_addc_u32 s39, s43, 0
	s_add_i32 s82, s85, s51
	s_add_i32 s80, s82, 0x2000
	s_add_i32 s79, 0, 0x18000
	s_add_u32 s36, s40, 0x12000
	s_addc_u32 s37, s41, 0
	s_add_i32 s75, 0, 0x1c000
	s_add_u32 s30, s42, 0x80
	s_addc_u32 s31, s43, 0
	s_add_i32 s78, s79, s51
	s_add_i32 s74, s78, 0x2000
	s_add_u32 s28, s42, 0x10080
	s_addc_u32 s29, s43, 0
	s_add_i32 s83, s75, s51
	s_add_i32 s81, s83, 0x2000
	s_nop 0
	global_load_lds_dwordx4 v132, s[44:45]
	s_mov_b32 m0, s87
	s_nop 0
	global_load_lds_dwordx4 v136, s[44:45]
	s_waitcnt vmcnt(8)
	s_waitcnt lgkmcnt(0)
	s_barrier
	s_setprio 1
	v_mfma_f32_16x16x32_bf16 v[128:131], v[140:143], v[156:159], v[128:131]
	v_mfma_f32_16x16x32_bf16 v[124:127], v[148:151], v[156:159], v[124:127]
	v_mfma_f32_16x16x32_bf16 v[112:115], v[140:143], v[164:167], v[112:115]
	v_mfma_f32_16x16x32_bf16 v[108:111], v[148:151], v[164:167], v[108:111]
	v_mfma_f32_16x16x32_bf16 v[96:99], v[140:143], v[172:175], v[96:99]
	v_mfma_f32_16x16x32_bf16 v[92:95], v[148:151], v[172:175], v[92:95]
	v_mfma_f32_16x16x32_bf16 v[80:83], v[140:143], v[180:183], v[80:83]
	v_mfma_f32_16x16x32_bf16 v[76:79], v[148:151], v[180:183], v[76:79]
	v_mfma_f32_16x16x32_bf16 v[128:131], v[144:147], v[160:163], v[128:131]
	v_mfma_f32_16x16x32_bf16 v[124:127], v[152:155], v[160:163], v[124:127]
	v_mfma_f32_16x16x32_bf16 v[112:115], v[144:147], v[168:171], v[112:115]
	v_mfma_f32_16x16x32_bf16 v[108:111], v[152:155], v[168:171], v[108:111]
	v_mfma_f32_16x16x32_bf16 v[96:99], v[144:147], v[176:179], v[96:99]
	v_mfma_f32_16x16x32_bf16 v[92:95], v[152:155], v[176:179], v[92:95]
	v_mfma_f32_16x16x32_bf16 v[80:83], v[144:147], v[184:187], v[80:83]
	v_mfma_f32_16x16x32_bf16 v[76:79], v[152:155], v[184:187], v[76:79]
	s_setprio 0
	s_setprio 1
	v_mfma_f32_16x16x32_bf16 v[120:123], v[188:191], v[156:159], v[120:123]
	v_mfma_f32_16x16x32_bf16 v[116:119], v[210:213], v[156:159], v[116:119]
	v_mfma_f32_16x16x32_bf16 v[104:107], v[188:191], v[164:167], v[104:107]
	v_mfma_f32_16x16x32_bf16 v[100:103], v[210:213], v[164:167], v[100:103]
	v_mfma_f32_16x16x32_bf16 v[88:91], v[188:191], v[172:175], v[88:91]
	v_mfma_f32_16x16x32_bf16 v[84:87], v[210:213], v[172:175], v[84:87]
	v_mfma_f32_16x16x32_bf16 v[72:75], v[188:191], v[180:183], v[72:75]
	v_mfma_f32_16x16x32_bf16 v[68:71], v[210:213], v[180:183], v[68:71]
	v_mfma_f32_16x16x32_bf16 v[120:123], v[192:195], v[160:163], v[120:123]
	v_mfma_f32_16x16x32_bf16 v[116:119], v[214:217], v[160:163], v[116:119]
	v_mfma_f32_16x16x32_bf16 v[104:107], v[192:195], v[168:171], v[104:107]
	v_mfma_f32_16x16x32_bf16 v[100:103], v[214:217], v[168:171], v[100:103]
	v_mfma_f32_16x16x32_bf16 v[88:91], v[192:195], v[176:179], v[88:91]
	v_mfma_f32_16x16x32_bf16 v[84:87], v[214:217], v[176:179], v[84:87]
	v_mfma_f32_16x16x32_bf16 v[72:75], v[192:195], v[184:187], v[72:75]
	v_mfma_f32_16x16x32_bf16 v[68:71], v[214:217], v[184:187], v[68:71]
	s_setprio 0
	s_barrier
	ds_read_b128 v[156:159], v3 offset:16384
	ds_read_b128 v[160:163], v3 offset:17408
	ds_read_b128 v[164:167], v3 offset:18432
	ds_read_b128 v[168:171], v3 offset:19456
	ds_read_b128 v[172:175], v3 offset:20480
	ds_read_b128 v[176:179], v3 offset:21504
	ds_read_b128 v[180:183], v3 offset:22528
	ds_read_b128 v[184:187], v3 offset:23552
	s_mov_b32 m0, s86
	s_nop 0
	global_load_lds_dwordx4 v134, s[42:43]
	s_mov_b32 m0, s84
	s_nop 0
	global_load_lds_dwordx4 v138, s[42:43]
	s_mov_b32 m0, s52
	s_nop 0
	global_load_lds_dwordx4 v132, s[40:41]
	s_mov_b32 m0, s53
	s_nop 0
	global_load_lds_dwordx4 v136, s[40:41]
	s_mov_b32 m0, s82
	s_nop 0
	global_load_lds_dwordx4 v134, s[38:39]
	s_mov_b32 m0, s80
	s_nop 0
	global_load_lds_dwordx4 v138, s[38:39]
	s_waitcnt vmcnt(8)
	s_waitcnt lgkmcnt(0)
	s_barrier
	s_setprio 1
	v_mfma_f32_16x16x32_bf16 v[64:67], v[140:143], v[156:159], v[64:67]
	v_mfma_f32_16x16x32_bf16 v[60:63], v[148:151], v[156:159], v[60:63]
	v_mfma_f32_16x16x32_bf16 v[48:51], v[140:143], v[164:167], v[48:51]
	v_mfma_f32_16x16x32_bf16 v[44:47], v[148:151], v[164:167], v[44:47]
	v_mfma_f32_16x16x32_bf16 v[32:35], v[140:143], v[172:175], v[32:35]
	v_mfma_f32_16x16x32_bf16 v[28:31], v[148:151], v[172:175], v[28:31]
	v_mfma_f32_16x16x32_bf16 v[16:19], v[140:143], v[180:183], v[16:19]
	v_mfma_f32_16x16x32_bf16 v[12:15], v[148:151], v[180:183], v[12:15]
	v_mfma_f32_16x16x32_bf16 v[64:67], v[144:147], v[160:163], v[64:67]
	v_mfma_f32_16x16x32_bf16 v[60:63], v[152:155], v[160:163], v[60:63]
	v_mfma_f32_16x16x32_bf16 v[48:51], v[144:147], v[168:171], v[48:51]
	v_mfma_f32_16x16x32_bf16 v[44:47], v[152:155], v[168:171], v[44:47]
	v_mfma_f32_16x16x32_bf16 v[32:35], v[144:147], v[176:179], v[32:35]
	v_mfma_f32_16x16x32_bf16 v[28:31], v[152:155], v[176:179], v[28:31]
	v_mfma_f32_16x16x32_bf16 v[16:19], v[144:147], v[184:187], v[16:19]
	v_mfma_f32_16x16x32_bf16 v[12:15], v[152:155], v[184:187], v[12:15]
	s_setprio 0
	s_setprio 1
	v_mfma_f32_16x16x32_bf16 v[56:59], v[188:191], v[156:159], v[56:59]
	v_mfma_f32_16x16x32_bf16 v[52:55], v[210:213], v[156:159], v[52:55]
	v_mfma_f32_16x16x32_bf16 v[40:43], v[188:191], v[164:167], v[40:43]
	v_mfma_f32_16x16x32_bf16 v[36:39], v[210:213], v[164:167], v[36:39]
	v_mfma_f32_16x16x32_bf16 v[24:27], v[188:191], v[172:175], v[24:27]
	v_mfma_f32_16x16x32_bf16 v[20:23], v[210:213], v[172:175], v[20:23]
	v_mfma_f32_16x16x32_bf16 v[8:11], v[188:191], v[180:183], v[8:11]
	v_mfma_f32_16x16x32_bf16 v[4:7], v[210:213], v[180:183], v[4:7]
	v_mfma_f32_16x16x32_bf16 v[56:59], v[192:195], v[160:163], v[56:59]
	v_mfma_f32_16x16x32_bf16 v[52:55], v[214:217], v[160:163], v[52:55]
	v_mfma_f32_16x16x32_bf16 v[40:43], v[192:195], v[168:171], v[40:43]
	v_mfma_f32_16x16x32_bf16 v[36:39], v[214:217], v[168:171], v[36:39]
	v_mfma_f32_16x16x32_bf16 v[24:27], v[192:195], v[176:179], v[24:27]
	v_mfma_f32_16x16x32_bf16 v[20:23], v[214:217], v[176:179], v[20:23]
	v_mfma_f32_16x16x32_bf16 v[8:11], v[192:195], v[184:187], v[8:11]
	v_mfma_f32_16x16x32_bf16 v[4:7], v[214:217], v[184:187], v[4:7]
	s_setprio 0
	s_barrier
	ds_read_b128 v[140:143], v218 offset:32768
	ds_read_b128 v[144:147], v218 offset:33792
	ds_read_b128 v[148:151], v218 offset:34816
	ds_read_b128 v[152:155], v218 offset:35840
	ds_read_b128 v[156:159], v3 offset:32768
	ds_read_b128 v[160:163], v3 offset:33792
	ds_read_b128 v[164:167], v3 offset:34816
	ds_read_b128 v[168:171], v3 offset:35840
	ds_read_b128 v[172:175], v3 offset:36864
	ds_read_b128 v[176:179], v3 offset:37888
	ds_read_b128 v[180:183], v3 offset:38912
	ds_read_b128 v[184:187], v3 offset:39936
	ds_read_b128 v[188:191], v218 offset:49152
	ds_read_b128 v[192:195], v218 offset:50176
	ds_read_b128 v[210:213], v218 offset:51200
	ds_read_b128 v[214:217], v218 offset:52224
	s_mov_b32 m0, s55
	s_nop 0
	global_load_lds_dwordx4 v132, s[36:37]
	s_mov_b32 m0, s56
	s_nop 0
	global_load_lds_dwordx4 v136, s[36:37]
	s_waitcnt vmcnt(8)
	s_waitcnt lgkmcnt(0)
	s_barrier
	s_setprio 1
	v_mfma_f32_16x16x32_bf16 v[128:131], v[140:143], v[156:159], v[128:131]
	v_mfma_f32_16x16x32_bf16 v[124:127], v[148:151], v[156:159], v[124:127]
	v_mfma_f32_16x16x32_bf16 v[112:115], v[140:143], v[164:167], v[112:115]
	v_mfma_f32_16x16x32_bf16 v[108:111], v[148:151], v[164:167], v[108:111]
	v_mfma_f32_16x16x32_bf16 v[96:99], v[140:143], v[172:175], v[96:99]
	v_mfma_f32_16x16x32_bf16 v[92:95], v[148:151], v[172:175], v[92:95]
	v_mfma_f32_16x16x32_bf16 v[80:83], v[140:143], v[180:183], v[80:83]
	v_mfma_f32_16x16x32_bf16 v[76:79], v[148:151], v[180:183], v[76:79]
	v_mfma_f32_16x16x32_bf16 v[128:131], v[144:147], v[160:163], v[128:131]
	v_mfma_f32_16x16x32_bf16 v[124:127], v[152:155], v[160:163], v[124:127]
	v_mfma_f32_16x16x32_bf16 v[112:115], v[144:147], v[168:171], v[112:115]
	v_mfma_f32_16x16x32_bf16 v[108:111], v[152:155], v[168:171], v[108:111]
	v_mfma_f32_16x16x32_bf16 v[96:99], v[144:147], v[176:179], v[96:99]
	v_mfma_f32_16x16x32_bf16 v[92:95], v[152:155], v[176:179], v[92:95]
	v_mfma_f32_16x16x32_bf16 v[80:83], v[144:147], v[184:187], v[80:83]
	v_mfma_f32_16x16x32_bf16 v[76:79], v[152:155], v[184:187], v[76:79]
	s_setprio 0
	s_setprio 1
	v_mfma_f32_16x16x32_bf16 v[120:123], v[188:191], v[156:159], v[120:123]
	v_mfma_f32_16x16x32_bf16 v[116:119], v[210:213], v[156:159], v[116:119]
	v_mfma_f32_16x16x32_bf16 v[104:107], v[188:191], v[164:167], v[104:107]
	v_mfma_f32_16x16x32_bf16 v[100:103], v[210:213], v[164:167], v[100:103]
	v_mfma_f32_16x16x32_bf16 v[88:91], v[188:191], v[172:175], v[88:91]
	v_mfma_f32_16x16x32_bf16 v[84:87], v[210:213], v[172:175], v[84:87]
	v_mfma_f32_16x16x32_bf16 v[72:75], v[188:191], v[180:183], v[72:75]
	v_mfma_f32_16x16x32_bf16 v[68:71], v[210:213], v[180:183], v[68:71]
	v_mfma_f32_16x16x32_bf16 v[120:123], v[192:195], v[160:163], v[120:123]
	v_mfma_f32_16x16x32_bf16 v[116:119], v[214:217], v[160:163], v[116:119]
	v_mfma_f32_16x16x32_bf16 v[104:107], v[192:195], v[168:171], v[104:107]
	v_mfma_f32_16x16x32_bf16 v[100:103], v[214:217], v[168:171], v[100:103]
	v_mfma_f32_16x16x32_bf16 v[88:91], v[192:195], v[176:179], v[88:91]
	v_mfma_f32_16x16x32_bf16 v[84:87], v[214:217], v[176:179], v[84:87]
	v_mfma_f32_16x16x32_bf16 v[72:75], v[192:195], v[184:187], v[72:75]
	v_mfma_f32_16x16x32_bf16 v[68:71], v[214:217], v[184:187], v[68:71]
	s_setprio 0
	s_barrier
	ds_read_b128 v[156:159], v3 offset:49152
	ds_read_b128 v[160:163], v3 offset:50176
	ds_read_b128 v[164:167], v3 offset:51200
	ds_read_b128 v[168:171], v3 offset:52224
	ds_read_b128 v[172:175], v3 offset:53248
	ds_read_b128 v[176:179], v3 offset:54272
	ds_read_b128 v[180:183], v3 offset:55296
	ds_read_b128 v[184:187], v3 offset:56320
	s_mov_b32 m0, s78
	s_nop 0
	global_load_lds_dwordx4 v134, s[30:31]
	s_mov_b32 m0, s74
	s_nop 0
	global_load_lds_dwordx4 v138, s[30:31]
	s_mov_b32 m0, s65
	s_nop 0
	global_load_lds_dwordx4 v132, s[26:27]
	s_mov_b32 m0, s67
	s_nop 0
	global_load_lds_dwordx4 v136, s[26:27]
	s_mov_b32 m0, s83
	s_nop 0
	global_load_lds_dwordx4 v134, s[28:29]
	s_mov_b32 m0, s81
	s_nop 0
	global_load_lds_dwordx4 v138, s[28:29]
	s_andn2_b64 vcc, exec, s[24:25]
	s_mov_b64 s[28:29], -1
	s_mov_b64 s[24:25], 0
	s_mov_b64 s[26:27], 0x100
	s_waitcnt vmcnt(8)
	s_waitcnt lgkmcnt(0)
	s_barrier
	s_setprio 1
	v_mfma_f32_16x16x32_bf16 v[64:67], v[140:143], v[156:159], v[64:67]
	v_mfma_f32_16x16x32_bf16 v[60:63], v[148:151], v[156:159], v[60:63]
	v_mfma_f32_16x16x32_bf16 v[48:51], v[140:143], v[164:167], v[48:51]
	v_mfma_f32_16x16x32_bf16 v[44:47], v[148:151], v[164:167], v[44:47]
	v_mfma_f32_16x16x32_bf16 v[32:35], v[140:143], v[172:175], v[32:35]
	v_mfma_f32_16x16x32_bf16 v[28:31], v[148:151], v[172:175], v[28:31]
	v_mfma_f32_16x16x32_bf16 v[16:19], v[140:143], v[180:183], v[16:19]
	v_mfma_f32_16x16x32_bf16 v[12:15], v[148:151], v[180:183], v[12:15]
	v_mfma_f32_16x16x32_bf16 v[64:67], v[144:147], v[160:163], v[64:67]
	v_mfma_f32_16x16x32_bf16 v[60:63], v[152:155], v[160:163], v[60:63]
	v_mfma_f32_16x16x32_bf16 v[48:51], v[144:147], v[168:171], v[48:51]
	v_mfma_f32_16x16x32_bf16 v[44:47], v[152:155], v[168:171], v[44:47]
	v_mfma_f32_16x16x32_bf16 v[32:35], v[144:147], v[176:179], v[32:35]
	v_mfma_f32_16x16x32_bf16 v[28:31], v[152:155], v[176:179], v[28:31]
	v_mfma_f32_16x16x32_bf16 v[16:19], v[144:147], v[184:187], v[16:19]
	v_mfma_f32_16x16x32_bf16 v[12:15], v[152:155], v[184:187], v[12:15]
	s_setprio 0
	s_setprio 1
	v_mfma_f32_16x16x32_bf16 v[56:59], v[188:191], v[156:159], v[56:59]
	v_mfma_f32_16x16x32_bf16 v[52:55], v[210:213], v[156:159], v[52:55]
	v_mfma_f32_16x16x32_bf16 v[40:43], v[188:191], v[164:167], v[40:43]
	v_mfma_f32_16x16x32_bf16 v[36:39], v[210:213], v[164:167], v[36:39]
	v_mfma_f32_16x16x32_bf16 v[24:27], v[188:191], v[172:175], v[24:27]
	v_mfma_f32_16x16x32_bf16 v[20:23], v[210:213], v[172:175], v[20:23]
	v_mfma_f32_16x16x32_bf16 v[8:11], v[188:191], v[180:183], v[8:11]
	v_mfma_f32_16x16x32_bf16 v[4:7], v[210:213], v[180:183], v[4:7]
	v_mfma_f32_16x16x32_bf16 v[56:59], v[192:195], v[160:163], v[56:59]
	v_mfma_f32_16x16x32_bf16 v[52:55], v[214:217], v[160:163], v[52:55]
	v_mfma_f32_16x16x32_bf16 v[40:43], v[192:195], v[168:171], v[40:43]
	v_mfma_f32_16x16x32_bf16 v[36:39], v[214:217], v[168:171], v[36:39]
	v_mfma_f32_16x16x32_bf16 v[24:27], v[192:195], v[176:179], v[24:27]
	v_mfma_f32_16x16x32_bf16 v[20:23], v[214:217], v[176:179], v[20:23]
	v_mfma_f32_16x16x32_bf16 v[8:11], v[192:195], v[184:187], v[8:11]
	v_mfma_f32_16x16x32_bf16 v[4:7], v[214:217], v[184:187], v[4:7]
	s_setprio 0
	s_barrier
	s_cbranch_vccz .LBB0_654
	v_mov_b32_e32 v141, v0
	s_ashr_i32 s23, s22, 31
	v_readfirstlane_b32 s0, v141
	s_bfe_u32 s17, s0, 0x20006
	s_ashr_i32 s0, s0, 2
	s_andn2_b32 s0, s0, 63
	s_ashr_i32 s1, s0, 31
	s_lshl_b64 s[14:15], s[22:23], 10
	s_add_u32 s24, s57, s14
	s_addc_u32 s25, s62, s15
	s_lshl_b64 s[14:15], s[0:1], 2
	v_and_b32_e32 v142, 15, v141
	s_add_u32 s24, s24, s14
	s_addc_u32 s25, s25, s15
	v_lshlrev_b32_e32 v140, 2, v142
	global_load_dword v150, v140, s[24:25] offset:64
	global_load_dword v149, v140, s[24:25] offset:128
	global_load_dword v148, v140, s[24:25] offset:192
	global_load_dword v147, v140, s[24:25] offset:512
	global_load_dword v146, v140, s[24:25] offset:576
	global_load_dword v145, v140, s[24:25] offset:640
	global_load_dword v144, v140, s[24:25] offset:704
	v_mul_f32_e32 v129, v129, v129
	v_mul_f32_e32 v125, v125, v125
	v_mul_f32_e32 v121, v121, v121
	v_mul_f32_e32 v117, v117, v117
	v_fmac_f32_e32 v129, v128, v128
	v_mul_f32_e32 v128, v131, v131
	v_fmac_f32_e32 v125, v124, v124
	v_mul_f32_e32 v124, v127, v127
	v_fmac_f32_e32 v121, v120, v120
	v_mul_f32_e32 v120, v123, v123
	v_fmac_f32_e32 v117, v116, v116
	v_mul_f32_e32 v116, v119, v119
	v_fmac_f32_e32 v128, v130, v130
	v_fmac_f32_e32 v124, v126, v126
	v_fmac_f32_e32 v120, v122, v122
	v_fmac_f32_e32 v116, v118, v118
	v_add_f32_e32 v128, v129, v128
	v_add_f32_e32 v124, v125, v124
	v_add_f32_e32 v120, v121, v120
	v_add_f32_e32 v116, v117, v116
	v_add_f32_e32 v124, v128, v124
	v_add_f32_e32 v116, v120, v116
	v_add_f32_e32 v117, v124, v116
	ds_swizzle_b32 v118, v117 offset:swizzle(SWAP,16)
	v_and_b32_e32 v152, 64, v236
	v_xor_b32_e32 v151, 32, v236
	v_add_u32_e32 v152, 64, v152
	v_cmp_lt_i32_e32 vcc, v151, v152
	s_lshl_b32 s14, s73, 2
	s_or_b32 s26, s17, s14
	v_cndmask_b32_e32 v116, v236, v151, vcc
	s_lshl_b64 s[14:15], s[22:23], 8
	v_lshlrev_b32_e32 v116, 2, v116
	s_waitcnt lgkmcnt(0)
	v_add_f32_e32 v117, v117, v118
	s_add_u32 s0, s14, s0
	ds_bpermute_b32 v118, v116, v117
	s_addc_u32 s1, s15, s1
	s_ashr_i32 s27, s26, 31
	v_or_b32_e32 v143, s0, v142
	v_mov_b32_e32 v142, s1
	s_lshl_b64 s[0:1], s[26:27], 2
	v_and_b32_e32 v119, 48, v141
	s_add_u32 s0, s63, s0
	v_cmp_eq_u32_e64 s[14:15], 0, v119
	s_addc_u32 s1, s64, s1
	s_and_saveexec_b64 s[22:23], s[14:15]
	s_cbranch_execz .LBB0_657
	v_mov_b32_e32 v141, v2
	v_lshl_add_u64 v[120:121], s[24:25], 0, v[140:141]
	global_load_dword v119, v[120:121], off
	s_waitcnt lgkmcnt(0)
	v_add_f32_e32 v117, v117, v118
	s_waitcnt vmcnt(0)
	v_add_f32_e32 v117, v117, v119
	v_fmamk_f32 v117, v117, 0x3c2aaaab, v231
	v_cmp_gt_f32_e32 vcc, s11, v117
	v_mul_f32_e32 v118, 0x4b800000, v117
	s_nop 0
	v_cndmask_b32_e32 v117, v117, v118, vcc
	v_rsq_f32_e32 v117, v117
	s_nop 0
	v_mul_f32_e32 v118, 0x45800000, v117
	v_cndmask_b32_e32 v117, v117, v118, vcc
	v_mad_u64_u32 v[118:119], s[24:25], v143, 48, s[0:1]
	v_mov_b32_e32 v120, v119
	v_mad_u64_u32 v[120:121], s[24:25], v142, 48, v[120:121]
	v_mov_b32_e32 v119, v120
	global_store_dword v[118:119], v117, off

.LBB0_754:
	s_add_u32 s6, s30, s54
	s_addc_u32 s7, s31, s35
	s_add_u32 s6, s6, 0x97400
	s_addc_u32 s7, s7, 0
	s_mul_i32 s19, s92, 0xc3000
	s_mul_hi_u32 s18, s92, 0xc3000
	s_add_u32 s19, s30, s19
	s_addc_u32 s18, s31, s18
	s_add_u32 s35, s19, 0xb7c00
	s_addc_u32 s54, s18, 0
	s_add_u32 s28, s30, 0x14493c00
	s_mul_i32 s68, s92, 0x60
	s_addc_u32 s29, s31, 0
	s_lshl_b64 s[18:19], s[68:69], 2
	v_and_b32_e32 v3, 15, v1
	s_add_u32 s40, s0, s18
	v_and_b32_e32 v4, 48, v1
	v_lshlrev_b32_e32 v3, 6, v3
	v_lshlrev_b32_e32 v1, 2, v1
	s_addc_u32 s41, s1, s19
	v_or_b32_e32 v5, v3, v4
	s_lshl_b32 s0, s16, 13
	v_and_b32_e32 v1, 32, v1
	v_bitop3_b32 v6, v5, s0, v1 bitop3:0xde
	s_lshl_b32 s0, s17, 12
	v_bitop3_b32 v3, v3, v1, v4 bitop3:0x36
	s_and_b32 s0, s0, 0x3000
	v_or_b32_e32 v1, s0, v3
	s_add_u32 s0, s22, 0x80
	v_mov_b32_e32 v149, v2
	s_addc_u32 s1, s23, 0
	s_waitcnt vmcnt(2)
	s_barrier
	s_add_i32 m0, s57, 0x18000
	v_lshl_add_u64 v[4:5], s[0:1], 0, v[148:149]
	v_mov_b32_e32 v151, v2
	global_load_lds_dwordx4 v[4:5], off
	s_add_i32 m0, s57, 0x1a000
	v_lshl_add_u64 v[4:5], s[0:1], 0, v[150:151]
	s_add_u32 s0, s8, 0x80
	s_addc_u32 s1, s9, 0
	s_add_i32 s68, s57, 0x8000
	global_load_lds_dwordx4 v[4:5], off
	s_mov_b32 m0, s68
	v_lshl_add_u64 v[4:5], s[0:1], 0, v[148:149]
	s_add_i32 s74, s57, 0xa000
	global_load_lds_dwordx4 v[4:5], off
	v_lshl_add_u64 v[4:5], s[0:1], 0, v[150:151]
	s_add_u32 s0, s22, 0x18080
	s_mov_b32 m0, s74
	s_addc_u32 s1, s23, 0
	global_load_lds_dwordx4 v[4:5], off
	s_add_i32 m0, s57, 0x1c000
	v_lshl_add_u64 v[4:5], s[0:1], 0, v[148:149]
	global_load_lds_dwordx4 v[4:5], off
	v_lshl_add_u64 v[4:5], s[0:1], 0, v[150:151]
	s_add_i32 m0, s57, 0x1e000
	s_mov_b32 s75, 0
	global_load_lds_dwordx4 v[4:5], off
	s_waitcnt vmcnt(6)
	v_add_u32_e32 v3, 0, v6
	s_barrier
	s_branch .LBB0_758

.LBB0_769:
	ds_read_b128 v[132:135], v216
	ds_read_b128 v[136:139], v216 offset:1024
	ds_read_b128 v[140:143], v216 offset:2048
	ds_read_b128 v[144:147], v216 offset:3072
	ds_read_b128 v[152:155], v3
	ds_read_b128 v[156:159], v3 offset:1024
	ds_read_b128 v[160:163], v3 offset:2048
	ds_read_b128 v[164:167], v3 offset:3072
	ds_read_b128 v[168:171], v3 offset:4096
	ds_read_b128 v[172:175], v3 offset:5120
	ds_read_b128 v[176:179], v3 offset:6144
	ds_read_b128 v[180:183], v3 offset:7168
	ds_read_b128 v[184:187], v216 offset:16384
	ds_read_b128 v[188:191], v216 offset:17408
	ds_read_b128 v[192:195], v216 offset:18432
	ds_read_b128 v[210:213], v216 offset:19456
	s_add_u32 s0, s8, 0x100
	s_addc_u32 s1, s9, 0
	s_cmp_eq_u32 s62, 2
	s_cselect_b32 s22, s42, s0
	s_cselect_b32 s23, s43, s1
	s_cselect_b32 s18, s44, s47
	s_cselect_b32 s19, s45, s49
	s_add_u32 s20, s22, 0x80
	s_addc_u32 s21, s23, 0
	s_add_i32 s64, 0, 0x10000
	s_add_u32 s8, s8, 0x18080
	s_addc_u32 s9, s9, 0
	s_add_i32 m0, s57, 0xc000
	s_nop 0
	global_load_lds_dwordx4 v148, s[8:9]
	s_add_i32 m0, s57, 0xe000
	s_nop 0
	global_load_lds_dwordx4 v150, s[8:9]
	s_waitcnt vmcnt(8)
	s_waitcnt lgkmcnt(0)
	s_barrier
	s_setprio 1
	v_mfma_f32_16x16x32_bf16 v[128:131], v[132:135], v[152:155], v[128:131]
	v_mfma_f32_16x16x32_bf16 v[124:127], v[140:143], v[152:155], v[124:127]
	v_mfma_f32_16x16x32_bf16 v[112:115], v[132:135], v[160:163], v[112:115]
	v_mfma_f32_16x16x32_bf16 v[108:111], v[140:143], v[160:163], v[108:111]
	v_mfma_f32_16x16x32_bf16 v[96:99], v[132:135], v[168:171], v[96:99]
	v_mfma_f32_16x16x32_bf16 v[92:95], v[140:143], v[168:171], v[92:95]
	v_mfma_f32_16x16x32_bf16 v[80:83], v[132:135], v[176:179], v[80:83]
	v_mfma_f32_16x16x32_bf16 v[76:79], v[140:143], v[176:179], v[76:79]
	v_mfma_f32_16x16x32_bf16 v[128:131], v[136:139], v[156:159], v[128:131]
	v_mfma_f32_16x16x32_bf16 v[124:127], v[144:147], v[156:159], v[124:127]
	v_mfma_f32_16x16x32_bf16 v[112:115], v[136:139], v[164:167], v[112:115]
	v_mfma_f32_16x16x32_bf16 v[108:111], v[144:147], v[164:167], v[108:111]
	v_mfma_f32_16x16x32_bf16 v[96:99], v[136:139], v[172:175], v[96:99]
	v_mfma_f32_16x16x32_bf16 v[92:95], v[144:147], v[172:175], v[92:95]
	v_mfma_f32_16x16x32_bf16 v[80:83], v[136:139], v[180:183], v[80:83]
	v_mfma_f32_16x16x32_bf16 v[76:79], v[144:147], v[180:183], v[76:79]
	s_setprio 0
	s_setprio 1
	v_mfma_f32_16x16x32_bf16 v[120:123], v[184:187], v[152:155], v[120:123]
	v_mfma_f32_16x16x32_bf16 v[116:119], v[192:195], v[152:155], v[116:119]
	v_mfma_f32_16x16x32_bf16 v[104:107], v[184:187], v[160:163], v[104:107]
	v_mfma_f32_16x16x32_bf16 v[100:103], v[192:195], v[160:163], v[100:103]
	v_mfma_f32_16x16x32_bf16 v[88:91], v[184:187], v[168:171], v[88:91]
	v_mfma_f32_16x16x32_bf16 v[84:87], v[192:195], v[168:171], v[84:87]
	v_mfma_f32_16x16x32_bf16 v[72:75], v[184:187], v[176:179], v[72:75]
	v_mfma_f32_16x16x32_bf16 v[68:71], v[192:195], v[176:179], v[68:71]
	v_mfma_f32_16x16x32_bf16 v[120:123], v[188:191], v[156:159], v[120:123]
	v_mfma_f32_16x16x32_bf16 v[116:119], v[210:213], v[156:159], v[116:119]
	v_mfma_f32_16x16x32_bf16 v[104:107], v[188:191], v[164:167], v[104:107]
	v_mfma_f32_16x16x32_bf16 v[100:103], v[210:213], v[164:167], v[100:103]
	v_mfma_f32_16x16x32_bf16 v[88:91], v[188:191], v[172:175], v[88:91]
	v_mfma_f32_16x16x32_bf16 v[84:87], v[210:213], v[172:175], v[84:87]
	v_mfma_f32_16x16x32_bf16 v[72:75], v[188:191], v[180:183], v[72:75]
	v_mfma_f32_16x16x32_bf16 v[68:71], v[210:213], v[180:183], v[68:71]
	s_setprio 0
	s_barrier
	ds_read_b128 v[152:155], v3 offset:16384
	ds_read_b128 v[156:159], v3 offset:17408
	ds_read_b128 v[160:163], v3 offset:18432
	ds_read_b128 v[164:167], v3 offset:19456
	ds_read_b128 v[168:171], v3 offset:20480
	ds_read_b128 v[172:175], v3 offset:21504
	ds_read_b128 v[176:179], v3 offset:22528
	ds_read_b128 v[180:183], v3 offset:23552
	s_add_i32 s65, 0, 0x14000
	s_mov_b64 s[8:9], s[18:19]
	s_add_i32 s64, s64, s56
	s_mov_b32 m0, s64
	s_nop 0
	global_load_lds_dwordx4 v148, s[8:9]
	s_add_i32 m0, s64, 0x2000
	s_nop 0
	global_load_lds_dwordx4 v150, s[8:9]
	s_mov_b64 s[8:9], s[22:23]
	s_mov_b32 m0, s57
	s_nop 0
	global_load_lds_dwordx4 v148, s[8:9]
	s_mov_b32 m0, s63
	s_nop 0
	global_load_lds_dwordx4 v150, s[8:9]
	s_add_u32 s8, s18, 0x18000
	s_addc_u32 s9, s19, 0
	s_add_i32 s64, s65, s56
	s_mov_b32 m0, s64
	s_nop 0
	global_load_lds_dwordx4 v148, s[8:9]
	s_add_i32 m0, s64, 0x2000
	s_nop 0
	global_load_lds_dwordx4 v150, s[8:9]
	s_add_i32 s64, 0, 0x18000
	s_waitcnt vmcnt(8)
	s_waitcnt lgkmcnt(0)
	s_barrier
	s_setprio 1
	v_mfma_f32_16x16x32_bf16 v[64:67], v[132:135], v[152:155], v[64:67]
	v_mfma_f32_16x16x32_bf16 v[60:63], v[140:143], v[152:155], v[60:63]
	v_mfma_f32_16x16x32_bf16 v[48:51], v[132:135], v[160:163], v[48:51]
	v_mfma_f32_16x16x32_bf16 v[44:47], v[140:143], v[160:163], v[44:47]
	v_mfma_f32_16x16x32_bf16 v[32:35], v[132:135], v[168:171], v[32:35]
	v_mfma_f32_16x16x32_bf16 v[28:31], v[140:143], v[168:171], v[28:31]
	v_mfma_f32_16x16x32_bf16 v[16:19], v[132:135], v[176:179], v[16:19]
	v_mfma_f32_16x16x32_bf16 v[12:15], v[140:143], v[176:179], v[12:15]
	v_mfma_f32_16x16x32_bf16 v[64:67], v[136:139], v[156:159], v[64:67]
	v_mfma_f32_16x16x32_bf16 v[60:63], v[144:147], v[156:159], v[60:63]
	v_mfma_f32_16x16x32_bf16 v[48:51], v[136:139], v[164:167], v[48:51]
	v_mfma_f32_16x16x32_bf16 v[44:47], v[144:147], v[164:167], v[44:47]
	v_mfma_f32_16x16x32_bf16 v[32:35], v[136:139], v[172:175], v[32:35]
	v_mfma_f32_16x16x32_bf16 v[28:31], v[144:147], v[172:175], v[28:31]
	v_mfma_f32_16x16x32_bf16 v[16:19], v[136:139], v[180:183], v[16:19]
	v_mfma_f32_16x16x32_bf16 v[12:15], v[144:147], v[180:183], v[12:15]
	s_setprio 0
	s_setprio 1
	v_mfma_f32_16x16x32_bf16 v[56:59], v[184:187], v[152:155], v[56:59]
	v_mfma_f32_16x16x32_bf16 v[52:55], v[192:195], v[152:155], v[52:55]
	v_mfma_f32_16x16x32_bf16 v[40:43], v[184:187], v[160:163], v[40:43]
	v_mfma_f32_16x16x32_bf16 v[36:39], v[192:195], v[160:163], v[36:39]
	v_mfma_f32_16x16x32_bf16 v[24:27], v[184:187], v[168:171], v[24:27]
	v_mfma_f32_16x16x32_bf16 v[20:23], v[192:195], v[168:171], v[20:23]
	v_mfma_f32_16x16x32_bf16 v[8:11], v[184:187], v[176:179], v[8:11]
	v_mfma_f32_16x16x32_bf16 v[4:7], v[192:195], v[176:179], v[4:7]
	v_mfma_f32_16x16x32_bf16 v[56:59], v[188:191], v[156:159], v[56:59]
	v_mfma_f32_16x16x32_bf16 v[52:55], v[210:213], v[156:159], v[52:55]
	v_mfma_f32_16x16x32_bf16 v[40:43], v[188:191], v[164:167], v[40:43]
	v_mfma_f32_16x16x32_bf16 v[36:39], v[210:213], v[164:167], v[36:39]
	v_mfma_f32_16x16x32_bf16 v[24:27], v[188:191], v[172:175], v[24:27]
	v_mfma_f32_16x16x32_bf16 v[20:23], v[210:213], v[172:175], v[20:23]
	v_mfma_f32_16x16x32_bf16 v[8:11], v[188:191], v[180:183], v[8:11]
	v_mfma_f32_16x16x32_bf16 v[4:7], v[210:213], v[180:183], v[4:7]
	s_setprio 0
	s_barrier
	ds_read_b128 v[132:135], v216 offset:32768
	ds_read_b128 v[136:139], v216 offset:33792
	ds_read_b128 v[140:143], v216 offset:34816
	ds_read_b128 v[144:147], v216 offset:35840
	ds_read_b128 v[152:155], v3 offset:32768
	ds_read_b128 v[156:159], v3 offset:33792
	ds_read_b128 v[160:163], v3 offset:34816
	ds_read_b128 v[164:167], v3 offset:35840
	ds_read_b128 v[168:171], v3 offset:36864
	ds_read_b128 v[172:175], v3 offset:37888
	ds_read_b128 v[176:179], v3 offset:38912
	ds_read_b128 v[180:183], v3 offset:39936
	ds_read_b128 v[184:187], v216 offset:49152
	ds_read_b128 v[188:191], v216 offset:50176
	ds_read_b128 v[192:195], v216 offset:51200
	ds_read_b128 v[210:213], v216 offset:52224
	s_add_u32 s8, s22, 0x18000
	s_addc_u32 s9, s23, 0
	s_mov_b32 m0, s72
	s_nop 0
	global_load_lds_dwordx4 v148, s[8:9]
	s_mov_b32 m0, s73
	s_nop 0
	global_load_lds_dwordx4 v150, s[8:9]
	s_waitcnt vmcnt(8)
	s_waitcnt lgkmcnt(0)
	s_barrier
	s_setprio 1
	v_mfma_f32_16x16x32_bf16 v[128:131], v[132:135], v[152:155], v[128:131]
	v_mfma_f32_16x16x32_bf16 v[124:127], v[140:143], v[152:155], v[124:127]
	v_mfma_f32_16x16x32_bf16 v[112:115], v[132:135], v[160:163], v[112:115]
	v_mfma_f32_16x16x32_bf16 v[108:111], v[140:143], v[160:163], v[108:111]
	v_mfma_f32_16x16x32_bf16 v[96:99], v[132:135], v[168:171], v[96:99]
	v_mfma_f32_16x16x32_bf16 v[92:95], v[140:143], v[168:171], v[92:95]
	v_mfma_f32_16x16x32_bf16 v[80:83], v[132:135], v[176:179], v[80:83]
	v_mfma_f32_16x16x32_bf16 v[76:79], v[140:143], v[176:179], v[76:79]
	v_mfma_f32_16x16x32_bf16 v[128:131], v[136:139], v[156:159], v[128:131]
	v_mfma_f32_16x16x32_bf16 v[124:127], v[144:147], v[156:159], v[124:127]
	v_mfma_f32_16x16x32_bf16 v[112:115], v[136:139], v[164:167], v[112:115]
	v_mfma_f32_16x16x32_bf16 v[108:111], v[144:147], v[164:167], v[108:111]
	v_mfma_f32_16x16x32_bf16 v[96:99], v[136:139], v[172:175], v[96:99]
	v_mfma_f32_16x16x32_bf16 v[92:95], v[144:147], v[172:175], v[92:95]
	v_mfma_f32_16x16x32_bf16 v[80:83], v[136:139], v[180:183], v[80:83]
	v_mfma_f32_16x16x32_bf16 v[76:79], v[144:147], v[180:183], v[76:79]
	s_setprio 0
	s_setprio 1
	v_mfma_f32_16x16x32_bf16 v[120:123], v[184:187], v[152:155], v[120:123]
	v_mfma_f32_16x16x32_bf16 v[116:119], v[192:195], v[152:155], v[116:119]
	v_mfma_f32_16x16x32_bf16 v[104:107], v[184:187], v[160:163], v[104:107]
	v_mfma_f32_16x16x32_bf16 v[100:103], v[192:195], v[160:163], v[100:103]
	v_mfma_f32_16x16x32_bf16 v[88:91], v[184:187], v[168:171], v[88:91]
	v_mfma_f32_16x16x32_bf16 v[84:87], v[192:195], v[168:171], v[84:87]
	v_mfma_f32_16x16x32_bf16 v[72:75], v[184:187], v[176:179], v[72:75]
	v_mfma_f32_16x16x32_bf16 v[68:71], v[192:195], v[176:179], v[68:71]
	v_mfma_f32_16x16x32_bf16 v[120:123], v[188:191], v[156:159], v[120:123]
	v_mfma_f32_16x16x32_bf16 v[116:119], v[210:213], v[156:159], v[116:119]
	v_mfma_f32_16x16x32_bf16 v[104:107], v[188:191], v[164:167], v[104:107]
	v_mfma_f32_16x16x32_bf16 v[100:103], v[210:213], v[164:167], v[100:103]
	v_mfma_f32_16x16x32_bf16 v[88:91], v[188:191], v[172:175], v[88:91]
	v_mfma_f32_16x16x32_bf16 v[84:87], v[210:213], v[172:175], v[84:87]
	v_mfma_f32_16x16x32_bf16 v[72:75], v[188:191], v[180:183], v[72:75]
	v_mfma_f32_16x16x32_bf16 v[68:71], v[210:213], v[180:183], v[68:71]
	s_setprio 0
	s_barrier
	ds_read_b128 v[152:155], v3 offset:49152
	ds_read_b128 v[156:159], v3 offset:50176
	ds_read_b128 v[160:163], v3 offset:51200
	ds_read_b128 v[164:167], v3 offset:52224
	ds_read_b128 v[168:171], v3 offset:53248
	ds_read_b128 v[172:175], v3 offset:54272
	ds_read_b128 v[176:179], v3 offset:55296
	ds_read_b128 v[180:183], v3 offset:56320
	s_add_i32 s22, 0, 0x1c000
	s_add_u32 s8, s18, 0x80
	s_addc_u32 s9, s19, 0
	s_add_i32 s23, s64, s56
	s_mov_b32 m0, s23
	s_nop 0
	global_load_lds_dwordx4 v148, s[8:9]
	s_add_i32 m0, s23, 0x2000
	s_nop 0
	global_load_lds_dwordx4 v150, s[8:9]
	s_mov_b32 m0, s68
	s_nop 0
	global_load_lds_dwordx4 v148, s[20:21]
	s_mov_b32 m0, s74
	s_nop 0
	global_load_lds_dwordx4 v150, s[20:21]
	s_add_u32 s8, s18, 0x18080
	s_addc_u32 s9, s19, 0
	s_add_i32 s18, s22, s56
	s_mov_b32 m0, s18
	s_nop 0
	global_load_lds_dwordx4 v148, s[8:9]
	s_add_i32 m0, s18, 0x2000
	s_nop 0
	global_load_lds_dwordx4 v150, s[8:9]
	s_add_i32 s62, s62, 2
	s_add_u32 s47, s47, 0x100
	s_addc_u32 s49, s49, 0
	s_cmp_gt_u32 s62, 3
	s_mov_b64 s[8:9], s[0:1]
	s_waitcnt vmcnt(8)
	s_waitcnt lgkmcnt(0)
	s_barrier
	s_setprio 1
	v_mfma_f32_16x16x32_bf16 v[64:67], v[132:135], v[152:155], v[64:67]
	v_mfma_f32_16x16x32_bf16 v[60:63], v[140:143], v[152:155], v[60:63]
	v_mfma_f32_16x16x32_bf16 v[48:51], v[132:135], v[160:163], v[48:51]
	v_mfma_f32_16x16x32_bf16 v[44:47], v[140:143], v[160:163], v[44:47]
	v_mfma_f32_16x16x32_bf16 v[32:35], v[132:135], v[168:171], v[32:35]
	v_mfma_f32_16x16x32_bf16 v[28:31], v[140:143], v[168:171], v[28:31]
	v_mfma_f32_16x16x32_bf16 v[16:19], v[132:135], v[176:179], v[16:19]
	v_mfma_f32_16x16x32_bf16 v[12:15], v[140:143], v[176:179], v[12:15]
	v_mfma_f32_16x16x32_bf16 v[64:67], v[136:139], v[156:159], v[64:67]
	v_mfma_f32_16x16x32_bf16 v[60:63], v[144:147], v[156:159], v[60:63]
	v_mfma_f32_16x16x32_bf16 v[48:51], v[136:139], v[164:167], v[48:51]
	v_mfma_f32_16x16x32_bf16 v[44:47], v[144:147], v[164:167], v[44:47]
	v_mfma_f32_16x16x32_bf16 v[32:35], v[136:139], v[172:175], v[32:35]
	v_mfma_f32_16x16x32_bf16 v[28:31], v[144:147], v[172:175], v[28:31]
	v_mfma_f32_16x16x32_bf16 v[16:19], v[136:139], v[180:183], v[16:19]
	v_mfma_f32_16x16x32_bf16 v[12:15], v[144:147], v[180:183], v[12:15]
	s_setprio 0
	s_setprio 1
	v_mfma_f32_16x16x32_bf16 v[56:59], v[184:187], v[152:155], v[56:59]
	v_mfma_f32_16x16x32_bf16 v[52:55], v[192:195], v[152:155], v[52:55]
	v_mfma_f32_16x16x32_bf16 v[40:43], v[184:187], v[160:163], v[40:43]
	v_mfma_f32_16x16x32_bf16 v[36:39], v[192:195], v[160:163], v[36:39]
	v_mfma_f32_16x16x32_bf16 v[24:27], v[184:187], v[168:171], v[24:27]
	v_mfma_f32_16x16x32_bf16 v[20:23], v[192:195], v[168:171], v[20:23]
	v_mfma_f32_16x16x32_bf16 v[8:11], v[184:187], v[176:179], v[8:11]
	v_mfma_f32_16x16x32_bf16 v[4:7], v[192:195], v[176:179], v[4:7]
	v_mfma_f32_16x16x32_bf16 v[56:59], v[188:191], v[156:159], v[56:59]
	v_mfma_f32_16x16x32_bf16 v[52:55], v[210:213], v[156:159], v[52:55]
	v_mfma_f32_16x16x32_bf16 v[40:43], v[188:191], v[164:167], v[40:43]
	v_mfma_f32_16x16x32_bf16 v[36:39], v[210:213], v[164:167], v[36:39]
	v_mfma_f32_16x16x32_bf16 v[24:27], v[188:191], v[172:175], v[24:27]
	v_mfma_f32_16x16x32_bf16 v[20:23], v[210:213], v[172:175], v[20:23]
	v_mfma_f32_16x16x32_bf16 v[8:11], v[188:191], v[180:183], v[8:11]
	v_mfma_f32_16x16x32_bf16 v[4:7], v[210:213], v[180:183], v[4:7]
	s_setprio 0
	s_barrier
	s_cbranch_scc0 .LBB0_769
	v_mov_b32_e32 v132, v0
	s_nop 0
	v_readfirstlane_b32 s0, v132
	s_lshr_b32 s1, s0, 6
	s_and_b32 s49, s1, 3
	s_cmp_eq_u32 s48, 4
	s_cselect_b64 s[8:9], -1, 0
	s_cmp_gt_u32 s49, 1
	s_cselect_b64 s[18:19], -1, 0
	s_and_b64 s[8:9], s[8:9], s[18:19]
	s_and_b64 vcc, exec, s[8:9]
	s_cbranch_vccnz .LBB0_757
	s_ashr_i32 s0, s0, 2
	s_lshl_b32 s1, s46, 8
	s_andn2_b32 s0, s0, 63
	s_add_i32 s0, s0, s1
	v_and_or_b32 v152, v132, 15, s0
	v_ashrrev_i32_e32 v153, 31, v152
	v_bfe_u32 v134, v132, 4, 2
	v_lshl_add_u64 v[132:133], v[152:153], 2, s[6:7]
	global_load_dword v135, v[132:133], off
	global_load_dword v178, v[132:133], off offset:64
	global_load_dword v177, v[132:133], off offset:128
	global_load_dword v176, v[132:133], off offset:192
	global_load_dword v175, v[132:133], off offset:512
	global_load_dword v174, v[132:133], off offset:576
	global_load_dword v173, v[132:133], off offset:640
	global_load_dword v172, v[132:133], off offset:704
	s_cmp_gt_i32 s48, 2
	s_cselect_b64 s[0:1], -1, 0
	v_lshlrev_b32_e32 v179, 3, v134
	s_lshl_b32 s8, s48, 3
	s_lshl_b32 s9, s49, 1
	s_or_b32 s8, s8, s9
	s_sub_i32 s46, s8, 24
	v_cmp_eq_u32_e64 s[18:19], 0, v134
	v_cmp_ne_u32_e64 s[20:21], 0, v134
	s_mov_b64 s[8:9], -1
	v_lshlrev_b32_e32 v154, 2, v179
	s_waitcnt vmcnt(0)
	v_fmamk_f32 v132, v135, 0x3b2aaaab, v231
	v_cmp_gt_f32_e32 vcc, s11, v132
	v_mul_f32_e32 v133, 0x4b800000, v132
	s_nop 0
	v_cndmask_b32_e32 v132, v132, v133, vcc
	v_rsq_f32_e32 v132, v132
	s_nop 0
	v_mul_f32_e32 v133, 0x45800000, v132
	v_cndmask_b32_e32 v158, v132, v133, vcc
	v_and_b32_e32 v132, 8, v179
	v_mov_b32_e32 v159, v158
	s_and_b64 vcc, exec, s[0:1]
	v_lshlrev_b32_e32 v156, 2, v132
	v_pk_mul_f32 v[128:129], v[128:129], v[158:159]
	v_pk_mul_f32 v[124:125], v[124:125], v[158:159]
	s_cbranch_vccz .LBB0_781
	v_and_b32_e32 v133, 64, v236
	v_xor_b32_e32 v132, 32, v236
	v_add_u32_e32 v133, 64, v133
	v_cmp_lt_i32_e32 vcc, v132, v133
	v_mov_b32_e32 v162, v158
	v_mov_b32_e32 v163, v158
	v_cndmask_b32_e32 v132, v236, v132, vcc
	v_pk_mul_f32 v[160:161], v[130:131], v[162:163]
	v_lshlrev_b32_e32 v170, 2, v132
	v_mul_f32_e32 v132, v129, v129
	v_mul_f32_e32 v133, v161, v161
	v_fmac_f32_e32 v132, v128, v128
	v_fmac_f32_e32 v133, v160, v160
	v_add_f32_e32 v155, v132, v133
	global_load_dwordx4 v[136:139], v154, s[40:41] offset:272
	global_load_dwordx4 v[144:147], v154, s[40:41] offset:256
	global_load_dwordx4 v[132:135], v156, s[26:27] offset:16
	global_load_dwordx4 v[140:143], v156, s[26:27]
	v_pk_mul_f32 v[162:163], v[126:127], v[162:163]
	v_mul_f32_e32 v157, v125, v125
	v_mul_f32_e32 v164, v163, v163
	v_fmac_f32_e32 v157, v124, v124
	v_fmac_f32_e32 v164, v162, v162
	v_add_f32_e32 v157, v157, v164
	v_add_f32_e32 v155, v155, v157
	ds_swizzle_b32 v157, v155 offset:swizzle(SWAP,16)
	s_waitcnt lgkmcnt(0)
	v_add_f32_e32 v155, v155, v157
	ds_bpermute_b32 v157, v170, v155
	s_and_saveexec_b64 s[8:9], s[20:21]
	s_xor_b64 s[8:9], exec, s[8:9]
	s_ashr_i32 s47, s46, 31
	s_or_saveexec_b64 s[8:9], s[8:9]
	v_mov_b64_e32 v[164:165], s[46:47]
	s_xor_b64 exec, exec, s[8:9]
	s_cbranch_execz .LBB0_776
	s_ashr_i32 s47, s46, 31
	s_mul_i32 s22, s46, 0x10400
	s_mul_hi_i32 s23, s46, 0x10400
	s_add_u32 s22, s35, s22
	s_addc_u32 s23, s54, s23
	s_waitcnt lgkmcnt(0)
	v_add_f32_e32 v155, v155, v157
	v_lshl_add_u64 v[164:165], v[152:153], 2, s[22:23]
	global_atomic_add_f32 v[164:165], v155, off
	v_mov_b64_e32 v[164:165], s[46:47]

.LBB0_1000:
	s_add_u32 s22, s14, 0x16923c00
	s_addc_u32 s23, s15, 0
	s_add_u32 s24, s14, 0x18d23c00
	s_addc_u32 s25, s15, 0
	v_and_b32_e32 v3, 15, v1
	s_add_u32 s26, s14, 0x303ccc00
	v_and_b32_e32 v4, 48, v1
	v_lshlrev_b32_e32 v3, 6, v3
	v_lshlrev_b32_e32 v1, 2, v1
	s_addc_u32 s27, s15, 0
	v_or_b32_e32 v5, v3, v4
	s_lshl_b32 s9, s16, 13
	v_and_b32_e32 v1, 32, v1
	v_bitop3_b32 v6, v5, s9, v1 bitop3:0xde
	s_lshl_b32 s9, s17, 12
	s_and_b32 s9, s9, 0x3000
	s_add_u32 s14, s0, 0x80
	v_mov_b32_e32 v167, v2
	s_addc_u32 s15, s1, 0
	v_bitop3_b32 v3, v3, v1, v4 bitop3:0x36
	s_waitcnt vmcnt(2)
	s_barrier
	s_add_i32 m0, s56, 0x18000
	v_lshl_add_u64 v[4:5], s[14:15], 0, v[166:167]
	v_mov_b32_e32 v171, v2
	global_load_lds_dwordx4 v[4:5], off
	s_add_i32 m0, s56, 0x1a000
	v_lshl_add_u64 v[4:5], s[14:15], 0, v[170:171]
	s_add_u32 s14, s20, 0x80
	v_mov_b32_e32 v165, v2
	s_addc_u32 s15, s21, 0
	s_add_i32 s64, s56, 0x8000
	v_mov_b32_e32 v169, v2
	global_load_lds_dwordx4 v[4:5], off
	s_mov_b32 m0, s64
	v_lshl_add_u64 v[4:5], s[14:15], 0, v[164:165]
	s_add_i32 s65, s56, 0xa000
	global_load_lds_dwordx4 v[4:5], off
	v_lshl_add_u64 v[4:5], s[14:15], 0, v[168:169]
	s_add_u32 s14, s0, 0x10080
	s_mov_b32 m0, s65
	s_addc_u32 s15, s1, 0
	global_load_lds_dwordx4 v[4:5], off
	s_add_i32 m0, s56, 0x1c000
	v_lshl_add_u64 v[4:5], s[14:15], 0, v[166:167]
	global_load_lds_dwordx4 v[4:5], off
	v_lshl_add_u64 v[4:5], s[14:15], 0, v[170:171]
	s_add_i32 m0, s56, 0x1e000
	v_or_b32_e32 v1, s9, v3
	global_load_lds_dwordx4 v[4:5], off
	s_waitcnt vmcnt(6)
	s_mov_b32 s72, 0
	v_add_u32_e32 v3, 0, v6
	s_barrier
	s_branch .LBB0_1003

.LBB0_1012:
	ds_read_b128 v[68:71], v218
	ds_read_b128 v[88:91], v218 offset:1024
	ds_read_b128 v[108:111], v218 offset:2048
	ds_read_b128 v[128:131], v218 offset:3072
	ds_read_b128 v[148:151], v3
	ds_read_b128 v[152:155], v3 offset:1024
	ds_read_b128 v[156:159], v3 offset:2048
	ds_read_b128 v[160:163], v3 offset:3072
	ds_read_b128 v[172:175], v3 offset:4096
	ds_read_b128 v[176:179], v3 offset:5120
	ds_read_b128 v[180:183], v3 offset:6144
	ds_read_b128 v[184:187], v3 offset:7168
	ds_read_b128 v[188:191], v218 offset:16384
	ds_read_b128 v[192:195], v218 offset:17408
	ds_read_b128 v[210:213], v218 offset:18432
	ds_read_b128 v[214:217], v218 offset:19456
	s_add_u32 s29, s20, s36
	s_addc_u32 s42, s21, s37
	s_add_u32 s43, s29, 0x100
	s_addc_u32 s44, s42, 0
	s_and_b64 s[40:41], s[38:39], exec
	s_cselect_b32 s47, s31, s44
	s_cselect_b32 s46, s30, s43
	s_add_u32 s36, s0, s36
	s_addc_u32 s37, s1, s37
	s_add_u32 s40, s36, 0x100
	s_addc_u32 s41, s37, 0
	s_add_u32 s36, s46, 0x80
	s_addc_u32 s37, s47, 0
	s_add_i32 s78, 0, 0x10000
	s_and_b64 s[38:39], s[38:39], exec
	s_cselect_b32 s49, s9, s41
	s_cselect_b32 s48, s19, s40
	s_add_u32 s50, s29, 0x12080
	s_addc_u32 s51, s42, 0
	s_add_i32 s83, s78, s55
	s_add_i32 m0, s56, 0xc000
	s_add_i32 s84, s56, 0xe000
	s_add_i32 s82, 0, 0x14000
	s_add_i32 s81, s83, 0x2000
	s_add_u32 s44, s48, 0x10000
	s_addc_u32 s45, s49, 0
	s_add_i32 s79, s82, s55
	s_add_i32 s75, s79, 0x2000
	s_add_i32 s74, 0, 0x18000
	s_add_u32 s42, s46, 0x12000
	s_addc_u32 s43, s47, 0
	s_add_i32 s67, 0, 0x1c000
	s_add_u32 s40, s48, 0x80
	s_addc_u32 s41, s49, 0
	s_add_i32 s68, s74, s55
	s_add_i32 s29, s68, 0x2000
	s_add_u32 s38, s48, 0x10080
	s_addc_u32 s39, s49, 0
	s_add_i32 s80, s67, s55
	s_add_i32 s78, s80, 0x2000
	s_nop 0
	global_load_lds_dwordx4 v164, s[50:51]
	s_mov_b32 m0, s84
	s_nop 0
	global_load_lds_dwordx4 v168, s[50:51]
	s_waitcnt vmcnt(8)
	s_waitcnt lgkmcnt(0)
	s_barrier
	s_setprio 1
	v_mfma_f32_16x16x32_bf16 v[144:147], v[68:71], v[148:151], v[144:147]
	v_mfma_f32_16x16x32_bf16 v[140:143], v[108:111], v[148:151], v[140:143]
	v_mfma_f32_16x16x32_bf16 v[124:127], v[68:71], v[156:159], v[124:127]
	v_mfma_f32_16x16x32_bf16 v[120:123], v[108:111], v[156:159], v[120:123]
	v_mfma_f32_16x16x32_bf16 v[104:107], v[68:71], v[172:175], v[104:107]
	v_mfma_f32_16x16x32_bf16 v[100:103], v[108:111], v[172:175], v[100:103]
	v_mfma_f32_16x16x32_bf16 v[84:87], v[68:71], v[180:183], v[84:87]
	v_mfma_f32_16x16x32_bf16 v[80:83], v[108:111], v[180:183], v[80:83]
	v_mfma_f32_16x16x32_bf16 v[144:147], v[88:91], v[152:155], v[144:147]
	v_mfma_f32_16x16x32_bf16 v[140:143], v[128:131], v[152:155], v[140:143]
	v_mfma_f32_16x16x32_bf16 v[124:127], v[88:91], v[160:163], v[124:127]
	v_mfma_f32_16x16x32_bf16 v[120:123], v[128:131], v[160:163], v[120:123]
	v_mfma_f32_16x16x32_bf16 v[104:107], v[88:91], v[176:179], v[104:107]
	v_mfma_f32_16x16x32_bf16 v[100:103], v[128:131], v[176:179], v[100:103]
	v_mfma_f32_16x16x32_bf16 v[84:87], v[88:91], v[184:187], v[84:87]
	v_mfma_f32_16x16x32_bf16 v[80:83], v[128:131], v[184:187], v[80:83]
	s_setprio 0
	s_setprio 1
	v_mfma_f32_16x16x32_bf16 v[136:139], v[188:191], v[148:151], v[136:139]
	v_mfma_f32_16x16x32_bf16 v[132:135], v[210:213], v[148:151], v[132:135]
	v_mfma_f32_16x16x32_bf16 v[116:119], v[188:191], v[156:159], v[116:119]
	v_mfma_f32_16x16x32_bf16 v[112:115], v[210:213], v[156:159], v[112:115]
	v_mfma_f32_16x16x32_bf16 v[96:99], v[188:191], v[172:175], v[96:99]
	v_mfma_f32_16x16x32_bf16 v[92:95], v[210:213], v[172:175], v[92:95]
	v_mfma_f32_16x16x32_bf16 v[76:79], v[188:191], v[180:183], v[76:79]
	v_mfma_f32_16x16x32_bf16 v[72:75], v[210:213], v[180:183], v[72:75]
	v_mfma_f32_16x16x32_bf16 v[136:139], v[192:195], v[152:155], v[136:139]
	v_mfma_f32_16x16x32_bf16 v[132:135], v[214:217], v[152:155], v[132:135]
	v_mfma_f32_16x16x32_bf16 v[116:119], v[192:195], v[160:163], v[116:119]
	v_mfma_f32_16x16x32_bf16 v[112:115], v[214:217], v[160:163], v[112:115]
	v_mfma_f32_16x16x32_bf16 v[96:99], v[192:195], v[176:179], v[96:99]
	v_mfma_f32_16x16x32_bf16 v[92:95], v[214:217], v[176:179], v[92:95]
	v_mfma_f32_16x16x32_bf16 v[76:79], v[192:195], v[184:187], v[76:79]
	v_mfma_f32_16x16x32_bf16 v[72:75], v[214:217], v[184:187], v[72:75]
	s_setprio 0
	s_barrier
	ds_read_b128 v[148:151], v3 offset:16384
	ds_read_b128 v[152:155], v3 offset:17408
	ds_read_b128 v[156:159], v3 offset:18432
	ds_read_b128 v[160:163], v3 offset:19456
	ds_read_b128 v[172:175], v3 offset:20480
	ds_read_b128 v[176:179], v3 offset:21504
	ds_read_b128 v[180:183], v3 offset:22528
	ds_read_b128 v[184:187], v3 offset:23552
	s_mov_b32 m0, s83
	s_nop 0
	global_load_lds_dwordx4 v166, s[48:49]
	s_mov_b32 m0, s81
	s_nop 0
	global_load_lds_dwordx4 v170, s[48:49]
	s_mov_b32 m0, s56
	s_nop 0
	global_load_lds_dwordx4 v164, s[46:47]
	s_mov_b32 m0, s57
	s_nop 0
	global_load_lds_dwordx4 v168, s[46:47]
	s_mov_b32 m0, s79
	s_nop 0
	global_load_lds_dwordx4 v166, s[44:45]
	s_mov_b32 m0, s75
	s_nop 0
	global_load_lds_dwordx4 v170, s[44:45]
	s_waitcnt vmcnt(8)
	s_waitcnt lgkmcnt(0)
	s_barrier
	s_setprio 1
	v_mfma_f32_16x16x32_bf16 v[64:67], v[68:71], v[148:151], v[64:67]
	v_mfma_f32_16x16x32_bf16 v[60:63], v[108:111], v[148:151], v[60:63]
	v_mfma_f32_16x16x32_bf16 v[48:51], v[68:71], v[156:159], v[48:51]
	v_mfma_f32_16x16x32_bf16 v[44:47], v[108:111], v[156:159], v[44:47]
	v_mfma_f32_16x16x32_bf16 v[32:35], v[68:71], v[172:175], v[32:35]
	v_mfma_f32_16x16x32_bf16 v[28:31], v[108:111], v[172:175], v[28:31]
	v_mfma_f32_16x16x32_bf16 v[16:19], v[68:71], v[180:183], v[16:19]
	v_mfma_f32_16x16x32_bf16 v[12:15], v[108:111], v[180:183], v[12:15]
	v_mfma_f32_16x16x32_bf16 v[64:67], v[88:91], v[152:155], v[64:67]
	v_mfma_f32_16x16x32_bf16 v[60:63], v[128:131], v[152:155], v[60:63]
	v_mfma_f32_16x16x32_bf16 v[48:51], v[88:91], v[160:163], v[48:51]
	v_mfma_f32_16x16x32_bf16 v[44:47], v[128:131], v[160:163], v[44:47]
	v_mfma_f32_16x16x32_bf16 v[32:35], v[88:91], v[176:179], v[32:35]
	v_mfma_f32_16x16x32_bf16 v[28:31], v[128:131], v[176:179], v[28:31]
	v_mfma_f32_16x16x32_bf16 v[16:19], v[88:91], v[184:187], v[16:19]
	v_mfma_f32_16x16x32_bf16 v[12:15], v[128:131], v[184:187], v[12:15]
	s_setprio 0
	s_setprio 1
	v_mfma_f32_16x16x32_bf16 v[56:59], v[188:191], v[148:151], v[56:59]
	v_mfma_f32_16x16x32_bf16 v[52:55], v[210:213], v[148:151], v[52:55]
	v_mfma_f32_16x16x32_bf16 v[40:43], v[188:191], v[156:159], v[40:43]
	v_mfma_f32_16x16x32_bf16 v[36:39], v[210:213], v[156:159], v[36:39]
	v_mfma_f32_16x16x32_bf16 v[24:27], v[188:191], v[172:175], v[24:27]
	v_mfma_f32_16x16x32_bf16 v[20:23], v[210:213], v[172:175], v[20:23]
	v_mfma_f32_16x16x32_bf16 v[8:11], v[188:191], v[180:183], v[8:11]
	v_mfma_f32_16x16x32_bf16 v[4:7], v[210:213], v[180:183], v[4:7]
	v_mfma_f32_16x16x32_bf16 v[56:59], v[192:195], v[152:155], v[56:59]
	v_mfma_f32_16x16x32_bf16 v[52:55], v[214:217], v[152:155], v[52:55]
	v_mfma_f32_16x16x32_bf16 v[40:43], v[192:195], v[160:163], v[40:43]
	v_mfma_f32_16x16x32_bf16 v[36:39], v[214:217], v[160:163], v[36:39]
	v_mfma_f32_16x16x32_bf16 v[24:27], v[192:195], v[176:179], v[24:27]
	v_mfma_f32_16x16x32_bf16 v[20:23], v[214:217], v[176:179], v[20:23]
	v_mfma_f32_16x16x32_bf16 v[8:11], v[192:195], v[184:187], v[8:11]
	v_mfma_f32_16x16x32_bf16 v[4:7], v[214:217], v[184:187], v[4:7]
	s_setprio 0
	s_barrier
	ds_read_b128 v[68:71], v218 offset:32768
	ds_read_b128 v[88:91], v218 offset:33792
	ds_read_b128 v[108:111], v218 offset:34816
	ds_read_b128 v[128:131], v218 offset:35840
	ds_read_b128 v[148:151], v3 offset:32768
	ds_read_b128 v[152:155], v3 offset:33792
	ds_read_b128 v[156:159], v3 offset:34816
	ds_read_b128 v[160:163], v3 offset:35840
	ds_read_b128 v[172:175], v3 offset:36864
	ds_read_b128 v[176:179], v3 offset:37888
	ds_read_b128 v[180:183], v3 offset:38912
	ds_read_b128 v[184:187], v3 offset:39936
	ds_read_b128 v[188:191], v218 offset:49152
	ds_read_b128 v[192:195], v218 offset:50176
	ds_read_b128 v[210:213], v218 offset:51200
	ds_read_b128 v[214:217], v218 offset:52224
	s_mov_b32 m0, s62
	s_nop 0
	global_load_lds_dwordx4 v164, s[42:43]
	s_mov_b32 m0, s63
	s_nop 0
	global_load_lds_dwordx4 v168, s[42:43]
	s_waitcnt vmcnt(8)
	s_waitcnt lgkmcnt(0)
	s_barrier
	s_setprio 1
	v_mfma_f32_16x16x32_bf16 v[144:147], v[68:71], v[148:151], v[144:147]
	v_mfma_f32_16x16x32_bf16 v[140:143], v[108:111], v[148:151], v[140:143]
	v_mfma_f32_16x16x32_bf16 v[124:127], v[68:71], v[156:159], v[124:127]
	v_mfma_f32_16x16x32_bf16 v[120:123], v[108:111], v[156:159], v[120:123]
	v_mfma_f32_16x16x32_bf16 v[104:107], v[68:71], v[172:175], v[104:107]
	v_mfma_f32_16x16x32_bf16 v[100:103], v[108:111], v[172:175], v[100:103]
	v_mfma_f32_16x16x32_bf16 v[84:87], v[68:71], v[180:183], v[84:87]
	v_mfma_f32_16x16x32_bf16 v[80:83], v[108:111], v[180:183], v[80:83]
	v_mfma_f32_16x16x32_bf16 v[144:147], v[88:91], v[152:155], v[144:147]
	v_mfma_f32_16x16x32_bf16 v[140:143], v[128:131], v[152:155], v[140:143]
	v_mfma_f32_16x16x32_bf16 v[124:127], v[88:91], v[160:163], v[124:127]
	v_mfma_f32_16x16x32_bf16 v[120:123], v[128:131], v[160:163], v[120:123]
	v_mfma_f32_16x16x32_bf16 v[104:107], v[88:91], v[176:179], v[104:107]
	v_mfma_f32_16x16x32_bf16 v[100:103], v[128:131], v[176:179], v[100:103]
	v_mfma_f32_16x16x32_bf16 v[84:87], v[88:91], v[184:187], v[84:87]
	v_mfma_f32_16x16x32_bf16 v[80:83], v[128:131], v[184:187], v[80:83]
	s_setprio 0
	s_setprio 1
	v_mfma_f32_16x16x32_bf16 v[136:139], v[188:191], v[148:151], v[136:139]
	v_mfma_f32_16x16x32_bf16 v[132:135], v[210:213], v[148:151], v[132:135]
	v_mfma_f32_16x16x32_bf16 v[116:119], v[188:191], v[156:159], v[116:119]
	v_mfma_f32_16x16x32_bf16 v[112:115], v[210:213], v[156:159], v[112:115]
	v_mfma_f32_16x16x32_bf16 v[96:99], v[188:191], v[172:175], v[96:99]
	v_mfma_f32_16x16x32_bf16 v[92:95], v[210:213], v[172:175], v[92:95]
	v_mfma_f32_16x16x32_bf16 v[76:79], v[188:191], v[180:183], v[76:79]
	v_mfma_f32_16x16x32_bf16 v[72:75], v[210:213], v[180:183], v[72:75]
	v_mfma_f32_16x16x32_bf16 v[136:139], v[192:195], v[152:155], v[136:139]
	v_mfma_f32_16x16x32_bf16 v[132:135], v[214:217], v[152:155], v[132:135]
	v_mfma_f32_16x16x32_bf16 v[116:119], v[192:195], v[160:163], v[116:119]
	v_mfma_f32_16x16x32_bf16 v[112:115], v[214:217], v[160:163], v[112:115]
	v_mfma_f32_16x16x32_bf16 v[96:99], v[192:195], v[176:179], v[96:99]
	v_mfma_f32_16x16x32_bf16 v[92:95], v[214:217], v[176:179], v[92:95]
	v_mfma_f32_16x16x32_bf16 v[76:79], v[192:195], v[184:187], v[76:79]
	v_mfma_f32_16x16x32_bf16 v[72:75], v[214:217], v[184:187], v[72:75]
	s_setprio 0
	s_barrier
	ds_read_b128 v[148:151], v3 offset:49152
	ds_read_b128 v[152:155], v3 offset:50176
	ds_read_b128 v[156:159], v3 offset:51200
	ds_read_b128 v[160:163], v3 offset:52224
	ds_read_b128 v[172:175], v3 offset:53248
	ds_read_b128 v[176:179], v3 offset:54272
	ds_read_b128 v[180:183], v3 offset:55296
	ds_read_b128 v[184:187], v3 offset:56320
	s_mov_b32 m0, s68
	s_nop 0
	global_load_lds_dwordx4 v166, s[40:41]
	s_mov_b32 m0, s29
	s_nop 0
	global_load_lds_dwordx4 v170, s[40:41]
	s_mov_b32 m0, s64
	s_nop 0
	global_load_lds_dwordx4 v164, s[36:37]
	s_mov_b32 m0, s65
	s_nop 0
	global_load_lds_dwordx4 v168, s[36:37]
	s_mov_b32 m0, s80
	s_nop 0
	global_load_lds_dwordx4 v166, s[38:39]
	s_mov_b32 m0, s78
	s_nop 0
	global_load_lds_dwordx4 v170, s[38:39]
	s_andn2_b64 vcc, exec, s[16:17]
	s_mov_b64 s[38:39], -1
	s_mov_b64 s[16:17], 0
	s_mov_b64 s[36:37], 0x100
	s_waitcnt vmcnt(8)
	s_waitcnt lgkmcnt(0)
	s_barrier
	s_setprio 1
	v_mfma_f32_16x16x32_bf16 v[64:67], v[68:71], v[148:151], v[64:67]
	v_mfma_f32_16x16x32_bf16 v[60:63], v[108:111], v[148:151], v[60:63]
	v_mfma_f32_16x16x32_bf16 v[48:51], v[68:71], v[156:159], v[48:51]
	v_mfma_f32_16x16x32_bf16 v[44:47], v[108:111], v[156:159], v[44:47]
	v_mfma_f32_16x16x32_bf16 v[32:35], v[68:71], v[172:175], v[32:35]
	v_mfma_f32_16x16x32_bf16 v[28:31], v[108:111], v[172:175], v[28:31]
	v_mfma_f32_16x16x32_bf16 v[16:19], v[68:71], v[180:183], v[16:19]
	v_mfma_f32_16x16x32_bf16 v[12:15], v[108:111], v[180:183], v[12:15]
	v_mfma_f32_16x16x32_bf16 v[64:67], v[88:91], v[152:155], v[64:67]
	v_mfma_f32_16x16x32_bf16 v[60:63], v[128:131], v[152:155], v[60:63]
	v_mfma_f32_16x16x32_bf16 v[48:51], v[88:91], v[160:163], v[48:51]
	v_mfma_f32_16x16x32_bf16 v[44:47], v[128:131], v[160:163], v[44:47]
	v_mfma_f32_16x16x32_bf16 v[32:35], v[88:91], v[176:179], v[32:35]
	v_mfma_f32_16x16x32_bf16 v[28:31], v[128:131], v[176:179], v[28:31]
	v_mfma_f32_16x16x32_bf16 v[16:19], v[88:91], v[184:187], v[16:19]
	v_mfma_f32_16x16x32_bf16 v[12:15], v[128:131], v[184:187], v[12:15]
	s_setprio 0
	s_setprio 1
	v_mfma_f32_16x16x32_bf16 v[56:59], v[188:191], v[148:151], v[56:59]
	v_mfma_f32_16x16x32_bf16 v[52:55], v[210:213], v[148:151], v[52:55]
	v_mfma_f32_16x16x32_bf16 v[40:43], v[188:191], v[156:159], v[40:43]
	v_mfma_f32_16x16x32_bf16 v[36:39], v[210:213], v[156:159], v[36:39]
	v_mfma_f32_16x16x32_bf16 v[24:27], v[188:191], v[172:175], v[24:27]
	v_mfma_f32_16x16x32_bf16 v[20:23], v[210:213], v[172:175], v[20:23]
	v_mfma_f32_16x16x32_bf16 v[8:11], v[188:191], v[180:183], v[8:11]
	v_mfma_f32_16x16x32_bf16 v[4:7], v[210:213], v[180:183], v[4:7]
	v_mfma_f32_16x16x32_bf16 v[56:59], v[192:195], v[152:155], v[56:59]
	v_mfma_f32_16x16x32_bf16 v[52:55], v[214:217], v[152:155], v[52:55]
	v_mfma_f32_16x16x32_bf16 v[40:43], v[192:195], v[160:163], v[40:43]
	v_mfma_f32_16x16x32_bf16 v[36:39], v[214:217], v[160:163], v[36:39]
	v_mfma_f32_16x16x32_bf16 v[24:27], v[192:195], v[176:179], v[24:27]
	v_mfma_f32_16x16x32_bf16 v[20:23], v[214:217], v[176:179], v[20:23]
	v_mfma_f32_16x16x32_bf16 v[8:11], v[192:195], v[184:187], v[8:11]
	v_mfma_f32_16x16x32_bf16 v[4:7], v[214:217], v[184:187], v[4:7]
	s_setprio 0
	s_barrier
	s_cbranch_vccz .LBB0_1012
	v_mov_b32_e32 v68, v0
	s_cmp_gt_i32 s8, 2
	s_cselect_b64 s[0:1], -1, 0
	v_readfirstlane_b32 s9, v68
	s_ashr_i32 s19, s18, 31
	s_lshl_b64 s[16:17], s[18:19], 8
	s_ashr_i32 s18, s9, 2
	s_andn2_b32 s18, s18, 63
	s_ashr_i32 s19, s18, 31
	s_add_u32 s18, s16, s18
	v_bfe_u32 v174, v68, 4, 2
	s_addc_u32 s19, s17, s19
	v_and_or_b32 v172, v68, 15, s18
	v_mov_b32_e32 v173, s19
	v_lshlrev_b32_e32 v179, 3, v174
	s_and_b64 vcc, exec, s[0:1]
	s_cbranch_vccnz .LBB0_1015
	v_mov_b64_e32 v[68:69], s[6:7]
	s_movk_i32 s20, 0x240
	v_mad_u64_u32 v[68:69], s[16:17], v172, s20, v[68:69]
	v_mov_b32_e32 v70, v69
	v_mad_u64_u32 v[70:71], s[16:17], v173, s20, v[70:71]
	v_mov_b32_e32 v69, v70
	v_lshlrev_b32_e32 v70, 1, v179
	v_mov_b32_e32 v71, v2
	v_lshl_add_u64 v[68:69], v[68:69], 0, v[70:71]
	v_add_co_u32_e32 v70, vcc, 0x2000, v68
	s_movk_i32 s16, 0x4000
	s_nop 0
	v_addc_co_u32_e32 v71, vcc, 0, v69, vcc
	global_load_dwordx4 v[160:163], v[68:69], off offset:512
	global_load_dwordx4 v[156:159], v[70:71], off offset:1536
	v_add_co_u32_e32 v70, vcc, s16, v68
	s_nop 1
	v_addc_co_u32_e32 v71, vcc, 0, v69, vcc
	v_add_co_u32_e32 v88, vcc, 0x6000, v68
	s_nop 1
	v_addc_co_u32_e32 v89, vcc, 0, v69, vcc
	global_load_dwordx4 v[152:155], v[70:71], off offset:2560
	global_load_dwordx4 v[148:151], v[88:89], off offset:3584
	v_add_co_u32_e32 v70, vcc, 0x12000, v68
	s_nop 1
	v_addc_co_u32_e32 v71, vcc, 0, v69, vcc
	v_add_co_u32_e32 v88, vcc, 0x14000, v68
	s_nop 1
	v_addc_co_u32_e32 v89, vcc, 0, v69, vcc
	global_load_dwordx4 v[128:131], v[70:71], off offset:512
	global_load_dwordx4 v[108:111], v[88:89], off offset:1536
	v_add_co_u32_e32 v70, vcc, 0x16000, v68
	s_nop 1
	v_addc_co_u32_e32 v71, vcc, 0, v69, vcc
	v_add_co_u32_e32 v68, vcc, 0x18000, v68
	s_nop 1
	v_addc_co_u32_e32 v69, vcc, 0, v69, vcc
	global_load_dwordx4 v[88:91], v[70:71], off offset:2560
	s_nop 0
	global_load_dwordx4 v[68:71], v[68:69], off offset:3584

.LBB0_1755:
	s_add_u32 s20, s18, s50
	s_addc_u32 s21, s19, 0
	s_add_u32 s20, s20, 0x5000
	s_addc_u32 s21, s21, 0
	s_add_u32 s22, s18, 0x7c7dc00
	s_addc_u32 s23, s19, 0
	s_add_u32 s24, s18, 0x94ddc00
	s_addc_u32 s25, s19, 0
	s_lshl_b64 s[18:19], s[6:7], 2
	s_add_u32 s26, s14, s18
	s_addc_u32 s27, s15, s19
	s_add_u32 s14, s16, s36
	s_addc_u32 s15, s17, s37
	s_add_u32 s28, s14, 0x5348000
	s_addc_u32 s29, s15, 0
	s_add_u32 s14, s16, s49
	s_addc_u32 s15, s17, s48
	s_add_u32 s30, s14, 0x53fc000
	s_addc_u32 s31, s15, 0
	s_lshl_b32 s14, s38, 12
	s_lshl_b32 s16, s39, 13
	s_and_b32 s17, s14, 0x3000
	s_add_u32 s14, s8, 0x80
	v_mov_b32_e32 v139, v2
	s_addc_u32 s15, s9, 0
	s_waitcnt vmcnt(2)
	s_barrier
	s_add_i32 m0, s57, 0x18000
	v_lshl_add_u64 v[4:5], s[14:15], 0, v[138:139]
	v_mov_b32_e32 v137, v2
	global_load_lds_dwordx4 v[4:5], off
	s_add_i32 m0, s57, 0x1a000
	v_lshl_add_u64 v[4:5], s[14:15], 0, v[136:137]
	s_add_u32 s14, s0, 0x80
	s_addc_u32 s15, s1, 0
	s_add_i32 s73, s57, 0x8000
	global_load_lds_dwordx4 v[4:5], off
	s_mov_b32 m0, s73
	v_lshl_add_u64 v[4:5], s[14:15], 0, v[138:139]
	s_add_i32 s74, s57, 0xa000
	global_load_lds_dwordx4 v[4:5], off
	v_lshl_add_u64 v[4:5], s[14:15], 0, v[136:137]
	s_add_u32 s14, s8, 0x40080
	s_mov_b32 m0, s74
	s_addc_u32 s15, s9, 0
	global_load_lds_dwordx4 v[4:5], off
	s_add_i32 m0, s57, 0x1c000
	v_lshl_add_u64 v[4:5], s[14:15], 0, v[138:139]
	global_load_lds_dwordx4 v[4:5], off
	v_lshl_add_u64 v[4:5], s[14:15], 0, v[136:137]
	s_add_i32 m0, s57, 0x1e000
	v_and_b32_e32 v3, 15, v1
	global_load_lds_dwordx4 v[4:5], off
	v_and_b32_e32 v4, 48, v1
	v_lshlrev_b32_e32 v3, 6, v3
	v_lshlrev_b32_e32 v1, 2, v1
	v_or_b32_e32 v5, v3, v4
	v_and_b32_e32 v1, 32, v1
	s_waitcnt vmcnt(6)
	v_bitop3_b32 v3, v3, v1, v4 bitop3:0x36
	v_bitop3_b32 v4, v5, s16, v1 bitop3:0xde
	v_readlane_b32 s14, v254, 34
	v_or_b32_e32 v1, s17, v3
	s_mov_b32 s75, 0
	v_add_u32_e32 v3, 0, v4
	v_readlane_b32 s78, v254, 33
	s_mov_b32 s64, s14
	s_barrier
	v_readlane_b32 s15, v254, 35
	s_branch .LBB0_1758

.LBB0_1765:
	ds_read_b128 v[132:135], v216
	ds_read_b128 v[140:143], v216 offset:1024
	ds_read_b128 v[144:147], v216 offset:2048
	ds_read_b128 v[148:151], v216 offset:3072
	ds_read_b128 v[152:155], v3
	ds_read_b128 v[156:159], v3 offset:1024
	ds_read_b128 v[160:163], v3 offset:2048
	ds_read_b128 v[164:167], v3 offset:3072
	ds_read_b128 v[168:171], v3 offset:4096
	ds_read_b128 v[172:175], v3 offset:5120
	ds_read_b128 v[176:179], v3 offset:6144
	ds_read_b128 v[180:183], v3 offset:7168
	ds_read_b128 v[184:187], v216 offset:16384
	ds_read_b128 v[188:191], v216 offset:17408
	ds_read_b128 v[192:195], v216 offset:18432
	ds_read_b128 v[210:213], v216 offset:19456
	s_add_u32 s8, s0, 0x100
	s_addc_u32 s9, s1, 0
	s_cmp_eq_u32 s80, 12
	s_cselect_b32 s46, s65, s8
	s_cselect_b32 s47, s41, s9
	s_cselect_b32 s14, s67, s68
	s_cselect_b32 s15, s39, s79
	s_add_u32 s18, s46, 0x80
	s_addc_u32 s19, s47, 0
	s_add_i32 s81, 0, 0x10000
	s_add_u32 s0, s0, 0x40080
	s_addc_u32 s1, s1, 0
	s_add_i32 m0, s57, 0xc000
	s_nop 0
	global_load_lds_dwordx4 v138, s[0:1]
	s_add_i32 m0, s57, 0xe000
	s_nop 0
	global_load_lds_dwordx4 v136, s[0:1]
	s_waitcnt vmcnt(8)
	s_waitcnt lgkmcnt(0)
	s_barrier
	s_setprio 1
	v_mfma_f32_16x16x32_bf16 v[128:131], v[132:135], v[152:155], v[128:131]
	v_mfma_f32_16x16x32_bf16 v[124:127], v[144:147], v[152:155], v[124:127]
	v_mfma_f32_16x16x32_bf16 v[112:115], v[132:135], v[160:163], v[112:115]
	v_mfma_f32_16x16x32_bf16 v[108:111], v[144:147], v[160:163], v[108:111]
	v_mfma_f32_16x16x32_bf16 v[96:99], v[132:135], v[168:171], v[96:99]
	v_mfma_f32_16x16x32_bf16 v[92:95], v[144:147], v[168:171], v[92:95]
	v_mfma_f32_16x16x32_bf16 v[80:83], v[132:135], v[176:179], v[80:83]
	v_mfma_f32_16x16x32_bf16 v[76:79], v[144:147], v[176:179], v[76:79]
	v_mfma_f32_16x16x32_bf16 v[128:131], v[140:143], v[156:159], v[128:131]
	v_mfma_f32_16x16x32_bf16 v[124:127], v[148:151], v[156:159], v[124:127]
	v_mfma_f32_16x16x32_bf16 v[112:115], v[140:143], v[164:167], v[112:115]
	v_mfma_f32_16x16x32_bf16 v[108:111], v[148:151], v[164:167], v[108:111]
	v_mfma_f32_16x16x32_bf16 v[96:99], v[140:143], v[172:175], v[96:99]
	v_mfma_f32_16x16x32_bf16 v[92:95], v[148:151], v[172:175], v[92:95]
	v_mfma_f32_16x16x32_bf16 v[80:83], v[140:143], v[180:183], v[80:83]
	v_mfma_f32_16x16x32_bf16 v[76:79], v[148:151], v[180:183], v[76:79]
	s_setprio 0
	s_setprio 1
	v_mfma_f32_16x16x32_bf16 v[120:123], v[184:187], v[152:155], v[120:123]
	v_mfma_f32_16x16x32_bf16 v[116:119], v[192:195], v[152:155], v[116:119]
	v_mfma_f32_16x16x32_bf16 v[104:107], v[184:187], v[160:163], v[104:107]
	v_mfma_f32_16x16x32_bf16 v[100:103], v[192:195], v[160:163], v[100:103]
	v_mfma_f32_16x16x32_bf16 v[88:91], v[184:187], v[168:171], v[88:91]
	v_mfma_f32_16x16x32_bf16 v[84:87], v[192:195], v[168:171], v[84:87]
	v_mfma_f32_16x16x32_bf16 v[72:75], v[184:187], v[176:179], v[72:75]
	v_mfma_f32_16x16x32_bf16 v[68:71], v[192:195], v[176:179], v[68:71]
	v_mfma_f32_16x16x32_bf16 v[120:123], v[188:191], v[156:159], v[120:123]
	v_mfma_f32_16x16x32_bf16 v[116:119], v[210:213], v[156:159], v[116:119]
	v_mfma_f32_16x16x32_bf16 v[104:107], v[188:191], v[164:167], v[104:107]
	v_mfma_f32_16x16x32_bf16 v[100:103], v[210:213], v[164:167], v[100:103]
	v_mfma_f32_16x16x32_bf16 v[88:91], v[188:191], v[172:175], v[88:91]
	v_mfma_f32_16x16x32_bf16 v[84:87], v[210:213], v[172:175], v[84:87]
	v_mfma_f32_16x16x32_bf16 v[72:75], v[188:191], v[180:183], v[72:75]
	v_mfma_f32_16x16x32_bf16 v[68:71], v[210:213], v[180:183], v[68:71]
	s_setprio 0
	s_barrier
	ds_read_b128 v[152:155], v3 offset:16384
	ds_read_b128 v[156:159], v3 offset:17408
	ds_read_b128 v[160:163], v3 offset:18432
	ds_read_b128 v[164:167], v3 offset:19456
	ds_read_b128 v[168:171], v3 offset:20480
	ds_read_b128 v[172:175], v3 offset:21504
	ds_read_b128 v[176:179], v3 offset:22528
	ds_read_b128 v[180:183], v3 offset:23552
	s_add_i32 s82, 0, 0x14000
	s_mov_b64 s[0:1], s[14:15]
	s_add_i32 s81, s81, s56
	s_mov_b32 m0, s81
	s_nop 0
	global_load_lds_dwordx4 v138, s[0:1]
	s_add_i32 m0, s81, 0x2000
	s_nop 0
	global_load_lds_dwordx4 v136, s[0:1]
	s_mov_b64 s[0:1], s[46:47]
	s_mov_b32 m0, s57
	s_nop 0
	global_load_lds_dwordx4 v138, s[0:1]
	s_mov_b32 m0, s62
	s_nop 0
	global_load_lds_dwordx4 v136, s[0:1]
	s_add_u32 s0, s14, 0x40000
	s_addc_u32 s1, s15, 0
	s_add_i32 s81, s82, s56
	s_mov_b32 m0, s81
	s_nop 0
	global_load_lds_dwordx4 v138, s[0:1]
	s_add_i32 m0, s81, 0x2000
	s_nop 0
	global_load_lds_dwordx4 v136, s[0:1]
	s_add_i32 s81, 0, 0x18000
	s_waitcnt vmcnt(8)
	s_waitcnt lgkmcnt(0)
	s_barrier
	s_setprio 1
	v_mfma_f32_16x16x32_bf16 v[64:67], v[132:135], v[152:155], v[64:67]
	v_mfma_f32_16x16x32_bf16 v[60:63], v[144:147], v[152:155], v[60:63]
	v_mfma_f32_16x16x32_bf16 v[48:51], v[132:135], v[160:163], v[48:51]
	v_mfma_f32_16x16x32_bf16 v[44:47], v[144:147], v[160:163], v[44:47]
	v_mfma_f32_16x16x32_bf16 v[32:35], v[132:135], v[168:171], v[32:35]
	v_mfma_f32_16x16x32_bf16 v[28:31], v[144:147], v[168:171], v[28:31]
	v_mfma_f32_16x16x32_bf16 v[16:19], v[132:135], v[176:179], v[16:19]
	v_mfma_f32_16x16x32_bf16 v[12:15], v[144:147], v[176:179], v[12:15]
	v_mfma_f32_16x16x32_bf16 v[64:67], v[140:143], v[156:159], v[64:67]
	v_mfma_f32_16x16x32_bf16 v[60:63], v[148:151], v[156:159], v[60:63]
	v_mfma_f32_16x16x32_bf16 v[48:51], v[140:143], v[164:167], v[48:51]
	v_mfma_f32_16x16x32_bf16 v[44:47], v[148:151], v[164:167], v[44:47]
	v_mfma_f32_16x16x32_bf16 v[32:35], v[140:143], v[172:175], v[32:35]
	v_mfma_f32_16x16x32_bf16 v[28:31], v[148:151], v[172:175], v[28:31]
	v_mfma_f32_16x16x32_bf16 v[16:19], v[140:143], v[180:183], v[16:19]
	v_mfma_f32_16x16x32_bf16 v[12:15], v[148:151], v[180:183], v[12:15]
	s_setprio 0
	s_setprio 1
	v_mfma_f32_16x16x32_bf16 v[56:59], v[184:187], v[152:155], v[56:59]
	v_mfma_f32_16x16x32_bf16 v[52:55], v[192:195], v[152:155], v[52:55]
	v_mfma_f32_16x16x32_bf16 v[40:43], v[184:187], v[160:163], v[40:43]
	v_mfma_f32_16x16x32_bf16 v[36:39], v[192:195], v[160:163], v[36:39]
	v_mfma_f32_16x16x32_bf16 v[24:27], v[184:187], v[168:171], v[24:27]
	v_mfma_f32_16x16x32_bf16 v[20:23], v[192:195], v[168:171], v[20:23]
	v_mfma_f32_16x16x32_bf16 v[8:11], v[184:187], v[176:179], v[8:11]
	v_mfma_f32_16x16x32_bf16 v[4:7], v[192:195], v[176:179], v[4:7]
	v_mfma_f32_16x16x32_bf16 v[56:59], v[188:191], v[156:159], v[56:59]
	v_mfma_f32_16x16x32_bf16 v[52:55], v[210:213], v[156:159], v[52:55]
	v_mfma_f32_16x16x32_bf16 v[40:43], v[188:191], v[164:167], v[40:43]
	v_mfma_f32_16x16x32_bf16 v[36:39], v[210:213], v[164:167], v[36:39]
	v_mfma_f32_16x16x32_bf16 v[24:27], v[188:191], v[172:175], v[24:27]
	v_mfma_f32_16x16x32_bf16 v[20:23], v[210:213], v[172:175], v[20:23]
	v_mfma_f32_16x16x32_bf16 v[8:11], v[188:191], v[180:183], v[8:11]
	v_mfma_f32_16x16x32_bf16 v[4:7], v[210:213], v[180:183], v[4:7]
	s_setprio 0
	s_barrier
	ds_read_b128 v[132:135], v216 offset:32768
	ds_read_b128 v[140:143], v216 offset:33792
	ds_read_b128 v[144:147], v216 offset:34816
	ds_read_b128 v[148:151], v216 offset:35840
	ds_read_b128 v[152:155], v3 offset:32768
	ds_read_b128 v[156:159], v3 offset:33792
	ds_read_b128 v[160:163], v3 offset:34816
	ds_read_b128 v[164:167], v3 offset:35840
	ds_read_b128 v[168:171], v3 offset:36864
	ds_read_b128 v[172:175], v3 offset:37888
	ds_read_b128 v[176:179], v3 offset:38912
	ds_read_b128 v[180:183], v3 offset:39936
	ds_read_b128 v[184:187], v216 offset:49152
	ds_read_b128 v[188:191], v216 offset:50176
	ds_read_b128 v[192:195], v216 offset:51200
	ds_read_b128 v[210:213], v216 offset:52224
	s_add_u32 s0, s46, 0x40000
	s_addc_u32 s1, s47, 0
	s_mov_b32 m0, s63
	s_nop 0
	global_load_lds_dwordx4 v138, s[0:1]
	s_mov_b32 m0, s72
	s_nop 0
	global_load_lds_dwordx4 v136, s[0:1]
	s_waitcnt vmcnt(8)
	s_waitcnt lgkmcnt(0)
	s_barrier
	s_setprio 1
	v_mfma_f32_16x16x32_bf16 v[128:131], v[132:135], v[152:155], v[128:131]
	v_mfma_f32_16x16x32_bf16 v[124:127], v[144:147], v[152:155], v[124:127]
	v_mfma_f32_16x16x32_bf16 v[112:115], v[132:135], v[160:163], v[112:115]
	v_mfma_f32_16x16x32_bf16 v[108:111], v[144:147], v[160:163], v[108:111]
	v_mfma_f32_16x16x32_bf16 v[96:99], v[132:135], v[168:171], v[96:99]
	v_mfma_f32_16x16x32_bf16 v[92:95], v[144:147], v[168:171], v[92:95]
	v_mfma_f32_16x16x32_bf16 v[80:83], v[132:135], v[176:179], v[80:83]
	v_mfma_f32_16x16x32_bf16 v[76:79], v[144:147], v[176:179], v[76:79]
	v_mfma_f32_16x16x32_bf16 v[128:131], v[140:143], v[156:159], v[128:131]
	v_mfma_f32_16x16x32_bf16 v[124:127], v[148:151], v[156:159], v[124:127]
	v_mfma_f32_16x16x32_bf16 v[112:115], v[140:143], v[164:167], v[112:115]
	v_mfma_f32_16x16x32_bf16 v[108:111], v[148:151], v[164:167], v[108:111]
	v_mfma_f32_16x16x32_bf16 v[96:99], v[140:143], v[172:175], v[96:99]
	v_mfma_f32_16x16x32_bf16 v[92:95], v[148:151], v[172:175], v[92:95]
	v_mfma_f32_16x16x32_bf16 v[80:83], v[140:143], v[180:183], v[80:83]
	v_mfma_f32_16x16x32_bf16 v[76:79], v[148:151], v[180:183], v[76:79]
	s_setprio 0
	s_setprio 1
	v_mfma_f32_16x16x32_bf16 v[120:123], v[184:187], v[152:155], v[120:123]
	v_mfma_f32_16x16x32_bf16 v[116:119], v[192:195], v[152:155], v[116:119]
	v_mfma_f32_16x16x32_bf16 v[104:107], v[184:187], v[160:163], v[104:107]
	v_mfma_f32_16x16x32_bf16 v[100:103], v[192:195], v[160:163], v[100:103]
	v_mfma_f32_16x16x32_bf16 v[88:91], v[184:187], v[168:171], v[88:91]
	v_mfma_f32_16x16x32_bf16 v[84:87], v[192:195], v[168:171], v[84:87]
	v_mfma_f32_16x16x32_bf16 v[72:75], v[184:187], v[176:179], v[72:75]
	v_mfma_f32_16x16x32_bf16 v[68:71], v[192:195], v[176:179], v[68:71]
	v_mfma_f32_16x16x32_bf16 v[120:123], v[188:191], v[156:159], v[120:123]
	v_mfma_f32_16x16x32_bf16 v[116:119], v[210:213], v[156:159], v[116:119]
	v_mfma_f32_16x16x32_bf16 v[104:107], v[188:191], v[164:167], v[104:107]
	v_mfma_f32_16x16x32_bf16 v[100:103], v[210:213], v[164:167], v[100:103]
	v_mfma_f32_16x16x32_bf16 v[88:91], v[188:191], v[172:175], v[88:91]
	v_mfma_f32_16x16x32_bf16 v[84:87], v[210:213], v[172:175], v[84:87]
	v_mfma_f32_16x16x32_bf16 v[72:75], v[188:191], v[180:183], v[72:75]
	v_mfma_f32_16x16x32_bf16 v[68:71], v[210:213], v[180:183], v[68:71]
	s_setprio 0
	s_barrier
	ds_read_b128 v[152:155], v3 offset:49152
	ds_read_b128 v[156:159], v3 offset:50176
	ds_read_b128 v[160:163], v3 offset:51200
	ds_read_b128 v[164:167], v3 offset:52224
	ds_read_b128 v[168:171], v3 offset:53248
	ds_read_b128 v[172:175], v3 offset:54272
	ds_read_b128 v[176:179], v3 offset:55296
	ds_read_b128 v[180:183], v3 offset:56320
	s_add_i32 s46, 0, 0x1c000
	s_add_u32 s0, s14, 0x80
	s_addc_u32 s1, s15, 0
	s_add_i32 s47, s81, s56
	s_mov_b32 m0, s47
	s_nop 0
	global_load_lds_dwordx4 v138, s[0:1]
	s_add_i32 m0, s47, 0x2000
	s_nop 0
	global_load_lds_dwordx4 v136, s[0:1]
	s_mov_b32 m0, s73
	s_nop 0
	global_load_lds_dwordx4 v138, s[18:19]
	s_mov_b32 m0, s74
	s_nop 0
	global_load_lds_dwordx4 v136, s[18:19]
	s_add_u32 s0, s14, 0x40080
	s_addc_u32 s1, s15, 0
	s_add_i32 s14, s46, s56
	s_mov_b32 m0, s14
	s_nop 0
	global_load_lds_dwordx4 v138, s[0:1]
	s_add_i32 m0, s14, 0x2000
	s_nop 0
	global_load_lds_dwordx4 v136, s[0:1]
	s_add_i32 s80, s80, 2
	s_add_u32 s68, s68, 0x100
	s_addc_u32 s79, s79, 0
	s_cmp_gt_u32 s80, 13
	s_mov_b64 s[0:1], s[8:9]
	s_waitcnt vmcnt(8)
	s_waitcnt lgkmcnt(0)
	s_barrier
	s_setprio 1
	v_mfma_f32_16x16x32_bf16 v[64:67], v[132:135], v[152:155], v[64:67]
	v_mfma_f32_16x16x32_bf16 v[60:63], v[144:147], v[152:155], v[60:63]
	v_mfma_f32_16x16x32_bf16 v[48:51], v[132:135], v[160:163], v[48:51]
	v_mfma_f32_16x16x32_bf16 v[44:47], v[144:147], v[160:163], v[44:47]
	v_mfma_f32_16x16x32_bf16 v[32:35], v[132:135], v[168:171], v[32:35]
	v_mfma_f32_16x16x32_bf16 v[28:31], v[144:147], v[168:171], v[28:31]
	v_mfma_f32_16x16x32_bf16 v[16:19], v[132:135], v[176:179], v[16:19]
	v_mfma_f32_16x16x32_bf16 v[12:15], v[144:147], v[176:179], v[12:15]
	v_mfma_f32_16x16x32_bf16 v[64:67], v[140:143], v[156:159], v[64:67]
	v_mfma_f32_16x16x32_bf16 v[60:63], v[148:151], v[156:159], v[60:63]
	v_mfma_f32_16x16x32_bf16 v[48:51], v[140:143], v[164:167], v[48:51]
	v_mfma_f32_16x16x32_bf16 v[44:47], v[148:151], v[164:167], v[44:47]
	v_mfma_f32_16x16x32_bf16 v[32:35], v[140:143], v[172:175], v[32:35]
	v_mfma_f32_16x16x32_bf16 v[28:31], v[148:151], v[172:175], v[28:31]
	v_mfma_f32_16x16x32_bf16 v[16:19], v[140:143], v[180:183], v[16:19]
	v_mfma_f32_16x16x32_bf16 v[12:15], v[148:151], v[180:183], v[12:15]
	s_setprio 0
	s_setprio 1
	v_mfma_f32_16x16x32_bf16 v[56:59], v[184:187], v[152:155], v[56:59]
	v_mfma_f32_16x16x32_bf16 v[52:55], v[192:195], v[152:155], v[52:55]
	v_mfma_f32_16x16x32_bf16 v[40:43], v[184:187], v[160:163], v[40:43]
	v_mfma_f32_16x16x32_bf16 v[36:39], v[192:195], v[160:163], v[36:39]
	v_mfma_f32_16x16x32_bf16 v[24:27], v[184:187], v[168:171], v[24:27]
	v_mfma_f32_16x16x32_bf16 v[20:23], v[192:195], v[168:171], v[20:23]
	v_mfma_f32_16x16x32_bf16 v[8:11], v[184:187], v[176:179], v[8:11]
	v_mfma_f32_16x16x32_bf16 v[4:7], v[192:195], v[176:179], v[4:7]
	v_mfma_f32_16x16x32_bf16 v[56:59], v[188:191], v[156:159], v[56:59]
	v_mfma_f32_16x16x32_bf16 v[52:55], v[210:213], v[156:159], v[52:55]
	v_mfma_f32_16x16x32_bf16 v[40:43], v[188:191], v[164:167], v[40:43]
	v_mfma_f32_16x16x32_bf16 v[36:39], v[210:213], v[164:167], v[36:39]
	v_mfma_f32_16x16x32_bf16 v[24:27], v[188:191], v[172:175], v[24:27]
	v_mfma_f32_16x16x32_bf16 v[20:23], v[210:213], v[172:175], v[20:23]
	v_mfma_f32_16x16x32_bf16 v[8:11], v[188:191], v[180:183], v[8:11]
	v_mfma_f32_16x16x32_bf16 v[4:7], v[210:213], v[180:183], v[4:7]
	s_setprio 0
	s_barrier
	s_cbranch_scc0 .LBB0_1765
	v_mov_b32_e32 v145, v0
	s_lshl_b32 s1, s64, 8
	v_readfirstlane_b32 s0, v145
	s_and_b32 s14, s0, 0xc0
	s_ashr_i32 s0, s0, 2
	v_and_b32_e32 v170, 15, v145
	s_and_b32 s15, s0, 0xffffffc0
	v_or_b32_e32 v132, s15, v170
	v_add_u32_e32 v132, s1, v132
	v_ashrrev_i32_e32 v133, 31, v132
	v_lshl_add_u64 v[132:133], v[132:133], 2, s[20:21]
	global_load_dword v134, v[132:133], off
	global_load_dword v174, v[132:133], off offset:64
	global_load_dword v173, v[132:133], off offset:128
	global_load_dword v172, v[132:133], off offset:192
	global_load_dword v171, v[132:133], off offset:512
	global_load_dword v169, v[132:133], off offset:576
	global_load_dword v168, v[132:133], off offset:640
	global_load_dword v167, v[132:133], off offset:704
	s_add_i32 s15, s15, s1
	s_cmp_gt_i32 s78, 2
	s_cselect_b64 s[0:1], -1, 0
	v_or_b32_e32 v142, s15, v170
	s_mov_b64 s[8:9], -1
	s_waitcnt vmcnt(0)
	v_fmamk_f32 v132, v134, 0x3a800000, v231
	v_cmp_gt_f32_e32 vcc, s11, v132
	v_mul_f32_e32 v133, 0x4b800000, v132
	s_nop 0
	v_cndmask_b32_e32 v132, v132, v133, vcc
	v_rsq_f32_e32 v132, v132
	s_nop 0
	v_mul_f32_e32 v133, 0x45800000, v132
	v_cndmask_b32_e32 v144, v132, v133, vcc
	v_lshrrev_b32_e32 v132, 1, v145
	v_and_b32_e32 v155, 24, v132
	s_and_b64 vcc, exec, s[0:1]
	v_lshlrev_b32_e32 v166, 2, v155
	v_lshlrev_b32_e32 v140, 1, v155
	s_cbranch_vccz .LBB0_1768
	v_ashrrev_i32_e32 v143, 31, v142
	v_lshlrev_b64 v[132:133], 9, v[142:143]
	v_lshl_add_u64 v[132:133], s[24:25], 0, v[132:133]
	s_lshl_b32 s68, s14, 1
	v_pk_mul_f32 v[160:161], v[130:131], v[144:145] op_sel_hi:[1,0]
	v_pk_mul_f32 v[162:163], v[128:129], v[144:145] op_sel_hi:[1,0]
	v_lshl_add_u64 v[164:165], v[132:133], 0, s[68:69]
	v_pk_mul_f32 v[132:133], v[160:161], v[160:161]
	v_pk_mul_f32 v[134:135], v[162:163], v[162:163]
	v_pk_mul_f32 v[156:157], v[126:127], v[144:145] op_sel_hi:[1,0]
	v_pk_mov_b32 v[146:147], v[134:135], v[132:133] op_sel:[1,0]
	v_mov_b32_e32 v135, v133
	v_pk_add_f32 v[132:133], v[146:147], v[134:135]
	v_pk_mul_f32 v[158:159], v[124:125], v[144:145] op_sel_hi:[1,0]
	v_pk_add_f32 v[132:133], v[132:133], v[132:133] op_sel_hi:[0,1]
	v_pk_mul_f32 v[134:135], v[156:157], v[156:157]
	v_pk_mul_f32 v[146:147], v[158:159], v[158:159]
	v_pk_mul_f32 v[152:153], v[120:121], v[144:145] op_sel_hi:[1,0]
	v_pk_mov_b32 v[148:149], v[146:147], v[134:135] op_sel:[1,0]
	v_mov_b32_e32 v147, v135
	v_pk_mul_f32 v[150:151], v[122:123], v[144:145] op_sel_hi:[1,0]
	v_mul_f32_e32 v132, v152, v152
	v_pk_add_f32 v[134:135], v[148:149], v[146:147]
	v_pk_fma_f32 v[176:177], v[152:153], v[152:153], v[132:133] op_sel_hi:[1,1,0]
	v_mul_f32_e32 v132, v150, v150
	v_pk_add_f32 v[134:135], v[134:135], v[134:135] op_sel_hi:[0,1]
	v_pk_fma_f32 v[178:179], v[150:151], v[150:151], v[132:133] op_sel_hi:[1,1,0]
	v_pk_mul_f32 v[146:147], v[118:119], v[144:145] op_sel_hi:[1,0]
	v_pk_mul_f32 v[148:149], v[116:117], v[144:145] op_sel_hi:[1,0]
	v_mul_f32_e32 v132, v146, v146
	v_mul_f32_e32 v176, v148, v148
	v_mul_f32_e32 v178, v149, v149
	v_mul_f32_e32 v134, v147, v147
	v_pk_add_f32 v[176:177], v[176:177], v[178:179]
	v_pk_add_f32 v[132:133], v[132:133], v[134:135]
	v_and_b32_e32 v134, 64, v236
	v_pk_add_f32 v[132:133], v[176:177], v[132:133]
	v_add_u32_e32 v134, 64, v134
	v_add_f32_e32 v132, v132, v133
	ds_swizzle_b32 v133, v132 offset:swizzle(SWAP,16)
	v_mov_b32_e32 v141, v2
	v_lshl_add_u64 v[164:165], v[164:165], 0, v[140:141]
	s_mov_b64 s[8:9], 0
	s_waitcnt lgkmcnt(0)
	v_add_f32_e32 v132, v132, v133
	v_xor_b32_e32 v133, 32, v236
	v_cmp_lt_i32_e32 vcc, v133, v134
	s_nop 1
	v_cndmask_b32_e32 v133, v236, v133, vcc
	v_lshlrev_b32_e32 v133, 2, v133
	ds_bpermute_b32 v133, v133, v132
	s_waitcnt lgkmcnt(0)
	v_add_f32_e32 v132, v132, v133
	v_fmamk_f32 v132, v132, 0x3c800000, v231
	v_cmp_gt_f32_e32 vcc, s11, v132
	v_mul_f32_e32 v133, 0x4b800000, v132
	s_nop 0
	v_cndmask_b32_e32 v132, v132, v133, vcc
	v_rsq_f32_e32 v132, v132
	s_nop 0
	v_mul_f32_e32 v133, 0x45800000, v132
	v_cndmask_b32_e32 v132, v132, v133, vcc
	v_mul_f32_e32 v154, 0x3e38aa3b, v132
	global_load_dwordx4 v[132:135], v166, s[26:27] offset:16
	global_load_dwordx4 v[176:179], v166, s[26:27]
	v_pk_mul_f32 v[162:163], v[162:163], v[154:155] op_sel_hi:[1,0]
	v_pk_mul_f32 v[160:161], v[160:161], v[154:155] op_sel_hi:[1,0]
	v_pk_mul_f32 v[158:159], v[158:159], v[154:155] op_sel_hi:[1,0]
	v_pk_mul_f32 v[156:157], v[156:157], v[154:155] op_sel_hi:[1,0]
	v_pk_mul_f32 v[152:153], v[152:153], v[154:155] op_sel_hi:[1,0]
	v_pk_mul_f32 v[150:151], v[150:151], v[154:155] op_sel_hi:[1,0]
	v_pk_mul_f32 v[148:149], v[148:149], v[154:155] op_sel_hi:[1,0]
	v_pk_mul_f32 v[146:147], v[146:147], v[154:155] op_sel_hi:[1,0]
	s_waitcnt vmcnt(1)
	v_pk_mul_f32 v[156:157], v[134:135], v[156:157]
	s_waitcnt vmcnt(0)
	v_pk_mul_f32 v[160:161], v[178:179], v[160:161]
	v_pk_mul_f32 v[162:163], v[176:177], v[162:163]
	v_pk_mul_f32 v[134:135], v[132:133], v[158:159]
	v_cvt_pk_bf16_f32 v132, v162, v163
	v_cvt_pk_bf16_f32 v133, v160, v161
	v_cvt_pk_bf16_f32 v134, v134, v135
	v_cvt_pk_bf16_f32 v135, v156, v157
	global_store_dwordx4 v[164:165], v[132:135], off
	global_load_dwordx4 v[132:135], v166, s[26:27] offset:144
	s_nop 0
	global_load_dwordx4 v[156:159], v166, s[26:27] offset:128
	s_waitcnt vmcnt(1)
	v_pk_mul_f32 v[146:147], v[134:135], v[146:147]
	s_waitcnt vmcnt(0)
	v_pk_mul_f32 v[150:151], v[158:159], v[150:151]
	v_pk_mul_f32 v[152:153], v[156:157], v[152:153]
	v_pk_mul_f32 v[134:135], v[132:133], v[148:149]
	v_cvt_pk_bf16_f32 v132, v152, v153
	v_cvt_pk_bf16_f32 v133, v150, v151
	v_cvt_pk_bf16_f32 v134, v134, v135
	v_cvt_pk_bf16_f32 v135, v146, v147
	global_store_dwordx4 v[164:165], v[132:135], off offset:64
